# k22 plus the counted vmcnt(8) and lgkmcnt(0) waits at the load-segment tails merged into one s_waitcnt
# speedup vs baseline: 1.0037x; 1.0009x over previous
.LBB0_143:
	ds_read_b128 v[168:171], v163
	ds_read_b128 v[172:175], v163 offset:1024
	ds_read_b128 v[176:179], v163 offset:2048
	ds_read_b128 v[180:183], v163 offset:3072
	ds_read_b128 v[184:187], v164
	ds_read_b128 v[188:191], v164 offset:1024
	ds_read_b128 v[192:195], v164 offset:2048
	ds_read_b128 v[196:199], v164 offset:3072
	s_add_u32 s26, s24, 0xfff80080
	s_addc_u32 s27, s25, -1
	s_cmp_eq_u32 s62, 28
	s_cselect_b32 s31, s15, s27
	s_cselect_b32 s30, s23, s26
	s_cselect_b32 s27, s13, s61
	s_cselect_b32 s26, s59, s60
	v_lshl_add_u64 v[154:155], s[24:25], 0, v[144:145]
	s_add_i32 m0, s43, 0xc000
	ds_read_b128 v[200:203], v165
	ds_read_b128 v[204:207], v165 offset:1024
	ds_read_b128 v[208:211], v165 offset:2048
	ds_read_b128 v[212:215], v165 offset:3072
	ds_read_b128 v[216:219], v165 offset:4096
	ds_read_b128 v[220:223], v165 offset:5120
	ds_read_b128 v[224:227], v165 offset:6144
	ds_read_b128 v[228:231], v165 offset:7168
	global_load_lds_dwordx4 v[154:155], off
	v_lshl_add_u64 v[154:155], s[24:25], 0, v[142:143]
	s_add_i32 m0, s43, 0xe000
	s_nop 0
	global_load_lds_dwordx4 v[154:155], off
	s_waitcnt vmcnt(8) lgkmcnt(0)
	s_barrier
	s_setprio 1
	v_mfma_f32_16x16x32_bf16 v[126:129], v[168:171], v[200:203], v[126:129]
	v_mfma_f32_16x16x32_bf16 v[122:125], v[176:179], v[200:203], v[122:125]
	v_mfma_f32_16x16x32_bf16 v[114:117], v[168:171], v[208:211], v[114:117]
	v_mfma_f32_16x16x32_bf16 v[106:109], v[176:179], v[208:211], v[106:109]
	v_mfma_f32_16x16x32_bf16 v[98:101], v[168:171], v[216:219], v[98:101]
	v_mfma_f32_16x16x32_bf16 v[90:93], v[176:179], v[216:219], v[90:93]
	v_mfma_f32_16x16x32_bf16 v[82:85], v[168:171], v[224:227], v[82:85]
	v_mfma_f32_16x16x32_bf16 v[74:77], v[176:179], v[224:227], v[74:77]
	v_mfma_f32_16x16x32_bf16 v[126:129], v[172:175], v[204:207], v[126:129]
	v_mfma_f32_16x16x32_bf16 v[122:125], v[180:183], v[204:207], v[122:125]
	v_mfma_f32_16x16x32_bf16 v[114:117], v[172:175], v[212:215], v[114:117]
	v_mfma_f32_16x16x32_bf16 v[106:109], v[180:183], v[212:215], v[106:109]
	v_mfma_f32_16x16x32_bf16 v[98:101], v[172:175], v[220:223], v[98:101]
	v_mfma_f32_16x16x32_bf16 v[90:93], v[180:183], v[220:223], v[90:93]
	v_mfma_f32_16x16x32_bf16 v[82:85], v[172:175], v[228:231], v[82:85]
	v_mfma_f32_16x16x32_bf16 v[74:77], v[180:183], v[228:231], v[74:77]
	s_setprio 0
	s_setprio 1
	v_mfma_f32_16x16x32_bf16 v[118:121], v[184:187], v[200:203], v[118:121]
	v_mfma_f32_16x16x32_bf16 v[110:113], v[192:195], v[200:203], v[110:113]
	v_mfma_f32_16x16x32_bf16 v[102:105], v[184:187], v[208:211], v[102:105]
	v_mfma_f32_16x16x32_bf16 v[94:97], v[192:195], v[208:211], v[94:97]
	v_mfma_f32_16x16x32_bf16 v[86:89], v[184:187], v[216:219], v[86:89]
	v_mfma_f32_16x16x32_bf16 v[78:81], v[192:195], v[216:219], v[78:81]
	v_mfma_f32_16x16x32_bf16 v[70:73], v[184:187], v[224:227], v[70:73]
	v_mfma_f32_16x16x32_bf16 v[66:69], v[192:195], v[224:227], v[66:69]
	v_mfma_f32_16x16x32_bf16 v[118:121], v[188:191], v[204:207], v[118:121]
	v_mfma_f32_16x16x32_bf16 v[110:113], v[196:199], v[204:207], v[110:113]
	v_mfma_f32_16x16x32_bf16 v[102:105], v[188:191], v[212:215], v[102:105]
	v_mfma_f32_16x16x32_bf16 v[94:97], v[196:199], v[212:215], v[94:97]
	v_mfma_f32_16x16x32_bf16 v[86:89], v[188:191], v[220:223], v[86:89]
	v_mfma_f32_16x16x32_bf16 v[78:81], v[196:199], v[220:223], v[78:81]
	v_mfma_f32_16x16x32_bf16 v[70:73], v[188:191], v[228:231], v[70:73]
	v_mfma_f32_16x16x32_bf16 v[66:69], v[196:199], v[228:231], v[66:69]
	s_barrier
	s_setprio 0
	s_add_i32 s63, s55, s42
	v_lshl_add_u64 v[154:155], s[26:27], 0, v[132:133]
	s_mov_b32 m0, s63
	ds_read_b128 v[200:203], v165 offset:16384
	ds_read_b128 v[204:207], v165 offset:17408
	ds_read_b128 v[208:211], v165 offset:18432
	ds_read_b128 v[212:215], v165 offset:19456
	ds_read_b128 v[216:219], v165 offset:20480
	ds_read_b128 v[220:223], v165 offset:21504
	ds_read_b128 v[224:227], v165 offset:22528
	ds_read_b128 v[228:231], v165 offset:23552
	global_load_lds_dwordx4 v[154:155], off
	s_add_i32 m0, s63, 0x2000
	s_add_u32 s64, s26, 0x80000
	v_lshl_add_u64 v[232:233], s[26:27], 0, v[136:137]
	s_addc_u32 s65, s27, 0
	s_add_i32 s63, s56, s42
	global_load_lds_dwordx4 v[232:233], off
	v_lshl_add_u64 v[234:235], s[64:65], 0, v[132:133]
	s_mov_b32 m0, s63
	v_lshl_add_u64 v[236:237], s[30:31], 0, v[134:135]
	global_load_lds_dwordx4 v[234:235], off
	v_lshl_add_u64 v[234:235], s[64:65], 0, v[136:137]
	s_add_i32 m0, s63, 0x2000
	s_nop 0
	global_load_lds_dwordx4 v[234:235], off
	v_lshl_add_u64 v[234:235], s[30:31], 0, v[130:131]
	s_mov_b32 m0, s43
	s_nop 0
	global_load_lds_dwordx4 v[234:235], off
	s_mov_b32 m0, s44
	s_nop 0
	global_load_lds_dwordx4 v[236:237], off
	s_waitcnt vmcnt(8) lgkmcnt(0)
	s_barrier
	s_setprio 1
	v_mfma_f32_16x16x32_bf16 v[62:65], v[168:171], v[200:203], v[62:65]
	v_mfma_f32_16x16x32_bf16 v[58:61], v[176:179], v[200:203], v[58:61]
	v_mfma_f32_16x16x32_bf16 v[50:53], v[168:171], v[208:211], v[50:53]
	v_mfma_f32_16x16x32_bf16 v[42:45], v[176:179], v[208:211], v[42:45]
	v_mfma_f32_16x16x32_bf16 v[34:37], v[168:171], v[216:219], v[34:37]
	v_mfma_f32_16x16x32_bf16 v[26:29], v[176:179], v[216:219], v[26:29]
	v_mfma_f32_16x16x32_bf16 v[18:21], v[168:171], v[224:227], v[18:21]
	v_mfma_f32_16x16x32_bf16 v[10:13], v[176:179], v[224:227], v[10:13]
	v_mfma_f32_16x16x32_bf16 v[62:65], v[172:175], v[204:207], v[62:65]
	v_mfma_f32_16x16x32_bf16 v[58:61], v[180:183], v[204:207], v[58:61]
	v_mfma_f32_16x16x32_bf16 v[50:53], v[172:175], v[212:215], v[50:53]
	v_mfma_f32_16x16x32_bf16 v[42:45], v[180:183], v[212:215], v[42:45]
	v_mfma_f32_16x16x32_bf16 v[34:37], v[172:175], v[220:223], v[34:37]
	v_mfma_f32_16x16x32_bf16 v[26:29], v[180:183], v[220:223], v[26:29]
	v_mfma_f32_16x16x32_bf16 v[18:21], v[172:175], v[228:231], v[18:21]
	v_mfma_f32_16x16x32_bf16 v[10:13], v[180:183], v[228:231], v[10:13]
	s_setprio 0
	s_setprio 1
	v_mfma_f32_16x16x32_bf16 v[54:57], v[184:187], v[200:203], v[54:57]
	v_mfma_f32_16x16x32_bf16 v[46:49], v[192:195], v[200:203], v[46:49]
	v_mfma_f32_16x16x32_bf16 v[38:41], v[184:187], v[208:211], v[38:41]
	v_mfma_f32_16x16x32_bf16 v[30:33], v[192:195], v[208:211], v[30:33]
	v_mfma_f32_16x16x32_bf16 v[22:25], v[184:187], v[216:219], v[22:25]
	v_mfma_f32_16x16x32_bf16 v[14:17], v[192:195], v[216:219], v[14:17]
	v_mfma_f32_16x16x32_bf16 v[6:9], v[184:187], v[224:227], v[6:9]
	v_mfma_f32_16x16x32_bf16 v[2:5], v[192:195], v[224:227], v[2:5]
	v_mfma_f32_16x16x32_bf16 v[54:57], v[188:191], v[204:207], v[54:57]
	v_mfma_f32_16x16x32_bf16 v[46:49], v[196:199], v[204:207], v[46:49]
	v_mfma_f32_16x16x32_bf16 v[38:41], v[188:191], v[212:215], v[38:41]
	v_mfma_f32_16x16x32_bf16 v[30:33], v[196:199], v[212:215], v[30:33]
	v_mfma_f32_16x16x32_bf16 v[22:25], v[188:191], v[220:223], v[22:25]
	v_mfma_f32_16x16x32_bf16 v[14:17], v[196:199], v[220:223], v[14:17]
	v_mfma_f32_16x16x32_bf16 v[6:9], v[188:191], v[228:231], v[6:9]
	v_mfma_f32_16x16x32_bf16 v[2:5], v[196:199], v[228:231], v[2:5]
	s_barrier
	s_setprio 0
	s_add_i32 s63, 0, 0x18000
	v_add_u32_e32 v138, s63, v159
	s_add_i32 s64, 0, 0x1c000
	ds_read_b128 v[168:171], v138
	ds_read_b128 v[172:175], v138 offset:1024
	ds_read_b128 v[176:179], v138 offset:2048
	ds_read_b128 v[180:183], v138 offset:3072
	v_add_u32_e32 v138, s64, v159
	ds_read_b128 v[184:187], v138
	ds_read_b128 v[188:191], v138 offset:1024
	ds_read_b128 v[192:195], v138 offset:2048
	ds_read_b128 v[196:199], v138 offset:3072
	s_add_u32 s30, s30, 0x80000
	s_addc_u32 s31, s31, 0
	s_mov_b32 m0, s45
	v_lshl_add_u64 v[238:239], s[30:31], 0, v[130:131]
	ds_read_b128 v[200:203], v165 offset:32768
	ds_read_b128 v[204:207], v165 offset:33792
	ds_read_b128 v[208:211], v165 offset:34816
	ds_read_b128 v[212:215], v165 offset:35840
	ds_read_b128 v[216:219], v165 offset:36864
	ds_read_b128 v[220:223], v165 offset:37888
	ds_read_b128 v[224:227], v165 offset:38912
	ds_read_b128 v[228:231], v165 offset:39936
	global_load_lds_dwordx4 v[238:239], off
	v_lshl_add_u64 v[238:239], s[30:31], 0, v[134:135]
	s_mov_b32 m0, s46
	s_nop 0
	global_load_lds_dwordx4 v[238:239], off
	s_waitcnt vmcnt(8) lgkmcnt(0)
	s_barrier
	s_setprio 1
	v_mfma_f32_16x16x32_bf16 v[126:129], v[168:171], v[200:203], v[126:129]
	v_mfma_f32_16x16x32_bf16 v[122:125], v[176:179], v[200:203], v[122:125]
	v_mfma_f32_16x16x32_bf16 v[114:117], v[168:171], v[208:211], v[114:117]
	v_mfma_f32_16x16x32_bf16 v[106:109], v[176:179], v[208:211], v[106:109]
	v_mfma_f32_16x16x32_bf16 v[98:101], v[168:171], v[216:219], v[98:101]
	v_mfma_f32_16x16x32_bf16 v[90:93], v[176:179], v[216:219], v[90:93]
	v_mfma_f32_16x16x32_bf16 v[82:85], v[168:171], v[224:227], v[82:85]
	v_mfma_f32_16x16x32_bf16 v[74:77], v[176:179], v[224:227], v[74:77]
	v_mfma_f32_16x16x32_bf16 v[126:129], v[172:175], v[204:207], v[126:129]
	v_mfma_f32_16x16x32_bf16 v[122:125], v[180:183], v[204:207], v[122:125]
	v_mfma_f32_16x16x32_bf16 v[114:117], v[172:175], v[212:215], v[114:117]
	v_mfma_f32_16x16x32_bf16 v[106:109], v[180:183], v[212:215], v[106:109]
	v_mfma_f32_16x16x32_bf16 v[98:101], v[172:175], v[220:223], v[98:101]
	v_mfma_f32_16x16x32_bf16 v[90:93], v[180:183], v[220:223], v[90:93]
	v_mfma_f32_16x16x32_bf16 v[82:85], v[172:175], v[228:231], v[82:85]
	v_mfma_f32_16x16x32_bf16 v[74:77], v[180:183], v[228:231], v[74:77]
	s_setprio 0
	s_setprio 1
	v_mfma_f32_16x16x32_bf16 v[118:121], v[184:187], v[200:203], v[118:121]
	v_mfma_f32_16x16x32_bf16 v[110:113], v[192:195], v[200:203], v[110:113]
	v_mfma_f32_16x16x32_bf16 v[102:105], v[184:187], v[208:211], v[102:105]
	v_mfma_f32_16x16x32_bf16 v[94:97], v[192:195], v[208:211], v[94:97]
	v_mfma_f32_16x16x32_bf16 v[86:89], v[184:187], v[216:219], v[86:89]
	v_mfma_f32_16x16x32_bf16 v[78:81], v[192:195], v[216:219], v[78:81]
	v_mfma_f32_16x16x32_bf16 v[70:73], v[184:187], v[224:227], v[70:73]
	v_mfma_f32_16x16x32_bf16 v[66:69], v[192:195], v[224:227], v[66:69]
	v_mfma_f32_16x16x32_bf16 v[118:121], v[188:191], v[204:207], v[118:121]
	v_mfma_f32_16x16x32_bf16 v[110:113], v[196:199], v[204:207], v[110:113]
	v_mfma_f32_16x16x32_bf16 v[102:105], v[188:191], v[212:215], v[102:105]
	v_mfma_f32_16x16x32_bf16 v[94:97], v[196:199], v[212:215], v[94:97]
	v_mfma_f32_16x16x32_bf16 v[86:89], v[188:191], v[220:223], v[86:89]
	v_mfma_f32_16x16x32_bf16 v[78:81], v[196:199], v[220:223], v[78:81]
	v_mfma_f32_16x16x32_bf16 v[70:73], v[188:191], v[228:231], v[70:73]
	v_mfma_f32_16x16x32_bf16 v[66:69], v[196:199], v[228:231], v[66:69]
	s_barrier
	s_setprio 0
	s_add_i32 s30, s63, s42
	v_lshl_add_u64 v[154:155], v[154:155], 0, s[8:9]
	s_mov_b32 m0, s30
	ds_read_b128 v[200:203], v165 offset:49152
	ds_read_b128 v[204:207], v165 offset:50176
	ds_read_b128 v[208:211], v165 offset:51200
	ds_read_b128 v[212:215], v165 offset:52224
	ds_read_b128 v[216:219], v165 offset:53248
	ds_read_b128 v[220:223], v165 offset:54272
	ds_read_b128 v[224:227], v165 offset:55296
	ds_read_b128 v[228:231], v165 offset:56320
	global_load_lds_dwordx4 v[154:155], off
	s_add_i32 m0, s30, 0x2000
	s_add_u32 s26, s26, 0x80080
	v_lshl_add_u64 v[154:155], v[232:233], 0, s[8:9]
	s_addc_u32 s27, s27, 0
	s_add_i32 s30, s64, s42
	global_load_lds_dwordx4 v[154:155], off
	v_lshl_add_u64 v[154:155], s[26:27], 0, v[132:133]
	s_mov_b32 m0, s30
	s_nop 0
	global_load_lds_dwordx4 v[154:155], off
	v_lshl_add_u64 v[154:155], s[26:27], 0, v[136:137]
	s_add_i32 m0, s30, 0x2000
	s_nop 0
	global_load_lds_dwordx4 v[154:155], off
	v_lshl_add_u64 v[154:155], v[234:235], 0, s[8:9]
	s_mov_b32 m0, s51
	s_nop 0
	global_load_lds_dwordx4 v[154:155], off
	v_lshl_add_u64 v[154:155], v[236:237], 0, s[8:9]
	s_mov_b32 m0, s53
	s_nop 0
	global_load_lds_dwordx4 v[154:155], off
	s_waitcnt vmcnt(8) lgkmcnt(0)
	s_barrier
	s_setprio 1
	v_mfma_f32_16x16x32_bf16 v[62:65], v[168:171], v[200:203], v[62:65]
	v_mfma_f32_16x16x32_bf16 v[58:61], v[176:179], v[200:203], v[58:61]
	v_mfma_f32_16x16x32_bf16 v[50:53], v[168:171], v[208:211], v[50:53]
	v_mfma_f32_16x16x32_bf16 v[42:45], v[176:179], v[208:211], v[42:45]
	v_mfma_f32_16x16x32_bf16 v[34:37], v[168:171], v[216:219], v[34:37]
	v_mfma_f32_16x16x32_bf16 v[26:29], v[176:179], v[216:219], v[26:29]
	v_mfma_f32_16x16x32_bf16 v[18:21], v[168:171], v[224:227], v[18:21]
	v_mfma_f32_16x16x32_bf16 v[10:13], v[176:179], v[224:227], v[10:13]
	v_mfma_f32_16x16x32_bf16 v[62:65], v[172:175], v[204:207], v[62:65]
	v_mfma_f32_16x16x32_bf16 v[58:61], v[180:183], v[204:207], v[58:61]
	v_mfma_f32_16x16x32_bf16 v[50:53], v[172:175], v[212:215], v[50:53]
	v_mfma_f32_16x16x32_bf16 v[42:45], v[180:183], v[212:215], v[42:45]
	v_mfma_f32_16x16x32_bf16 v[34:37], v[172:175], v[220:223], v[34:37]
	v_mfma_f32_16x16x32_bf16 v[26:29], v[180:183], v[220:223], v[26:29]
	v_mfma_f32_16x16x32_bf16 v[18:21], v[172:175], v[228:231], v[18:21]
	v_mfma_f32_16x16x32_bf16 v[10:13], v[180:183], v[228:231], v[10:13]
	s_setprio 0
	s_setprio 1
	v_mfma_f32_16x16x32_bf16 v[54:57], v[184:187], v[200:203], v[54:57]
	v_mfma_f32_16x16x32_bf16 v[46:49], v[192:195], v[200:203], v[46:49]
	v_mfma_f32_16x16x32_bf16 v[38:41], v[184:187], v[208:211], v[38:41]
	v_mfma_f32_16x16x32_bf16 v[30:33], v[192:195], v[208:211], v[30:33]
	v_mfma_f32_16x16x32_bf16 v[22:25], v[184:187], v[216:219], v[22:25]
	v_mfma_f32_16x16x32_bf16 v[14:17], v[192:195], v[216:219], v[14:17]
	v_mfma_f32_16x16x32_bf16 v[6:9], v[184:187], v[224:227], v[6:9]
	v_mfma_f32_16x16x32_bf16 v[2:5], v[192:195], v[224:227], v[2:5]
	v_mfma_f32_16x16x32_bf16 v[54:57], v[188:191], v[204:207], v[54:57]
	v_mfma_f32_16x16x32_bf16 v[46:49], v[196:199], v[204:207], v[46:49]
	v_mfma_f32_16x16x32_bf16 v[38:41], v[188:191], v[212:215], v[38:41]
	v_mfma_f32_16x16x32_bf16 v[30:33], v[196:199], v[212:215], v[30:33]
	v_mfma_f32_16x16x32_bf16 v[22:25], v[188:191], v[220:223], v[22:25]
	v_mfma_f32_16x16x32_bf16 v[14:17], v[196:199], v[220:223], v[14:17]
	v_mfma_f32_16x16x32_bf16 v[6:9], v[188:191], v[228:231], v[6:9]
	v_mfma_f32_16x16x32_bf16 v[2:5], v[196:199], v[228:231], v[2:5]
	s_barrier
	s_setprio 0
	s_add_i32 s62, s62, 2
	s_add_u32 s60, s60, 0x100
	s_addc_u32 s61, s61, 0
	s_add_u32 s24, s24, 0x100
	s_addc_u32 s25, s25, 0
	s_cmp_gt_u32 s62, 29
	s_cbranch_scc0 .LBB0_143
	s_and_b64 vcc, exec, s[10:11]
	s_cbranch_vccz .LBB0_146
	s_barrier

.LBB0_268:
	ds_read_b128 v[150:153], v139
	ds_read_b128 v[154:157], v139 offset:1024
	ds_read_b128 v[158:161], v139 offset:2048
	ds_read_b128 v[162:165], v139 offset:3072
	ds_read_b128 v[166:169], v146
	ds_read_b128 v[170:173], v146 offset:1024
	ds_read_b128 v[174:177], v146 offset:2048
	ds_read_b128 v[178:181], v146 offset:3072
	s_add_u32 s18, s14, s16
	s_addc_u32 s19, s15, s17
	s_add_u32 s18, s18, 0x28300100
	s_addc_u32 s19, s19, 0
	s_add_u32 s55, s41, s16
	s_addc_u32 s56, s42, s17
	s_cmpk_eq_i32 s16, 0x300
	s_cselect_b32 s23, s11, s19
	s_cselect_b32 s22, s10, s18
	s_cselect_b32 s19, s9, s56
	s_cselect_b32 s18, s8, s55
	s_mov_b32 m0, s44
	v_lshl_add_u64 v[214:215], v[142:143], 0, s[16:17]
	ds_read_b128 v[182:185], v147
	ds_read_b128 v[186:189], v147 offset:1024
	ds_read_b128 v[190:193], v147 offset:2048
	ds_read_b128 v[194:197], v147 offset:3072
	ds_read_b128 v[198:201], v147 offset:4096
	ds_read_b128 v[202:205], v147 offset:5120
	ds_read_b128 v[206:209], v147 offset:6144
	ds_read_b128 v[210:213], v147 offset:7168
	global_load_lds_dwordx4 v[214:215], off
	v_lshl_add_u64 v[214:215], v[140:141], 0, s[16:17]
	s_mov_b32 m0, s45
	s_nop 0
	global_load_lds_dwordx4 v[214:215], off
	s_waitcnt vmcnt(8) lgkmcnt(0)
	s_barrier
	s_setprio 1
	v_mfma_f32_16x16x32_bf16 v[126:129], v[150:153], v[182:185], v[126:129]
	v_mfma_f32_16x16x32_bf16 v[122:125], v[158:161], v[182:185], v[122:125]
	v_mfma_f32_16x16x32_bf16 v[118:121], v[150:153], v[190:193], v[118:121]
	v_mfma_f32_16x16x32_bf16 v[110:113], v[158:161], v[190:193], v[110:113]
	v_mfma_f32_16x16x32_bf16 v[102:105], v[150:153], v[198:201], v[102:105]
	v_mfma_f32_16x16x32_bf16 v[94:97], v[158:161], v[198:201], v[94:97]
	v_mfma_f32_16x16x32_bf16 v[86:89], v[150:153], v[206:209], v[86:89]
	v_mfma_f32_16x16x32_bf16 v[78:81], v[158:161], v[206:209], v[78:81]
	v_mfma_f32_16x16x32_bf16 v[126:129], v[154:157], v[186:189], v[126:129]
	v_mfma_f32_16x16x32_bf16 v[122:125], v[162:165], v[186:189], v[122:125]
	v_mfma_f32_16x16x32_bf16 v[118:121], v[154:157], v[194:197], v[118:121]
	v_mfma_f32_16x16x32_bf16 v[110:113], v[162:165], v[194:197], v[110:113]
	v_mfma_f32_16x16x32_bf16 v[102:105], v[154:157], v[202:205], v[102:105]
	v_mfma_f32_16x16x32_bf16 v[94:97], v[162:165], v[202:205], v[94:97]
	v_mfma_f32_16x16x32_bf16 v[86:89], v[154:157], v[210:213], v[86:89]
	v_mfma_f32_16x16x32_bf16 v[78:81], v[162:165], v[210:213], v[78:81]
	s_setprio 0
	s_setprio 1
	v_mfma_f32_16x16x32_bf16 v[114:117], v[166:169], v[182:185], v[114:117]
	v_mfma_f32_16x16x32_bf16 v[106:109], v[174:177], v[182:185], v[106:109]
	v_mfma_f32_16x16x32_bf16 v[98:101], v[166:169], v[190:193], v[98:101]
	v_mfma_f32_16x16x32_bf16 v[90:93], v[174:177], v[190:193], v[90:93]
	v_mfma_f32_16x16x32_bf16 v[82:85], v[166:169], v[198:201], v[82:85]
	v_mfma_f32_16x16x32_bf16 v[74:77], v[174:177], v[198:201], v[74:77]
	v_mfma_f32_16x16x32_bf16 v[70:73], v[166:169], v[206:209], v[70:73]
	v_mfma_f32_16x16x32_bf16 v[66:69], v[174:177], v[206:209], v[66:69]
	v_mfma_f32_16x16x32_bf16 v[114:117], v[170:173], v[186:189], v[114:117]
	v_mfma_f32_16x16x32_bf16 v[106:109], v[178:181], v[186:189], v[106:109]
	v_mfma_f32_16x16x32_bf16 v[98:101], v[170:173], v[194:197], v[98:101]
	v_mfma_f32_16x16x32_bf16 v[90:93], v[178:181], v[194:197], v[90:93]
	v_mfma_f32_16x16x32_bf16 v[82:85], v[170:173], v[202:205], v[82:85]
	v_mfma_f32_16x16x32_bf16 v[74:77], v[178:181], v[202:205], v[74:77]
	v_mfma_f32_16x16x32_bf16 v[70:73], v[170:173], v[210:213], v[70:73]
	v_mfma_f32_16x16x32_bf16 v[66:69], v[178:181], v[210:213], v[66:69]
	s_barrier
	s_setprio 0
	s_mov_b32 m0, s46
	v_lshl_add_u64 v[214:215], s[18:19], 0, v[132:133]
	s_add_u32 s56, s18, 0x20000
	ds_read_b128 v[182:185], v147 offset:16384
	ds_read_b128 v[186:189], v147 offset:17408
	ds_read_b128 v[190:193], v147 offset:18432
	ds_read_b128 v[194:197], v147 offset:19456
	ds_read_b128 v[198:201], v147 offset:20480
	ds_read_b128 v[202:205], v147 offset:21504
	ds_read_b128 v[206:209], v147 offset:22528
	ds_read_b128 v[210:213], v147 offset:23552
	global_load_lds_dwordx4 v[214:215], off
	v_lshl_add_u64 v[216:217], s[18:19], 0, v[136:137]
	s_mov_b32 m0, s47
	s_addc_u32 s57, s19, 0
	global_load_lds_dwordx4 v[216:217], off
	v_lshl_add_u64 v[218:219], s[56:57], 0, v[132:133]
	s_mov_b32 m0, s48
	v_lshl_add_u64 v[220:221], s[22:23], 0, v[134:135]
	global_load_lds_dwordx4 v[218:219], off
	v_lshl_add_u64 v[218:219], s[56:57], 0, v[136:137]
	s_mov_b32 m0, s49
	s_nop 0
	global_load_lds_dwordx4 v[218:219], off
	v_lshl_add_u64 v[218:219], s[22:23], 0, v[130:131]
	s_mov_b32 m0, s7
	s_nop 0
	global_load_lds_dwordx4 v[218:219], off
	s_mov_b32 m0, s36
	s_nop 0
	global_load_lds_dwordx4 v[220:221], off
	s_waitcnt vmcnt(8) lgkmcnt(0)
	s_barrier
	s_setprio 1
	v_mfma_f32_16x16x32_bf16 v[62:65], v[150:153], v[182:185], v[62:65]
	v_mfma_f32_16x16x32_bf16 v[58:61], v[158:161], v[182:185], v[58:61]
	v_mfma_f32_16x16x32_bf16 v[54:57], v[150:153], v[190:193], v[54:57]
	v_mfma_f32_16x16x32_bf16 v[46:49], v[158:161], v[190:193], v[46:49]
	v_mfma_f32_16x16x32_bf16 v[38:41], v[150:153], v[198:201], v[38:41]
	v_mfma_f32_16x16x32_bf16 v[30:33], v[158:161], v[198:201], v[30:33]
	v_mfma_f32_16x16x32_bf16 v[22:25], v[150:153], v[206:209], v[22:25]
	v_mfma_f32_16x16x32_bf16 v[14:17], v[158:161], v[206:209], v[14:17]
	v_mfma_f32_16x16x32_bf16 v[62:65], v[154:157], v[186:189], v[62:65]
	v_mfma_f32_16x16x32_bf16 v[58:61], v[162:165], v[186:189], v[58:61]
	v_mfma_f32_16x16x32_bf16 v[54:57], v[154:157], v[194:197], v[54:57]
	v_mfma_f32_16x16x32_bf16 v[46:49], v[162:165], v[194:197], v[46:49]
	v_mfma_f32_16x16x32_bf16 v[38:41], v[154:157], v[202:205], v[38:41]
	v_mfma_f32_16x16x32_bf16 v[30:33], v[162:165], v[202:205], v[30:33]
	v_mfma_f32_16x16x32_bf16 v[22:25], v[154:157], v[210:213], v[22:25]
	v_mfma_f32_16x16x32_bf16 v[14:17], v[162:165], v[210:213], v[14:17]
	s_setprio 0
	s_setprio 1
	v_mfma_f32_16x16x32_bf16 v[50:53], v[166:169], v[182:185], v[50:53]
	v_mfma_f32_16x16x32_bf16 v[42:45], v[174:177], v[182:185], v[42:45]
	v_mfma_f32_16x16x32_bf16 v[34:37], v[166:169], v[190:193], v[34:37]
	v_mfma_f32_16x16x32_bf16 v[26:29], v[174:177], v[190:193], v[26:29]
	v_mfma_f32_16x16x32_bf16 v[18:21], v[166:169], v[198:201], v[18:21]
	v_mfma_f32_16x16x32_bf16 v[10:13], v[174:177], v[198:201], v[10:13]
	v_mfma_f32_16x16x32_bf16 v[6:9], v[166:169], v[206:209], v[6:9]
	v_mfma_f32_16x16x32_bf16 v[2:5], v[174:177], v[206:209], v[2:5]
	v_mfma_f32_16x16x32_bf16 v[50:53], v[170:173], v[186:189], v[50:53]
	v_mfma_f32_16x16x32_bf16 v[42:45], v[178:181], v[186:189], v[42:45]
	v_mfma_f32_16x16x32_bf16 v[34:37], v[170:173], v[194:197], v[34:37]
	v_mfma_f32_16x16x32_bf16 v[26:29], v[178:181], v[194:197], v[26:29]
	v_mfma_f32_16x16x32_bf16 v[18:21], v[170:173], v[202:205], v[18:21]
	v_mfma_f32_16x16x32_bf16 v[10:13], v[178:181], v[202:205], v[10:13]
	v_mfma_f32_16x16x32_bf16 v[6:9], v[170:173], v[210:213], v[6:9]
	v_mfma_f32_16x16x32_bf16 v[2:5], v[178:181], v[210:213], v[2:5]
	s_barrier
	s_setprio 0
	ds_read_b128 v[150:153], v148
	ds_read_b128 v[154:157], v148 offset:1024
	ds_read_b128 v[158:161], v148 offset:2048
	ds_read_b128 v[162:165], v148 offset:3072
	ds_read_b128 v[166:169], v149
	ds_read_b128 v[170:173], v149 offset:1024
	ds_read_b128 v[174:177], v149 offset:2048
	ds_read_b128 v[178:181], v149 offset:3072
	s_add_u32 s22, s22, 0x20000
	s_addc_u32 s23, s23, 0
	s_mov_b32 m0, s37
	v_lshl_add_u64 v[222:223], s[22:23], 0, v[130:131]
	ds_read_b128 v[182:185], v147 offset:32768
	ds_read_b128 v[186:189], v147 offset:33792
	ds_read_b128 v[190:193], v147 offset:34816
	ds_read_b128 v[194:197], v147 offset:35840
	ds_read_b128 v[198:201], v147 offset:36864
	ds_read_b128 v[202:205], v147 offset:37888
	ds_read_b128 v[206:209], v147 offset:38912
	ds_read_b128 v[210:213], v147 offset:39936
	global_load_lds_dwordx4 v[222:223], off
	v_lshl_add_u64 v[222:223], s[22:23], 0, v[134:135]
	s_mov_b32 m0, s38
	s_nop 0
	global_load_lds_dwordx4 v[222:223], off
	s_waitcnt vmcnt(8) lgkmcnt(0)
	s_barrier
	s_setprio 1
	v_mfma_f32_16x16x32_bf16 v[126:129], v[150:153], v[182:185], v[126:129]
	v_mfma_f32_16x16x32_bf16 v[122:125], v[158:161], v[182:185], v[122:125]
	v_mfma_f32_16x16x32_bf16 v[118:121], v[150:153], v[190:193], v[118:121]
	v_mfma_f32_16x16x32_bf16 v[110:113], v[158:161], v[190:193], v[110:113]
	v_mfma_f32_16x16x32_bf16 v[102:105], v[150:153], v[198:201], v[102:105]
	v_mfma_f32_16x16x32_bf16 v[94:97], v[158:161], v[198:201], v[94:97]
	v_mfma_f32_16x16x32_bf16 v[86:89], v[150:153], v[206:209], v[86:89]
	v_mfma_f32_16x16x32_bf16 v[78:81], v[158:161], v[206:209], v[78:81]
	v_mfma_f32_16x16x32_bf16 v[126:129], v[154:157], v[186:189], v[126:129]
	v_mfma_f32_16x16x32_bf16 v[122:125], v[162:165], v[186:189], v[122:125]
	v_mfma_f32_16x16x32_bf16 v[118:121], v[154:157], v[194:197], v[118:121]
	v_mfma_f32_16x16x32_bf16 v[110:113], v[162:165], v[194:197], v[110:113]
	v_mfma_f32_16x16x32_bf16 v[102:105], v[154:157], v[202:205], v[102:105]
	v_mfma_f32_16x16x32_bf16 v[94:97], v[162:165], v[202:205], v[94:97]
	v_mfma_f32_16x16x32_bf16 v[86:89], v[154:157], v[210:213], v[86:89]
	v_mfma_f32_16x16x32_bf16 v[78:81], v[162:165], v[210:213], v[78:81]
	s_setprio 0
	s_setprio 1
	v_mfma_f32_16x16x32_bf16 v[114:117], v[166:169], v[182:185], v[114:117]
	v_mfma_f32_16x16x32_bf16 v[106:109], v[174:177], v[182:185], v[106:109]
	v_mfma_f32_16x16x32_bf16 v[98:101], v[166:169], v[190:193], v[98:101]
	v_mfma_f32_16x16x32_bf16 v[90:93], v[174:177], v[190:193], v[90:93]
	v_mfma_f32_16x16x32_bf16 v[82:85], v[166:169], v[198:201], v[82:85]
	v_mfma_f32_16x16x32_bf16 v[74:77], v[174:177], v[198:201], v[74:77]
	v_mfma_f32_16x16x32_bf16 v[70:73], v[166:169], v[206:209], v[70:73]
	v_mfma_f32_16x16x32_bf16 v[66:69], v[174:177], v[206:209], v[66:69]
	v_mfma_f32_16x16x32_bf16 v[114:117], v[170:173], v[186:189], v[114:117]
	v_mfma_f32_16x16x32_bf16 v[106:109], v[178:181], v[186:189], v[106:109]
	v_mfma_f32_16x16x32_bf16 v[98:101], v[170:173], v[194:197], v[98:101]
	v_mfma_f32_16x16x32_bf16 v[90:93], v[178:181], v[194:197], v[90:93]
	v_mfma_f32_16x16x32_bf16 v[82:85], v[170:173], v[202:205], v[82:85]
	v_mfma_f32_16x16x32_bf16 v[74:77], v[178:181], v[202:205], v[74:77]
	v_mfma_f32_16x16x32_bf16 v[70:73], v[170:173], v[210:213], v[70:73]
	v_mfma_f32_16x16x32_bf16 v[66:69], v[178:181], v[210:213], v[66:69]
	s_barrier
	s_setprio 0
	s_mov_b32 m0, s50
	v_lshl_add_u64 v[214:215], v[214:215], 0, s[12:13]
	s_add_u32 s18, s18, 0x20080
	ds_read_b128 v[182:185], v147 offset:49152
	ds_read_b128 v[186:189], v147 offset:50176
	ds_read_b128 v[190:193], v147 offset:51200
	ds_read_b128 v[194:197], v147 offset:52224
	ds_read_b128 v[198:201], v147 offset:53248
	ds_read_b128 v[202:205], v147 offset:54272
	ds_read_b128 v[206:209], v147 offset:55296
	ds_read_b128 v[210:213], v147 offset:56320
	global_load_lds_dwordx4 v[214:215], off
	v_lshl_add_u64 v[214:215], v[216:217], 0, s[12:13]
	s_mov_b32 m0, s51
	s_addc_u32 s19, s19, 0
	global_load_lds_dwordx4 v[214:215], off
	v_lshl_add_u64 v[214:215], s[18:19], 0, v[132:133]
	s_mov_b32 m0, s53
	s_nop 0
	global_load_lds_dwordx4 v[214:215], off
	v_lshl_add_u64 v[214:215], s[18:19], 0, v[136:137]
	s_mov_b32 m0, s54
	s_nop 0
	global_load_lds_dwordx4 v[214:215], off
	v_lshl_add_u64 v[214:215], v[218:219], 0, s[12:13]
	s_mov_b32 m0, s39
	s_nop 0
	global_load_lds_dwordx4 v[214:215], off
	v_lshl_add_u64 v[214:215], v[220:221], 0, s[12:13]
	s_mov_b32 m0, s40
	s_nop 0
	global_load_lds_dwordx4 v[214:215], off
	s_waitcnt vmcnt(8) lgkmcnt(0)
	s_barrier
	s_setprio 1
	v_mfma_f32_16x16x32_bf16 v[62:65], v[150:153], v[182:185], v[62:65]
	v_mfma_f32_16x16x32_bf16 v[58:61], v[158:161], v[182:185], v[58:61]
	v_mfma_f32_16x16x32_bf16 v[54:57], v[150:153], v[190:193], v[54:57]
	v_mfma_f32_16x16x32_bf16 v[46:49], v[158:161], v[190:193], v[46:49]
	v_mfma_f32_16x16x32_bf16 v[38:41], v[150:153], v[198:201], v[38:41]
	v_mfma_f32_16x16x32_bf16 v[30:33], v[158:161], v[198:201], v[30:33]
	v_mfma_f32_16x16x32_bf16 v[22:25], v[150:153], v[206:209], v[22:25]
	v_mfma_f32_16x16x32_bf16 v[14:17], v[158:161], v[206:209], v[14:17]
	v_mfma_f32_16x16x32_bf16 v[62:65], v[154:157], v[186:189], v[62:65]
	v_mfma_f32_16x16x32_bf16 v[58:61], v[162:165], v[186:189], v[58:61]
	v_mfma_f32_16x16x32_bf16 v[54:57], v[154:157], v[194:197], v[54:57]
	v_mfma_f32_16x16x32_bf16 v[46:49], v[162:165], v[194:197], v[46:49]
	v_mfma_f32_16x16x32_bf16 v[38:41], v[154:157], v[202:205], v[38:41]
	v_mfma_f32_16x16x32_bf16 v[30:33], v[162:165], v[202:205], v[30:33]
	v_mfma_f32_16x16x32_bf16 v[22:25], v[154:157], v[210:213], v[22:25]
	v_mfma_f32_16x16x32_bf16 v[14:17], v[162:165], v[210:213], v[14:17]
	s_setprio 0
	s_setprio 1
	v_mfma_f32_16x16x32_bf16 v[50:53], v[166:169], v[182:185], v[50:53]
	v_mfma_f32_16x16x32_bf16 v[42:45], v[174:177], v[182:185], v[42:45]
	v_mfma_f32_16x16x32_bf16 v[34:37], v[166:169], v[190:193], v[34:37]
	v_mfma_f32_16x16x32_bf16 v[26:29], v[174:177], v[190:193], v[26:29]
	v_mfma_f32_16x16x32_bf16 v[18:21], v[166:169], v[198:201], v[18:21]
	v_mfma_f32_16x16x32_bf16 v[10:13], v[174:177], v[198:201], v[10:13]
	v_mfma_f32_16x16x32_bf16 v[6:9], v[166:169], v[206:209], v[6:9]
	v_mfma_f32_16x16x32_bf16 v[2:5], v[174:177], v[206:209], v[2:5]
	v_mfma_f32_16x16x32_bf16 v[50:53], v[170:173], v[186:189], v[50:53]
	v_mfma_f32_16x16x32_bf16 v[42:45], v[178:181], v[186:189], v[42:45]
	v_mfma_f32_16x16x32_bf16 v[34:37], v[170:173], v[194:197], v[34:37]
	v_mfma_f32_16x16x32_bf16 v[26:29], v[178:181], v[194:197], v[26:29]
	v_mfma_f32_16x16x32_bf16 v[18:21], v[170:173], v[202:205], v[18:21]
	v_mfma_f32_16x16x32_bf16 v[10:13], v[178:181], v[202:205], v[10:13]
	v_mfma_f32_16x16x32_bf16 v[6:9], v[170:173], v[210:213], v[6:9]
	v_mfma_f32_16x16x32_bf16 v[2:5], v[178:181], v[210:213], v[2:5]
	s_barrier
	s_setprio 0
	s_add_i32 s43, s43, 2
	s_add_u32 s16, s16, 0x100
	s_addc_u32 s17, s17, 0
	s_cmp_gt_u32 s43, 5
	s_cbranch_scc0 .LBB0_268
	s_cmpk_lt_u32 s33, 0x100
	s_cbranch_scc0 .LBB0_271
	s_barrier

.LBB0_274:
	ds_read_b128 v[150:153], v144
	ds_read_b128 v[154:157], v144 offset:1024
	ds_read_b128 v[158:161], v144 offset:2048
	ds_read_b128 v[162:165], v144 offset:3072
	ds_read_b128 v[166:169], v145
	ds_read_b128 v[170:173], v145 offset:1024
	ds_read_b128 v[174:177], v145 offset:2048
	ds_read_b128 v[178:181], v145 offset:3072
	s_add_u32 s18, s14, s16
	s_addc_u32 s19, s15, s17
	s_add_u32 s18, s18, 0xf900100
	s_addc_u32 s19, s19, 0
	s_add_u32 s49, s40, s16
	s_addc_u32 s50, s41, s17
	s_cmpk_eq_i32 s16, 0x300
	s_cselect_b32 s23, s11, s19
	s_cselect_b32 s22, s10, s18
	s_cselect_b32 s19, s9, s50
	s_cselect_b32 s18, s8, s49
	s_mov_b32 m0, s43
	v_lshl_add_u64 v[214:215], v[140:141], 0, s[16:17]
	ds_read_b128 v[182:185], v146
	ds_read_b128 v[186:189], v146 offset:1024
	ds_read_b128 v[190:193], v146 offset:2048
	ds_read_b128 v[194:197], v146 offset:3072
	ds_read_b128 v[198:201], v146 offset:4096
	ds_read_b128 v[202:205], v146 offset:5120
	ds_read_b128 v[206:209], v146 offset:6144
	ds_read_b128 v[210:213], v146 offset:7168
	global_load_lds_dwordx4 v[214:215], off
	v_lshl_add_u64 v[214:215], v[138:139], 0, s[16:17]
	s_mov_b32 m0, s44
	s_nop 0
	global_load_lds_dwordx4 v[214:215], off
	s_waitcnt vmcnt(8) lgkmcnt(0)
	s_barrier
	s_setprio 1
	v_mfma_f32_16x16x32_bf16 v[126:129], v[150:153], v[182:185], v[126:129]
	v_mfma_f32_16x16x32_bf16 v[122:125], v[158:161], v[182:185], v[122:125]
	v_mfma_f32_16x16x32_bf16 v[118:121], v[150:153], v[190:193], v[118:121]
	v_mfma_f32_16x16x32_bf16 v[110:113], v[158:161], v[190:193], v[110:113]
	v_mfma_f32_16x16x32_bf16 v[102:105], v[150:153], v[198:201], v[102:105]
	v_mfma_f32_16x16x32_bf16 v[94:97], v[158:161], v[198:201], v[94:97]
	v_mfma_f32_16x16x32_bf16 v[86:89], v[150:153], v[206:209], v[86:89]
	v_mfma_f32_16x16x32_bf16 v[78:81], v[158:161], v[206:209], v[78:81]
	v_mfma_f32_16x16x32_bf16 v[126:129], v[154:157], v[186:189], v[126:129]
	v_mfma_f32_16x16x32_bf16 v[122:125], v[162:165], v[186:189], v[122:125]
	v_mfma_f32_16x16x32_bf16 v[118:121], v[154:157], v[194:197], v[118:121]
	v_mfma_f32_16x16x32_bf16 v[110:113], v[162:165], v[194:197], v[110:113]
	v_mfma_f32_16x16x32_bf16 v[102:105], v[154:157], v[202:205], v[102:105]
	v_mfma_f32_16x16x32_bf16 v[94:97], v[162:165], v[202:205], v[94:97]
	v_mfma_f32_16x16x32_bf16 v[86:89], v[154:157], v[210:213], v[86:89]
	v_mfma_f32_16x16x32_bf16 v[78:81], v[162:165], v[210:213], v[78:81]
	s_setprio 0
	s_setprio 1
	v_mfma_f32_16x16x32_bf16 v[114:117], v[166:169], v[182:185], v[114:117]
	v_mfma_f32_16x16x32_bf16 v[106:109], v[174:177], v[182:185], v[106:109]
	v_mfma_f32_16x16x32_bf16 v[98:101], v[166:169], v[190:193], v[98:101]
	v_mfma_f32_16x16x32_bf16 v[90:93], v[174:177], v[190:193], v[90:93]
	v_mfma_f32_16x16x32_bf16 v[82:85], v[166:169], v[198:201], v[82:85]
	v_mfma_f32_16x16x32_bf16 v[74:77], v[174:177], v[198:201], v[74:77]
	v_mfma_f32_16x16x32_bf16 v[70:73], v[166:169], v[206:209], v[70:73]
	v_mfma_f32_16x16x32_bf16 v[66:69], v[174:177], v[206:209], v[66:69]
	v_mfma_f32_16x16x32_bf16 v[114:117], v[170:173], v[186:189], v[114:117]
	v_mfma_f32_16x16x32_bf16 v[106:109], v[178:181], v[186:189], v[106:109]
	v_mfma_f32_16x16x32_bf16 v[98:101], v[170:173], v[194:197], v[98:101]
	v_mfma_f32_16x16x32_bf16 v[90:93], v[178:181], v[194:197], v[90:93]
	v_mfma_f32_16x16x32_bf16 v[82:85], v[170:173], v[202:205], v[82:85]
	v_mfma_f32_16x16x32_bf16 v[74:77], v[178:181], v[202:205], v[74:77]
	v_mfma_f32_16x16x32_bf16 v[70:73], v[170:173], v[210:213], v[70:73]
	v_mfma_f32_16x16x32_bf16 v[66:69], v[178:181], v[210:213], v[66:69]
	s_barrier
	s_setprio 0
	s_mov_b32 m0, s25
	v_lshl_add_u64 v[214:215], s[18:19], 0, v[130:131]
	s_add_u32 s50, s18, 0x20000
	ds_read_b128 v[182:185], v146 offset:16384
	ds_read_b128 v[186:189], v146 offset:17408
	ds_read_b128 v[190:193], v146 offset:18432
	ds_read_b128 v[194:197], v146 offset:19456
	ds_read_b128 v[198:201], v146 offset:20480
	ds_read_b128 v[202:205], v146 offset:21504
	ds_read_b128 v[206:209], v146 offset:22528
	ds_read_b128 v[210:213], v146 offset:23552
	global_load_lds_dwordx4 v[214:215], off
	v_lshl_add_u64 v[216:217], s[18:19], 0, v[136:137]
	s_mov_b32 m0, s45
	s_addc_u32 s51, s19, 0
	global_load_lds_dwordx4 v[216:217], off
	v_lshl_add_u64 v[218:219], s[50:51], 0, v[130:131]
	s_mov_b32 m0, s26
	v_lshl_add_u64 v[220:221], s[22:23], 0, v[134:135]
	global_load_lds_dwordx4 v[218:219], off
	v_lshl_add_u64 v[218:219], s[50:51], 0, v[136:137]
	s_mov_b32 m0, s46
	s_nop 0
	global_load_lds_dwordx4 v[218:219], off
	v_lshl_add_u64 v[218:219], s[22:23], 0, v[132:133]
	s_mov_b32 m0, s7
	s_nop 0
	global_load_lds_dwordx4 v[218:219], off
	s_mov_b32 m0, s34
	s_nop 0
	global_load_lds_dwordx4 v[220:221], off
	s_waitcnt vmcnt(8) lgkmcnt(0)
	s_barrier
	s_setprio 1
	v_mfma_f32_16x16x32_bf16 v[62:65], v[150:153], v[182:185], v[62:65]
	v_mfma_f32_16x16x32_bf16 v[58:61], v[158:161], v[182:185], v[58:61]
	v_mfma_f32_16x16x32_bf16 v[54:57], v[150:153], v[190:193], v[54:57]
	v_mfma_f32_16x16x32_bf16 v[46:49], v[158:161], v[190:193], v[46:49]
	v_mfma_f32_16x16x32_bf16 v[38:41], v[150:153], v[198:201], v[38:41]
	v_mfma_f32_16x16x32_bf16 v[30:33], v[158:161], v[198:201], v[30:33]
	v_mfma_f32_16x16x32_bf16 v[22:25], v[150:153], v[206:209], v[22:25]
	v_mfma_f32_16x16x32_bf16 v[14:17], v[158:161], v[206:209], v[14:17]
	v_mfma_f32_16x16x32_bf16 v[62:65], v[154:157], v[186:189], v[62:65]
	v_mfma_f32_16x16x32_bf16 v[58:61], v[162:165], v[186:189], v[58:61]
	v_mfma_f32_16x16x32_bf16 v[54:57], v[154:157], v[194:197], v[54:57]
	v_mfma_f32_16x16x32_bf16 v[46:49], v[162:165], v[194:197], v[46:49]
	v_mfma_f32_16x16x32_bf16 v[38:41], v[154:157], v[202:205], v[38:41]
	v_mfma_f32_16x16x32_bf16 v[30:33], v[162:165], v[202:205], v[30:33]
	v_mfma_f32_16x16x32_bf16 v[22:25], v[154:157], v[210:213], v[22:25]
	v_mfma_f32_16x16x32_bf16 v[14:17], v[162:165], v[210:213], v[14:17]
	s_setprio 0
	s_setprio 1
	v_mfma_f32_16x16x32_bf16 v[50:53], v[166:169], v[182:185], v[50:53]
	v_mfma_f32_16x16x32_bf16 v[42:45], v[174:177], v[182:185], v[42:45]
	v_mfma_f32_16x16x32_bf16 v[34:37], v[166:169], v[190:193], v[34:37]
	v_mfma_f32_16x16x32_bf16 v[26:29], v[174:177], v[190:193], v[26:29]
	v_mfma_f32_16x16x32_bf16 v[18:21], v[166:169], v[198:201], v[18:21]
	v_mfma_f32_16x16x32_bf16 v[10:13], v[174:177], v[198:201], v[10:13]
	v_mfma_f32_16x16x32_bf16 v[6:9], v[166:169], v[206:209], v[6:9]
	v_mfma_f32_16x16x32_bf16 v[2:5], v[174:177], v[206:209], v[2:5]
	v_mfma_f32_16x16x32_bf16 v[50:53], v[170:173], v[186:189], v[50:53]
	v_mfma_f32_16x16x32_bf16 v[42:45], v[178:181], v[186:189], v[42:45]
	v_mfma_f32_16x16x32_bf16 v[34:37], v[170:173], v[194:197], v[34:37]
	v_mfma_f32_16x16x32_bf16 v[26:29], v[178:181], v[194:197], v[26:29]
	v_mfma_f32_16x16x32_bf16 v[18:21], v[170:173], v[202:205], v[18:21]
	v_mfma_f32_16x16x32_bf16 v[10:13], v[178:181], v[202:205], v[10:13]
	v_mfma_f32_16x16x32_bf16 v[6:9], v[170:173], v[210:213], v[6:9]
	v_mfma_f32_16x16x32_bf16 v[2:5], v[178:181], v[210:213], v[2:5]
	s_barrier
	s_setprio 0
	ds_read_b128 v[150:153], v147
	ds_read_b128 v[154:157], v147 offset:1024
	ds_read_b128 v[158:161], v147 offset:2048
	ds_read_b128 v[162:165], v147 offset:3072
	ds_read_b128 v[166:169], v148
	ds_read_b128 v[170:173], v148 offset:1024
	ds_read_b128 v[174:177], v148 offset:2048
	ds_read_b128 v[178:181], v148 offset:3072
	s_add_u32 s22, s22, 0x20000
	s_addc_u32 s23, s23, 0
	s_mov_b32 m0, s35
	v_lshl_add_u64 v[222:223], s[22:23], 0, v[132:133]
	ds_read_b128 v[182:185], v146 offset:32768
	ds_read_b128 v[186:189], v146 offset:33792
	ds_read_b128 v[190:193], v146 offset:34816
	ds_read_b128 v[194:197], v146 offset:35840
	ds_read_b128 v[198:201], v146 offset:36864
	ds_read_b128 v[202:205], v146 offset:37888
	ds_read_b128 v[206:209], v146 offset:38912
	ds_read_b128 v[210:213], v146 offset:39936
	global_load_lds_dwordx4 v[222:223], off
	v_lshl_add_u64 v[222:223], s[22:23], 0, v[134:135]
	s_mov_b32 m0, s36
	s_nop 0
	global_load_lds_dwordx4 v[222:223], off
	s_waitcnt vmcnt(8) lgkmcnt(0)
	s_barrier
	s_setprio 1
	v_mfma_f32_16x16x32_bf16 v[126:129], v[150:153], v[182:185], v[126:129]
	v_mfma_f32_16x16x32_bf16 v[122:125], v[158:161], v[182:185], v[122:125]
	v_mfma_f32_16x16x32_bf16 v[118:121], v[150:153], v[190:193], v[118:121]
	v_mfma_f32_16x16x32_bf16 v[110:113], v[158:161], v[190:193], v[110:113]
	v_mfma_f32_16x16x32_bf16 v[102:105], v[150:153], v[198:201], v[102:105]
	v_mfma_f32_16x16x32_bf16 v[94:97], v[158:161], v[198:201], v[94:97]
	v_mfma_f32_16x16x32_bf16 v[86:89], v[150:153], v[206:209], v[86:89]
	v_mfma_f32_16x16x32_bf16 v[78:81], v[158:161], v[206:209], v[78:81]
	v_mfma_f32_16x16x32_bf16 v[126:129], v[154:157], v[186:189], v[126:129]
	v_mfma_f32_16x16x32_bf16 v[122:125], v[162:165], v[186:189], v[122:125]
	v_mfma_f32_16x16x32_bf16 v[118:121], v[154:157], v[194:197], v[118:121]
	v_mfma_f32_16x16x32_bf16 v[110:113], v[162:165], v[194:197], v[110:113]
	v_mfma_f32_16x16x32_bf16 v[102:105], v[154:157], v[202:205], v[102:105]
	v_mfma_f32_16x16x32_bf16 v[94:97], v[162:165], v[202:205], v[94:97]
	v_mfma_f32_16x16x32_bf16 v[86:89], v[154:157], v[210:213], v[86:89]
	v_mfma_f32_16x16x32_bf16 v[78:81], v[162:165], v[210:213], v[78:81]
	s_setprio 0
	s_setprio 1
	v_mfma_f32_16x16x32_bf16 v[114:117], v[166:169], v[182:185], v[114:117]
	v_mfma_f32_16x16x32_bf16 v[106:109], v[174:177], v[182:185], v[106:109]
	v_mfma_f32_16x16x32_bf16 v[98:101], v[166:169], v[190:193], v[98:101]
	v_mfma_f32_16x16x32_bf16 v[90:93], v[174:177], v[190:193], v[90:93]
	v_mfma_f32_16x16x32_bf16 v[82:85], v[166:169], v[198:201], v[82:85]
	v_mfma_f32_16x16x32_bf16 v[74:77], v[174:177], v[198:201], v[74:77]
	v_mfma_f32_16x16x32_bf16 v[70:73], v[166:169], v[206:209], v[70:73]
	v_mfma_f32_16x16x32_bf16 v[66:69], v[174:177], v[206:209], v[66:69]
	v_mfma_f32_16x16x32_bf16 v[114:117], v[170:173], v[186:189], v[114:117]
	v_mfma_f32_16x16x32_bf16 v[106:109], v[178:181], v[186:189], v[106:109]
	v_mfma_f32_16x16x32_bf16 v[98:101], v[170:173], v[194:197], v[98:101]
	v_mfma_f32_16x16x32_bf16 v[90:93], v[178:181], v[194:197], v[90:93]
	v_mfma_f32_16x16x32_bf16 v[82:85], v[170:173], v[202:205], v[82:85]
	v_mfma_f32_16x16x32_bf16 v[74:77], v[178:181], v[202:205], v[74:77]
	v_mfma_f32_16x16x32_bf16 v[70:73], v[170:173], v[210:213], v[70:73]
	v_mfma_f32_16x16x32_bf16 v[66:69], v[178:181], v[210:213], v[66:69]
	s_barrier
	s_setprio 0
	s_mov_b32 m0, s27
	v_lshl_add_u64 v[214:215], v[214:215], 0, s[12:13]
	s_add_u32 s18, s18, 0x20080
	ds_read_b128 v[182:185], v146 offset:49152
	ds_read_b128 v[186:189], v146 offset:50176
	ds_read_b128 v[190:193], v146 offset:51200
	ds_read_b128 v[194:197], v146 offset:52224
	ds_read_b128 v[198:201], v146 offset:53248
	ds_read_b128 v[202:205], v146 offset:54272
	ds_read_b128 v[206:209], v146 offset:55296
	ds_read_b128 v[210:213], v146 offset:56320
	global_load_lds_dwordx4 v[214:215], off
	v_lshl_add_u64 v[214:215], v[216:217], 0, s[12:13]
	s_mov_b32 m0, s47
	s_addc_u32 s19, s19, 0
	global_load_lds_dwordx4 v[214:215], off
	v_lshl_add_u64 v[214:215], s[18:19], 0, v[130:131]
	s_mov_b32 m0, s30
	s_nop 0
	global_load_lds_dwordx4 v[214:215], off
	v_lshl_add_u64 v[214:215], s[18:19], 0, v[136:137]
	s_mov_b32 m0, s48
	s_nop 0
	global_load_lds_dwordx4 v[214:215], off
	v_lshl_add_u64 v[214:215], v[218:219], 0, s[12:13]
	s_mov_b32 m0, s38
	s_nop 0
	global_load_lds_dwordx4 v[214:215], off
	v_lshl_add_u64 v[214:215], v[220:221], 0, s[12:13]
	s_mov_b32 m0, s39
	s_nop 0
	global_load_lds_dwordx4 v[214:215], off
	s_waitcnt vmcnt(8) lgkmcnt(0)
	s_barrier
	s_setprio 1
	v_mfma_f32_16x16x32_bf16 v[62:65], v[150:153], v[182:185], v[62:65]
	v_mfma_f32_16x16x32_bf16 v[58:61], v[158:161], v[182:185], v[58:61]
	v_mfma_f32_16x16x32_bf16 v[54:57], v[150:153], v[190:193], v[54:57]
	v_mfma_f32_16x16x32_bf16 v[46:49], v[158:161], v[190:193], v[46:49]
	v_mfma_f32_16x16x32_bf16 v[38:41], v[150:153], v[198:201], v[38:41]
	v_mfma_f32_16x16x32_bf16 v[30:33], v[158:161], v[198:201], v[30:33]
	v_mfma_f32_16x16x32_bf16 v[22:25], v[150:153], v[206:209], v[22:25]
	v_mfma_f32_16x16x32_bf16 v[14:17], v[158:161], v[206:209], v[14:17]
	v_mfma_f32_16x16x32_bf16 v[62:65], v[154:157], v[186:189], v[62:65]
	v_mfma_f32_16x16x32_bf16 v[58:61], v[162:165], v[186:189], v[58:61]
	v_mfma_f32_16x16x32_bf16 v[54:57], v[154:157], v[194:197], v[54:57]
	v_mfma_f32_16x16x32_bf16 v[46:49], v[162:165], v[194:197], v[46:49]
	v_mfma_f32_16x16x32_bf16 v[38:41], v[154:157], v[202:205], v[38:41]
	v_mfma_f32_16x16x32_bf16 v[30:33], v[162:165], v[202:205], v[30:33]
	v_mfma_f32_16x16x32_bf16 v[22:25], v[154:157], v[210:213], v[22:25]
	v_mfma_f32_16x16x32_bf16 v[14:17], v[162:165], v[210:213], v[14:17]
	s_setprio 0
	s_setprio 1
	v_mfma_f32_16x16x32_bf16 v[50:53], v[166:169], v[182:185], v[50:53]
	v_mfma_f32_16x16x32_bf16 v[42:45], v[174:177], v[182:185], v[42:45]
	v_mfma_f32_16x16x32_bf16 v[34:37], v[166:169], v[190:193], v[34:37]
	v_mfma_f32_16x16x32_bf16 v[26:29], v[174:177], v[190:193], v[26:29]
	v_mfma_f32_16x16x32_bf16 v[18:21], v[166:169], v[198:201], v[18:21]
	v_mfma_f32_16x16x32_bf16 v[10:13], v[174:177], v[198:201], v[10:13]
	v_mfma_f32_16x16x32_bf16 v[6:9], v[166:169], v[206:209], v[6:9]
	v_mfma_f32_16x16x32_bf16 v[2:5], v[174:177], v[206:209], v[2:5]
	v_mfma_f32_16x16x32_bf16 v[50:53], v[170:173], v[186:189], v[50:53]
	v_mfma_f32_16x16x32_bf16 v[42:45], v[178:181], v[186:189], v[42:45]
	v_mfma_f32_16x16x32_bf16 v[34:37], v[170:173], v[194:197], v[34:37]
	v_mfma_f32_16x16x32_bf16 v[26:29], v[178:181], v[194:197], v[26:29]
	v_mfma_f32_16x16x32_bf16 v[18:21], v[170:173], v[202:205], v[18:21]
	v_mfma_f32_16x16x32_bf16 v[10:13], v[178:181], v[202:205], v[10:13]
	v_mfma_f32_16x16x32_bf16 v[6:9], v[170:173], v[210:213], v[6:9]
	v_mfma_f32_16x16x32_bf16 v[2:5], v[178:181], v[210:213], v[2:5]
	s_barrier
	s_setprio 0
	s_add_i32 s42, s42, 2
	s_add_u32 s16, s16, 0x100
	s_addc_u32 s17, s17, 0
	s_cmp_gt_u32 s42, 5
	s_cbranch_scc0 .LBB0_274
	s_cmpk_lt_u32 s31, 0x100
	s_cbranch_scc0 .LBB0_277
	s_barrier

.Lpj_skip2_p:
	s_mov_b32 s32, 0
	s_waitcnt lgkmcnt(0)
	s_barrier
	s_setprio 1
	v_mfma_f32_16x16x32_bf16 v[64:67], v[154:157], v[196:199], 0
	v_mfma_f32_16x16x32_bf16 v[60:63], v[172:175], v[196:199], 0
	v_mfma_f32_16x16x32_bf16 v[52:55], v[154:157], v[204:207], 0
	v_mfma_f32_16x16x32_bf16 v[44:47], v[172:175], v[204:207], 0
	v_mfma_f32_16x16x32_bf16 v[36:39], v[154:157], v[212:215], 0
	v_mfma_f32_16x16x32_bf16 v[28:31], v[172:175], v[212:215], 0
	v_mfma_f32_16x16x32_bf16 v[20:23], v[154:157], v[220:223], 0
	v_mfma_f32_16x16x32_bf16 v[12:15], v[172:175], v[220:223], 0
	v_mfma_f32_16x16x32_bf16 v[64:67], v[168:171], v[200:203], v[64:67]
	v_mfma_f32_16x16x32_bf16 v[60:63], v[176:179], v[200:203], v[60:63]
	v_mfma_f32_16x16x32_bf16 v[52:55], v[168:171], v[208:211], v[52:55]
	v_mfma_f32_16x16x32_bf16 v[44:47], v[176:179], v[208:211], v[44:47]
	v_mfma_f32_16x16x32_bf16 v[36:39], v[168:171], v[216:219], v[36:39]
	v_mfma_f32_16x16x32_bf16 v[28:31], v[176:179], v[216:219], v[28:31]
	v_mfma_f32_16x16x32_bf16 v[20:23], v[168:171], v[224:227], v[20:23]
	v_mfma_f32_16x16x32_bf16 v[12:15], v[176:179], v[224:227], v[12:15]
	v_mfma_f32_16x16x32_bf16 v[56:59], v[180:183], v[196:199], 0
	v_mfma_f32_16x16x32_bf16 v[48:51], v[188:191], v[196:199], 0
	v_mfma_f32_16x16x32_bf16 v[40:43], v[180:183], v[204:207], 0
	v_mfma_f32_16x16x32_bf16 v[32:35], v[188:191], v[204:207], 0
	v_mfma_f32_16x16x32_bf16 v[24:27], v[180:183], v[212:215], 0
	v_mfma_f32_16x16x32_bf16 v[16:19], v[188:191], v[212:215], 0
	v_mfma_f32_16x16x32_bf16 v[8:11], v[180:183], v[220:223], 0
	v_mfma_f32_16x16x32_bf16 v[4:7], v[188:191], v[220:223], 0
	v_mfma_f32_16x16x32_bf16 v[56:59], v[184:187], v[200:203], v[56:59]
	v_mfma_f32_16x16x32_bf16 v[48:51], v[192:195], v[200:203], v[48:51]
	v_mfma_f32_16x16x32_bf16 v[40:43], v[184:187], v[208:211], v[40:43]
	v_mfma_f32_16x16x32_bf16 v[32:35], v[192:195], v[208:211], v[32:35]
	v_mfma_f32_16x16x32_bf16 v[24:27], v[184:187], v[216:219], v[24:27]
	v_mfma_f32_16x16x32_bf16 v[16:19], v[192:195], v[216:219], v[16:19]
	v_mfma_f32_16x16x32_bf16 v[8:11], v[184:187], v[224:227], v[8:11]
	v_mfma_f32_16x16x32_bf16 v[4:7], v[192:195], v[224:227], v[4:7]
	s_barrier
	s_setprio 0
	s_add_i32 s33, 0, 0x18000
	s_add_i32 s43, 0, 0x1c000
	ds_read_b128 v[154:157], v229 offset:32768
	ds_read_b128 v[168:171], v229 offset:33792
	ds_read_b128 v[172:175], v229 offset:34816
	ds_read_b128 v[176:179], v229 offset:35840
	ds_read_b128 v[180:183], v229 offset:49152
	ds_read_b128 v[184:187], v229 offset:50176
	ds_read_b128 v[188:191], v229 offset:51200
	ds_read_b128 v[192:195], v229 offset:52224
	s_add_u32 s48, s48, 0x80000
	s_addc_u32 s49, s49, 0
	s_mov_b32 m0, s14
	ds_read_b128 v[196:199], v167 offset:32768
	ds_read_b128 v[200:203], v167 offset:33792
	ds_read_b128 v[204:207], v167 offset:34816
	ds_read_b128 v[208:211], v167 offset:35840
	ds_read_b128 v[212:215], v167 offset:36864
	ds_read_b128 v[216:219], v167 offset:37888
	ds_read_b128 v[220:223], v167 offset:38912
	ds_read_b128 v[224:227], v167 offset:39936
	global_load_lds_dwordx4 v134, s[48:49]
	s_mov_b32 m0, s15
	s_nop 0
	global_load_lds_dwordx4 v132, s[48:49]
	s_waitcnt vmcnt(8) lgkmcnt(0)
	s_barrier
	s_setprio 1
	v_mfma_f32_16x16x32_bf16 v[128:131], v[154:157], v[196:199], v[128:131]
	v_mfma_f32_16x16x32_bf16 v[124:127], v[172:175], v[196:199], v[124:127]
	v_mfma_f32_16x16x32_bf16 v[116:119], v[154:157], v[204:207], v[116:119]
	v_mfma_f32_16x16x32_bf16 v[108:111], v[172:175], v[204:207], v[108:111]
	v_mfma_f32_16x16x32_bf16 v[100:103], v[154:157], v[212:215], v[100:103]
	v_mfma_f32_16x16x32_bf16 v[92:95], v[172:175], v[212:215], v[92:95]
	v_mfma_f32_16x16x32_bf16 v[84:87], v[154:157], v[220:223], v[84:87]
	v_mfma_f32_16x16x32_bf16 v[76:79], v[172:175], v[220:223], v[76:79]
	v_mfma_f32_16x16x32_bf16 v[128:131], v[168:171], v[200:203], v[128:131]
	v_mfma_f32_16x16x32_bf16 v[124:127], v[176:179], v[200:203], v[124:127]
	v_mfma_f32_16x16x32_bf16 v[116:119], v[168:171], v[208:211], v[116:119]
	v_mfma_f32_16x16x32_bf16 v[108:111], v[176:179], v[208:211], v[108:111]
	v_mfma_f32_16x16x32_bf16 v[100:103], v[168:171], v[216:219], v[100:103]
	v_mfma_f32_16x16x32_bf16 v[92:95], v[176:179], v[216:219], v[92:95]
	v_mfma_f32_16x16x32_bf16 v[84:87], v[168:171], v[224:227], v[84:87]
	v_mfma_f32_16x16x32_bf16 v[76:79], v[176:179], v[224:227], v[76:79]
	v_mfma_f32_16x16x32_bf16 v[120:123], v[180:183], v[196:199], v[120:123]
	v_mfma_f32_16x16x32_bf16 v[112:115], v[188:191], v[196:199], v[112:115]
	v_mfma_f32_16x16x32_bf16 v[104:107], v[180:183], v[204:207], v[104:107]
	v_mfma_f32_16x16x32_bf16 v[96:99], v[188:191], v[204:207], v[96:99]
	v_mfma_f32_16x16x32_bf16 v[88:91], v[180:183], v[212:215], v[88:91]
	v_mfma_f32_16x16x32_bf16 v[80:83], v[188:191], v[212:215], v[80:83]
	v_mfma_f32_16x16x32_bf16 v[72:75], v[180:183], v[220:223], v[72:75]
	v_mfma_f32_16x16x32_bf16 v[68:71], v[188:191], v[220:223], v[68:71]
	v_mfma_f32_16x16x32_bf16 v[120:123], v[184:187], v[200:203], v[120:123]
	v_mfma_f32_16x16x32_bf16 v[112:115], v[192:195], v[200:203], v[112:115]
	v_mfma_f32_16x16x32_bf16 v[104:107], v[184:187], v[208:211], v[104:107]
	v_mfma_f32_16x16x32_bf16 v[96:99], v[192:195], v[208:211], v[96:99]
	v_mfma_f32_16x16x32_bf16 v[88:91], v[184:187], v[216:219], v[88:91]
	v_mfma_f32_16x16x32_bf16 v[80:83], v[192:195], v[216:219], v[80:83]
	v_mfma_f32_16x16x32_bf16 v[72:75], v[184:187], v[224:227], v[72:75]
	v_mfma_f32_16x16x32_bf16 v[68:71], v[192:195], v[224:227], v[68:71]
	s_barrier
	s_setprio 0
	s_add_i32 s33, s33, s10
	s_mov_b32 m0, s33
	ds_read_b128 v[196:199], v167 offset:49152
	ds_read_b128 v[200:203], v167 offset:50176
	ds_read_b128 v[204:207], v167 offset:51200
	ds_read_b128 v[208:211], v167 offset:52224
	ds_read_b128 v[212:215], v167 offset:53248
	ds_read_b128 v[216:219], v167 offset:54272
	ds_read_b128 v[220:223], v167 offset:55296
	ds_read_b128 v[224:227], v167 offset:56320
	s_add_u32 s100, s46, 0x80
	s_addc_u32 s101, s47, 0
	global_load_lds_dwordx4 v2, s[100:101]
	s_add_i32 m0, s33, 0x2000
	s_add_u32 s46, s46, 0x80080
	s_addc_u32 s47, s47, 0
	s_add_i32 s33, s43, s10
	s_add_u32 s100, s46, 0xfff80000
	s_addc_u32 s101, s47, -1
	global_load_lds_dwordx4 v0, s[100:101]
	s_mov_b32 m0, s33
	s_nop 0
	global_load_lds_dwordx4 v2, s[46:47]
	s_add_i32 m0, s33, 0x2000
	s_nop 0
	global_load_lds_dwordx4 v0, s[46:47]
	s_mov_b32 m0, s16
	s_nop 0
	s_add_u32 s100, s48, 0xfff80080
	s_addc_u32 s101, s49, -1
	global_load_lds_dwordx4 v134, s[100:101]
	s_mov_b32 m0, s17
	s_nop 0
	s_add_u32 s100, s48, 0xfff80080
	s_addc_u32 s101, s49, -1
	global_load_lds_dwordx4 v132, s[100:101]
	s_add_i32 s35, s35, 2
	s_add_u32 s31, s31, 0x100
	s_addc_u32 s34, s34, 0
	s_add_u32 s44, s44, 0x100
	s_addc_u32 s45, s45, 0
	s_add_u32 s33, s44, 0xfff80080
	s_addc_u32 s43, s45, -1
	s_cmp_eq_u32 s35, 28
	s_cselect_b32 s49, s27, s43
	s_cselect_b32 s48, s28, s33
	s_cselect_b32 s47, s25, s34
	s_cselect_b32 s46, s29, s31
	s_waitcnt vmcnt(8) lgkmcnt(0)
	s_barrier
	s_setprio 1
	v_mfma_f32_16x16x32_bf16 v[64:67], v[154:157], v[196:199], v[64:67]
	v_mfma_f32_16x16x32_bf16 v[60:63], v[172:175], v[196:199], v[60:63]
	v_mfma_f32_16x16x32_bf16 v[52:55], v[154:157], v[204:207], v[52:55]
	v_mfma_f32_16x16x32_bf16 v[44:47], v[172:175], v[204:207], v[44:47]
	v_mfma_f32_16x16x32_bf16 v[36:39], v[154:157], v[212:215], v[36:39]
	v_mfma_f32_16x16x32_bf16 v[28:31], v[172:175], v[212:215], v[28:31]
	v_mfma_f32_16x16x32_bf16 v[20:23], v[154:157], v[220:223], v[20:23]
	v_mfma_f32_16x16x32_bf16 v[12:15], v[172:175], v[220:223], v[12:15]
	v_mfma_f32_16x16x32_bf16 v[64:67], v[168:171], v[200:203], v[64:67]
	v_mfma_f32_16x16x32_bf16 v[60:63], v[176:179], v[200:203], v[60:63]
	v_mfma_f32_16x16x32_bf16 v[52:55], v[168:171], v[208:211], v[52:55]
	v_mfma_f32_16x16x32_bf16 v[44:47], v[176:179], v[208:211], v[44:47]
	v_mfma_f32_16x16x32_bf16 v[36:39], v[168:171], v[216:219], v[36:39]
	v_mfma_f32_16x16x32_bf16 v[28:31], v[176:179], v[216:219], v[28:31]
	v_mfma_f32_16x16x32_bf16 v[20:23], v[168:171], v[224:227], v[20:23]
	v_mfma_f32_16x16x32_bf16 v[12:15], v[176:179], v[224:227], v[12:15]
	v_mfma_f32_16x16x32_bf16 v[56:59], v[180:183], v[196:199], v[56:59]
	v_mfma_f32_16x16x32_bf16 v[48:51], v[188:191], v[196:199], v[48:51]
	v_mfma_f32_16x16x32_bf16 v[40:43], v[180:183], v[204:207], v[40:43]
	v_mfma_f32_16x16x32_bf16 v[32:35], v[188:191], v[204:207], v[32:35]
	v_mfma_f32_16x16x32_bf16 v[24:27], v[180:183], v[212:215], v[24:27]
	v_mfma_f32_16x16x32_bf16 v[16:19], v[188:191], v[212:215], v[16:19]
	v_mfma_f32_16x16x32_bf16 v[8:11], v[180:183], v[220:223], v[8:11]
	v_mfma_f32_16x16x32_bf16 v[4:7], v[188:191], v[220:223], v[4:7]
	v_mfma_f32_16x16x32_bf16 v[56:59], v[184:187], v[200:203], v[56:59]
	v_mfma_f32_16x16x32_bf16 v[48:51], v[192:195], v[200:203], v[48:51]
	v_mfma_f32_16x16x32_bf16 v[40:43], v[184:187], v[208:211], v[40:43]
	v_mfma_f32_16x16x32_bf16 v[32:35], v[192:195], v[208:211], v[32:35]
	v_mfma_f32_16x16x32_bf16 v[24:27], v[184:187], v[216:219], v[24:27]
	v_mfma_f32_16x16x32_bf16 v[16:19], v[192:195], v[216:219], v[16:19]
	v_mfma_f32_16x16x32_bf16 v[8:11], v[184:187], v[224:227], v[8:11]
	v_mfma_f32_16x16x32_bf16 v[4:7], v[192:195], v[224:227], v[4:7]
	s_barrier
	s_setprio 0
.LBB0_342:
	s_add_i32 s50, 0, 0x10000
	s_add_i32 s33, 0, 0x14000
	ds_read_b128 v[154:157], v229
	ds_read_b128 v[168:171], v229 offset:1024
	ds_read_b128 v[172:175], v229 offset:2048
	ds_read_b128 v[176:179], v229 offset:3072
	ds_read_b128 v[180:183], v229 offset:16384
	ds_read_b128 v[184:187], v229 offset:17408
	ds_read_b128 v[188:191], v229 offset:18432
	ds_read_b128 v[192:195], v229 offset:19456
	s_add_i32 m0, s12, 0xc000
	ds_read_b128 v[196:199], v167
	ds_read_b128 v[200:203], v167 offset:1024
	ds_read_b128 v[204:207], v167 offset:2048
	ds_read_b128 v[208:211], v167 offset:3072
	ds_read_b128 v[212:215], v167 offset:4096
	ds_read_b128 v[216:219], v167 offset:5120
	ds_read_b128 v[220:223], v167 offset:6144
	ds_read_b128 v[224:227], v167 offset:7168
	global_load_lds_dwordx4 v140, s[44:45]
	s_add_i32 m0, s12, 0xe000
	s_nop 0
	global_load_lds_dwordx4 v138, s[44:45]
	s_waitcnt vmcnt(8) lgkmcnt(0)
	s_barrier
	s_setprio 1
	v_mfma_f32_16x16x32_bf16 v[128:131], v[154:157], v[196:199], v[128:131]
	v_mfma_f32_16x16x32_bf16 v[124:127], v[172:175], v[196:199], v[124:127]
	v_mfma_f32_16x16x32_bf16 v[116:119], v[154:157], v[204:207], v[116:119]
	v_mfma_f32_16x16x32_bf16 v[108:111], v[172:175], v[204:207], v[108:111]
	v_mfma_f32_16x16x32_bf16 v[100:103], v[154:157], v[212:215], v[100:103]
	v_mfma_f32_16x16x32_bf16 v[92:95], v[172:175], v[212:215], v[92:95]
	v_mfma_f32_16x16x32_bf16 v[84:87], v[154:157], v[220:223], v[84:87]
	v_mfma_f32_16x16x32_bf16 v[76:79], v[172:175], v[220:223], v[76:79]
	v_mfma_f32_16x16x32_bf16 v[128:131], v[168:171], v[200:203], v[128:131]
	v_mfma_f32_16x16x32_bf16 v[124:127], v[176:179], v[200:203], v[124:127]
	v_mfma_f32_16x16x32_bf16 v[116:119], v[168:171], v[208:211], v[116:119]
	v_mfma_f32_16x16x32_bf16 v[108:111], v[176:179], v[208:211], v[108:111]
	v_mfma_f32_16x16x32_bf16 v[100:103], v[168:171], v[216:219], v[100:103]
	v_mfma_f32_16x16x32_bf16 v[92:95], v[176:179], v[216:219], v[92:95]
	v_mfma_f32_16x16x32_bf16 v[84:87], v[168:171], v[224:227], v[84:87]
	v_mfma_f32_16x16x32_bf16 v[76:79], v[176:179], v[224:227], v[76:79]
	v_mfma_f32_16x16x32_bf16 v[120:123], v[180:183], v[196:199], v[120:123]
	v_mfma_f32_16x16x32_bf16 v[112:115], v[188:191], v[196:199], v[112:115]
	v_mfma_f32_16x16x32_bf16 v[104:107], v[180:183], v[204:207], v[104:107]
	v_mfma_f32_16x16x32_bf16 v[96:99], v[188:191], v[204:207], v[96:99]
	v_mfma_f32_16x16x32_bf16 v[88:91], v[180:183], v[212:215], v[88:91]
	v_mfma_f32_16x16x32_bf16 v[80:83], v[188:191], v[212:215], v[80:83]
	v_mfma_f32_16x16x32_bf16 v[72:75], v[180:183], v[220:223], v[72:75]
	v_mfma_f32_16x16x32_bf16 v[68:71], v[188:191], v[220:223], v[68:71]
	v_mfma_f32_16x16x32_bf16 v[120:123], v[184:187], v[200:203], v[120:123]
	v_mfma_f32_16x16x32_bf16 v[112:115], v[192:195], v[200:203], v[112:115]
	v_mfma_f32_16x16x32_bf16 v[104:107], v[184:187], v[208:211], v[104:107]
	v_mfma_f32_16x16x32_bf16 v[96:99], v[192:195], v[208:211], v[96:99]
	v_mfma_f32_16x16x32_bf16 v[88:91], v[184:187], v[216:219], v[88:91]
	v_mfma_f32_16x16x32_bf16 v[80:83], v[192:195], v[216:219], v[80:83]
	v_mfma_f32_16x16x32_bf16 v[72:75], v[184:187], v[224:227], v[72:75]
	v_mfma_f32_16x16x32_bf16 v[68:71], v[192:195], v[224:227], v[68:71]
	s_barrier
	s_setprio 0
	s_add_i32 s43, s50, s10
	s_mov_b32 m0, s43
	ds_read_b128 v[196:199], v167 offset:16384
	ds_read_b128 v[200:203], v167 offset:17408
	ds_read_b128 v[204:207], v167 offset:18432
	ds_read_b128 v[208:211], v167 offset:19456
	ds_read_b128 v[212:215], v167 offset:20480
	ds_read_b128 v[216:219], v167 offset:21504
	ds_read_b128 v[220:223], v167 offset:22528
	ds_read_b128 v[224:227], v167 offset:23552
	global_load_lds_dwordx4 v2, s[46:47]
	s_add_i32 m0, s43, 0x2000
	s_add_u32 s50, s46, 0x80000
	s_addc_u32 s51, s47, 0
	s_add_i32 s33, s33, s10
	global_load_lds_dwordx4 v0, s[46:47]
	s_mov_b32 m0, s33
	s_nop 0
	global_load_lds_dwordx4 v2, s[50:51]
	s_add_i32 m0, s33, 0x2000
	s_nop 0
	global_load_lds_dwordx4 v0, s[50:51]
	s_mov_b32 m0, s12
	s_nop 0
	global_load_lds_dwordx4 v134, s[48:49]
	s_mov_b32 m0, s13
	s_nop 0
	global_load_lds_dwordx4 v132, s[48:49]
	s_waitcnt vmcnt(8) lgkmcnt(0)
	s_barrier
	s_setprio 1
	v_mfma_f32_16x16x32_bf16 v[64:67], v[154:157], v[196:199], v[64:67]
	v_mfma_f32_16x16x32_bf16 v[60:63], v[172:175], v[196:199], v[60:63]
	v_mfma_f32_16x16x32_bf16 v[52:55], v[154:157], v[204:207], v[52:55]
	v_mfma_f32_16x16x32_bf16 v[44:47], v[172:175], v[204:207], v[44:47]
	v_mfma_f32_16x16x32_bf16 v[36:39], v[154:157], v[212:215], v[36:39]
	v_mfma_f32_16x16x32_bf16 v[28:31], v[172:175], v[212:215], v[28:31]
	v_mfma_f32_16x16x32_bf16 v[20:23], v[154:157], v[220:223], v[20:23]
	v_mfma_f32_16x16x32_bf16 v[12:15], v[172:175], v[220:223], v[12:15]
	v_mfma_f32_16x16x32_bf16 v[64:67], v[168:171], v[200:203], v[64:67]
	v_mfma_f32_16x16x32_bf16 v[60:63], v[176:179], v[200:203], v[60:63]
	v_mfma_f32_16x16x32_bf16 v[52:55], v[168:171], v[208:211], v[52:55]
	v_mfma_f32_16x16x32_bf16 v[44:47], v[176:179], v[208:211], v[44:47]
	v_mfma_f32_16x16x32_bf16 v[36:39], v[168:171], v[216:219], v[36:39]
	v_mfma_f32_16x16x32_bf16 v[28:31], v[176:179], v[216:219], v[28:31]
	v_mfma_f32_16x16x32_bf16 v[20:23], v[168:171], v[224:227], v[20:23]
	v_mfma_f32_16x16x32_bf16 v[12:15], v[176:179], v[224:227], v[12:15]
	v_mfma_f32_16x16x32_bf16 v[56:59], v[180:183], v[196:199], v[56:59]
	v_mfma_f32_16x16x32_bf16 v[48:51], v[188:191], v[196:199], v[48:51]
	v_mfma_f32_16x16x32_bf16 v[40:43], v[180:183], v[204:207], v[40:43]
	v_mfma_f32_16x16x32_bf16 v[32:35], v[188:191], v[204:207], v[32:35]
	v_mfma_f32_16x16x32_bf16 v[24:27], v[180:183], v[212:215], v[24:27]
	v_mfma_f32_16x16x32_bf16 v[16:19], v[188:191], v[212:215], v[16:19]
	v_mfma_f32_16x16x32_bf16 v[8:11], v[180:183], v[220:223], v[8:11]
	v_mfma_f32_16x16x32_bf16 v[4:7], v[188:191], v[220:223], v[4:7]
	v_mfma_f32_16x16x32_bf16 v[56:59], v[184:187], v[200:203], v[56:59]
	v_mfma_f32_16x16x32_bf16 v[48:51], v[192:195], v[200:203], v[48:51]
	v_mfma_f32_16x16x32_bf16 v[40:43], v[184:187], v[208:211], v[40:43]
	v_mfma_f32_16x16x32_bf16 v[32:35], v[192:195], v[208:211], v[32:35]
	v_mfma_f32_16x16x32_bf16 v[24:27], v[184:187], v[216:219], v[24:27]
	v_mfma_f32_16x16x32_bf16 v[16:19], v[192:195], v[216:219], v[16:19]
	v_mfma_f32_16x16x32_bf16 v[8:11], v[184:187], v[224:227], v[8:11]
	v_mfma_f32_16x16x32_bf16 v[4:7], v[192:195], v[224:227], v[4:7]
	s_barrier
	s_setprio 0
	s_add_i32 s33, 0, 0x18000
	s_add_i32 s43, 0, 0x1c000
	ds_read_b128 v[154:157], v229 offset:32768
	ds_read_b128 v[168:171], v229 offset:33792
	ds_read_b128 v[172:175], v229 offset:34816
	ds_read_b128 v[176:179], v229 offset:35840
	ds_read_b128 v[180:183], v229 offset:49152
	ds_read_b128 v[184:187], v229 offset:50176
	ds_read_b128 v[188:191], v229 offset:51200
	ds_read_b128 v[192:195], v229 offset:52224
	s_add_u32 s48, s48, 0x80000
	s_addc_u32 s49, s49, 0
	s_mov_b32 m0, s14
	ds_read_b128 v[196:199], v167 offset:32768
	ds_read_b128 v[200:203], v167 offset:33792
	ds_read_b128 v[204:207], v167 offset:34816
	ds_read_b128 v[208:211], v167 offset:35840
	ds_read_b128 v[212:215], v167 offset:36864
	ds_read_b128 v[216:219], v167 offset:37888
	ds_read_b128 v[220:223], v167 offset:38912
	ds_read_b128 v[224:227], v167 offset:39936
	global_load_lds_dwordx4 v134, s[48:49]
	s_mov_b32 m0, s15
	s_nop 0
	global_load_lds_dwordx4 v132, s[48:49]
	s_waitcnt vmcnt(8) lgkmcnt(0)
	s_barrier
	s_setprio 1
	v_mfma_f32_16x16x32_bf16 v[128:131], v[154:157], v[196:199], v[128:131]
	v_mfma_f32_16x16x32_bf16 v[124:127], v[172:175], v[196:199], v[124:127]
	v_mfma_f32_16x16x32_bf16 v[116:119], v[154:157], v[204:207], v[116:119]
	v_mfma_f32_16x16x32_bf16 v[108:111], v[172:175], v[204:207], v[108:111]
	v_mfma_f32_16x16x32_bf16 v[100:103], v[154:157], v[212:215], v[100:103]
	v_mfma_f32_16x16x32_bf16 v[92:95], v[172:175], v[212:215], v[92:95]
	v_mfma_f32_16x16x32_bf16 v[84:87], v[154:157], v[220:223], v[84:87]
	v_mfma_f32_16x16x32_bf16 v[76:79], v[172:175], v[220:223], v[76:79]
	v_mfma_f32_16x16x32_bf16 v[128:131], v[168:171], v[200:203], v[128:131]
	v_mfma_f32_16x16x32_bf16 v[124:127], v[176:179], v[200:203], v[124:127]
	v_mfma_f32_16x16x32_bf16 v[116:119], v[168:171], v[208:211], v[116:119]
	v_mfma_f32_16x16x32_bf16 v[108:111], v[176:179], v[208:211], v[108:111]
	v_mfma_f32_16x16x32_bf16 v[100:103], v[168:171], v[216:219], v[100:103]
	v_mfma_f32_16x16x32_bf16 v[92:95], v[176:179], v[216:219], v[92:95]
	v_mfma_f32_16x16x32_bf16 v[84:87], v[168:171], v[224:227], v[84:87]
	v_mfma_f32_16x16x32_bf16 v[76:79], v[176:179], v[224:227], v[76:79]
	v_mfma_f32_16x16x32_bf16 v[120:123], v[180:183], v[196:199], v[120:123]
	v_mfma_f32_16x16x32_bf16 v[112:115], v[188:191], v[196:199], v[112:115]
	v_mfma_f32_16x16x32_bf16 v[104:107], v[180:183], v[204:207], v[104:107]
	v_mfma_f32_16x16x32_bf16 v[96:99], v[188:191], v[204:207], v[96:99]
	v_mfma_f32_16x16x32_bf16 v[88:91], v[180:183], v[212:215], v[88:91]
	v_mfma_f32_16x16x32_bf16 v[80:83], v[188:191], v[212:215], v[80:83]
	v_mfma_f32_16x16x32_bf16 v[72:75], v[180:183], v[220:223], v[72:75]
	v_mfma_f32_16x16x32_bf16 v[68:71], v[188:191], v[220:223], v[68:71]
	v_mfma_f32_16x16x32_bf16 v[120:123], v[184:187], v[200:203], v[120:123]
	v_mfma_f32_16x16x32_bf16 v[112:115], v[192:195], v[200:203], v[112:115]
	v_mfma_f32_16x16x32_bf16 v[104:107], v[184:187], v[208:211], v[104:107]
	v_mfma_f32_16x16x32_bf16 v[96:99], v[192:195], v[208:211], v[96:99]
	v_mfma_f32_16x16x32_bf16 v[88:91], v[184:187], v[216:219], v[88:91]
	v_mfma_f32_16x16x32_bf16 v[80:83], v[192:195], v[216:219], v[80:83]
	v_mfma_f32_16x16x32_bf16 v[72:75], v[184:187], v[224:227], v[72:75]
	v_mfma_f32_16x16x32_bf16 v[68:71], v[192:195], v[224:227], v[68:71]
	s_barrier
	s_setprio 0
	s_add_i32 s33, s33, s10
	s_mov_b32 m0, s33
	ds_read_b128 v[196:199], v167 offset:49152
	ds_read_b128 v[200:203], v167 offset:50176
	ds_read_b128 v[204:207], v167 offset:51200
	ds_read_b128 v[208:211], v167 offset:52224
	ds_read_b128 v[212:215], v167 offset:53248
	ds_read_b128 v[216:219], v167 offset:54272
	ds_read_b128 v[220:223], v167 offset:55296
	ds_read_b128 v[224:227], v167 offset:56320
	s_add_u32 s100, s46, 0x80
	s_addc_u32 s101, s47, 0
	global_load_lds_dwordx4 v2, s[100:101]
	s_add_i32 m0, s33, 0x2000
	s_add_u32 s46, s46, 0x80080
	s_addc_u32 s47, s47, 0
	s_add_i32 s33, s43, s10
	s_add_u32 s100, s46, 0xfff80000
	s_addc_u32 s101, s47, -1
	global_load_lds_dwordx4 v0, s[100:101]
	s_mov_b32 m0, s33
	s_nop 0
	global_load_lds_dwordx4 v2, s[46:47]
	s_add_i32 m0, s33, 0x2000
	s_nop 0
	global_load_lds_dwordx4 v0, s[46:47]
	s_mov_b32 m0, s16
	s_nop 0
	s_add_u32 s100, s48, 0xfff80080
	s_addc_u32 s101, s49, -1
	global_load_lds_dwordx4 v134, s[100:101]
	s_mov_b32 m0, s17
	s_nop 0
	s_add_u32 s100, s48, 0xfff80080
	s_addc_u32 s101, s49, -1
	global_load_lds_dwordx4 v132, s[100:101]
	s_add_i32 s35, s35, 2
	s_add_u32 s31, s31, 0x100
	s_addc_u32 s34, s34, 0
	s_add_u32 s44, s44, 0x100
	s_addc_u32 s45, s45, 0
	s_add_u32 s33, s44, 0xfff80080
	s_addc_u32 s43, s45, -1
	s_cmp_eq_u32 s35, 28
	s_cselect_b32 s49, s27, s43
	s_cselect_b32 s48, s28, s33
	s_cselect_b32 s47, s25, s34
	s_cselect_b32 s46, s29, s31
	s_cmp_gt_u32 s35, 29
	s_waitcnt vmcnt(8) lgkmcnt(0)
	s_barrier
	s_setprio 1
	v_mfma_f32_16x16x32_bf16 v[64:67], v[154:157], v[196:199], v[64:67]
	v_mfma_f32_16x16x32_bf16 v[60:63], v[172:175], v[196:199], v[60:63]
	v_mfma_f32_16x16x32_bf16 v[52:55], v[154:157], v[204:207], v[52:55]
	v_mfma_f32_16x16x32_bf16 v[44:47], v[172:175], v[204:207], v[44:47]
	v_mfma_f32_16x16x32_bf16 v[36:39], v[154:157], v[212:215], v[36:39]
	v_mfma_f32_16x16x32_bf16 v[28:31], v[172:175], v[212:215], v[28:31]
	v_mfma_f32_16x16x32_bf16 v[20:23], v[154:157], v[220:223], v[20:23]
	v_mfma_f32_16x16x32_bf16 v[12:15], v[172:175], v[220:223], v[12:15]
	v_mfma_f32_16x16x32_bf16 v[64:67], v[168:171], v[200:203], v[64:67]
	v_mfma_f32_16x16x32_bf16 v[60:63], v[176:179], v[200:203], v[60:63]
	v_mfma_f32_16x16x32_bf16 v[52:55], v[168:171], v[208:211], v[52:55]
	v_mfma_f32_16x16x32_bf16 v[44:47], v[176:179], v[208:211], v[44:47]
	v_mfma_f32_16x16x32_bf16 v[36:39], v[168:171], v[216:219], v[36:39]
	v_mfma_f32_16x16x32_bf16 v[28:31], v[176:179], v[216:219], v[28:31]
	v_mfma_f32_16x16x32_bf16 v[20:23], v[168:171], v[224:227], v[20:23]
	v_mfma_f32_16x16x32_bf16 v[12:15], v[176:179], v[224:227], v[12:15]
	v_mfma_f32_16x16x32_bf16 v[56:59], v[180:183], v[196:199], v[56:59]
	v_mfma_f32_16x16x32_bf16 v[48:51], v[188:191], v[196:199], v[48:51]
	v_mfma_f32_16x16x32_bf16 v[40:43], v[180:183], v[204:207], v[40:43]
	v_mfma_f32_16x16x32_bf16 v[32:35], v[188:191], v[204:207], v[32:35]
	v_mfma_f32_16x16x32_bf16 v[24:27], v[180:183], v[212:215], v[24:27]
	v_mfma_f32_16x16x32_bf16 v[16:19], v[188:191], v[212:215], v[16:19]
	v_mfma_f32_16x16x32_bf16 v[8:11], v[180:183], v[220:223], v[8:11]
	v_mfma_f32_16x16x32_bf16 v[4:7], v[188:191], v[220:223], v[4:7]
	v_mfma_f32_16x16x32_bf16 v[56:59], v[184:187], v[200:203], v[56:59]
	v_mfma_f32_16x16x32_bf16 v[48:51], v[192:195], v[200:203], v[48:51]
	v_mfma_f32_16x16x32_bf16 v[40:43], v[184:187], v[208:211], v[40:43]
	v_mfma_f32_16x16x32_bf16 v[32:35], v[192:195], v[208:211], v[32:35]
	v_mfma_f32_16x16x32_bf16 v[24:27], v[184:187], v[216:219], v[24:27]
	v_mfma_f32_16x16x32_bf16 v[16:19], v[192:195], v[216:219], v[16:19]
	v_mfma_f32_16x16x32_bf16 v[8:11], v[184:187], v[224:227], v[8:11]
	v_mfma_f32_16x16x32_bf16 v[4:7], v[192:195], v[224:227], v[4:7]
	s_barrier
	s_setprio 0
	s_cbranch_scc0 .LBB0_342
	s_and_b64 vcc, exec, s[22:23]
	s_cbranch_vccz .LBB0_345
	s_nop 0

.LBB0_740:
	s_mov_b32 s48, s6
	s_ashr_i32 s49, s6, 31
	s_mov_b32 s94, s7
	s_lshl_b64 s[6:7], s[48:49], 20
	s_add_u32 s56, s70, s6
	s_addc_u32 s57, s71, s7
	s_and_b64 s[6:7], exec, s[52:53]
	s_mov_b32 s50, s5
	s_cselect_b32 s5, s57, s39
	s_cselect_b32 s6, s56, s38
	s_add_u32 s60, s80, s60
	s_addc_u32 s61, s81, s61
	s_mov_b32 s67, s8
	s_and_b64 s[8:9], exec, s[52:53]
	s_cselect_b32 s7, s61, s37
	s_cselect_b32 s8, s60, s36
	s_add_u32 s9, s36, 0x100
	s_addc_u32 s10, s37, 0
	s_add_u32 s36, s38, 0x80080
	s_addc_u32 s37, s39, 0
	s_mov_b32 s11, -2
	s_waitcnt lgkmcnt(0)
	s_add_u32 s12, s36, 0xfff80080
	s_addc_u32 s13, s37, -1
	s_add_i32 s14, 0, 0x10000
	s_cmp_eq_u32 s11, 28
	s_cselect_b32 s63, s5, s13
	s_cselect_b32 s62, s6, s12
	s_cselect_b32 s39, s7, s10
	s_cselect_b32 s38, s8, s9
	s_add_i32 s15, 0, 0x14000
	v_add_u32_e32 v144, s14, v230
	v_add_u32_e32 v160, s15, v230
	ds_read_b128 v[124:127], v144
	ds_read_b128 v[128:131], v144 offset:1024
	ds_read_b128 v[136:139], v144 offset:2048
	ds_read_b128 v[144:147], v144 offset:3072
	ds_read_b128 v[148:151], v160
	ds_read_b128 v[152:155], v160 offset:1024
	ds_read_b128 v[156:159], v160 offset:2048
	ds_read_b128 v[160:163], v160 offset:3072
	v_lshl_add_u64 v[196:197], s[36:37], 0, v[222:223]
	s_add_i32 m0, s21, 0xc000
	ds_read_b128 v[164:167], v243
	ds_read_b128 v[168:171], v243 offset:1024
	ds_read_b128 v[172:175], v243 offset:2048
	ds_read_b128 v[176:179], v243 offset:3072
	ds_read_b128 v[180:183], v243 offset:4096
	ds_read_b128 v[184:187], v243 offset:5120
	ds_read_b128 v[188:191], v243 offset:6144
	ds_read_b128 v[192:195], v243 offset:7168
	global_load_lds_dwordx4 v[196:197], off
	v_lshl_add_u64 v[196:197], s[36:37], 0, v[220:221]
	s_add_i32 m0, s21, 0xe000
	s_nop 0
	global_load_lds_dwordx4 v[196:197], off
	s_waitcnt vmcnt(8) lgkmcnt(0)
	s_barrier
	s_setprio 1
	v_mfma_f32_16x16x32_bf16 v[140:143], v[124:127], v[164:167], 0
	v_mfma_f32_16x16x32_bf16 v[132:135], v[136:139], v[164:167], 0
	v_mfma_f32_16x16x32_bf16 v[112:115], v[124:127], v[172:175], 0
	v_mfma_f32_16x16x32_bf16 v[108:111], v[136:139], v[172:175], 0
	v_mfma_f32_16x16x32_bf16 v[96:99], v[124:127], v[180:183], 0
	v_mfma_f32_16x16x32_bf16 v[92:95], v[136:139], v[180:183], 0
	v_mfma_f32_16x16x32_bf16 v[80:83], v[124:127], v[188:191], 0
	v_mfma_f32_16x16x32_bf16 v[76:79], v[136:139], v[188:191], 0
	v_mfma_f32_16x16x32_bf16 v[140:143], v[128:131], v[168:171], v[140:143]
	v_mfma_f32_16x16x32_bf16 v[132:135], v[144:147], v[168:171], v[132:135]
	v_mfma_f32_16x16x32_bf16 v[112:115], v[128:131], v[176:179], v[112:115]
	v_mfma_f32_16x16x32_bf16 v[108:111], v[144:147], v[176:179], v[108:111]
	v_mfma_f32_16x16x32_bf16 v[96:99], v[128:131], v[184:187], v[96:99]
	v_mfma_f32_16x16x32_bf16 v[92:95], v[144:147], v[184:187], v[92:95]
	v_mfma_f32_16x16x32_bf16 v[80:83], v[128:131], v[192:195], v[80:83]
	v_mfma_f32_16x16x32_bf16 v[76:79], v[144:147], v[192:195], v[76:79]
	s_setprio 0
	s_setprio 1
	v_mfma_f32_16x16x32_bf16 v[120:123], v[148:151], v[164:167], 0
	v_mfma_f32_16x16x32_bf16 v[116:119], v[156:159], v[164:167], 0
	v_mfma_f32_16x16x32_bf16 v[104:107], v[148:151], v[172:175], 0
	v_mfma_f32_16x16x32_bf16 v[100:103], v[156:159], v[172:175], 0
	v_mfma_f32_16x16x32_bf16 v[88:91], v[148:151], v[180:183], 0
	v_mfma_f32_16x16x32_bf16 v[84:87], v[156:159], v[180:183], 0
	v_mfma_f32_16x16x32_bf16 v[72:75], v[148:151], v[188:191], 0
	v_mfma_f32_16x16x32_bf16 v[68:71], v[156:159], v[188:191], 0
	v_mfma_f32_16x16x32_bf16 v[120:123], v[152:155], v[168:171], v[120:123]
	v_mfma_f32_16x16x32_bf16 v[116:119], v[160:163], v[168:171], v[116:119]
	v_mfma_f32_16x16x32_bf16 v[104:107], v[152:155], v[176:179], v[104:107]
	v_mfma_f32_16x16x32_bf16 v[100:103], v[160:163], v[176:179], v[100:103]
	v_mfma_f32_16x16x32_bf16 v[88:91], v[152:155], v[184:187], v[88:91]
	v_mfma_f32_16x16x32_bf16 v[84:87], v[160:163], v[184:187], v[84:87]
	v_mfma_f32_16x16x32_bf16 v[72:75], v[152:155], v[192:195], v[72:75]
	v_mfma_f32_16x16x32_bf16 v[68:71], v[160:163], v[192:195], v[68:71]
	s_barrier
	s_setprio 0
	s_add_i32 s12, s14, s82
	v_lshl_add_u64 v[196:197], s[38:39], 0, v[2:3]
	s_mov_b32 m0, s12
	ds_read_b128 v[164:167], v243 offset:16384
	ds_read_b128 v[168:171], v243 offset:17408
	ds_read_b128 v[172:175], v243 offset:18432
	ds_read_b128 v[176:179], v243 offset:19456
	ds_read_b128 v[180:183], v243 offset:20480
	ds_read_b128 v[184:187], v243 offset:21504
	ds_read_b128 v[188:191], v243 offset:22528
	ds_read_b128 v[192:195], v243 offset:23552
	global_load_lds_dwordx4 v[196:197], off
	s_add_i32 m0, s12, 0x2000
	s_add_u32 s12, s38, 0x80000
	v_lshl_add_u64 v[198:199], s[38:39], 0, v[218:219]
	s_addc_u32 s13, s39, 0
	s_add_i32 s14, s15, s82
	global_load_lds_dwordx4 v[198:199], off
	v_lshl_add_u64 v[200:201], s[12:13], 0, v[2:3]
	s_mov_b32 m0, s14
	v_lshl_add_u64 v[202:203], s[62:63], 0, v[216:217]
	global_load_lds_dwordx4 v[200:201], off
	v_lshl_add_u64 v[200:201], s[12:13], 0, v[218:219]
	s_add_i32 m0, s14, 0x2000
	s_nop 0
	global_load_lds_dwordx4 v[200:201], off
	v_lshl_add_u64 v[200:201], s[62:63], 0, v[0:1]
	s_mov_b32 m0, s21
	s_nop 0
	global_load_lds_dwordx4 v[200:201], off
	s_mov_b32 m0, s83
	s_nop 0
	global_load_lds_dwordx4 v[202:203], off
	s_waitcnt vmcnt(8) lgkmcnt(0)
	s_barrier
	s_setprio 1
	v_mfma_f32_16x16x32_bf16 v[64:67], v[124:127], v[164:167], 0
	v_mfma_f32_16x16x32_bf16 v[60:63], v[136:139], v[164:167], 0
	v_mfma_f32_16x16x32_bf16 v[48:51], v[124:127], v[172:175], 0
	v_mfma_f32_16x16x32_bf16 v[44:47], v[136:139], v[172:175], 0
	v_mfma_f32_16x16x32_bf16 v[32:35], v[124:127], v[180:183], 0
	v_mfma_f32_16x16x32_bf16 v[28:31], v[136:139], v[180:183], 0
	v_mfma_f32_16x16x32_bf16 v[16:19], v[124:127], v[188:191], 0
	v_mfma_f32_16x16x32_bf16 v[12:15], v[136:139], v[188:191], 0
	v_mfma_f32_16x16x32_bf16 v[64:67], v[128:131], v[168:171], v[64:67]
	v_mfma_f32_16x16x32_bf16 v[60:63], v[144:147], v[168:171], v[60:63]
	v_mfma_f32_16x16x32_bf16 v[48:51], v[128:131], v[176:179], v[48:51]
	v_mfma_f32_16x16x32_bf16 v[44:47], v[144:147], v[176:179], v[44:47]
	v_mfma_f32_16x16x32_bf16 v[32:35], v[128:131], v[184:187], v[32:35]
	v_mfma_f32_16x16x32_bf16 v[28:31], v[144:147], v[184:187], v[28:31]
	v_mfma_f32_16x16x32_bf16 v[16:19], v[128:131], v[192:195], v[16:19]
	v_mfma_f32_16x16x32_bf16 v[12:15], v[144:147], v[192:195], v[12:15]
	s_setprio 0
	s_setprio 1
	v_mfma_f32_16x16x32_bf16 v[56:59], v[148:151], v[164:167], 0
	v_mfma_f32_16x16x32_bf16 v[52:55], v[156:159], v[164:167], 0
	v_mfma_f32_16x16x32_bf16 v[40:43], v[148:151], v[172:175], 0
	v_mfma_f32_16x16x32_bf16 v[36:39], v[156:159], v[172:175], 0
	v_mfma_f32_16x16x32_bf16 v[24:27], v[148:151], v[180:183], 0
	v_mfma_f32_16x16x32_bf16 v[20:23], v[156:159], v[180:183], 0
	v_mfma_f32_16x16x32_bf16 v[8:11], v[148:151], v[188:191], 0
	v_mfma_f32_16x16x32_bf16 v[4:7], v[156:159], v[188:191], 0
	v_mfma_f32_16x16x32_bf16 v[56:59], v[152:155], v[168:171], v[56:59]
	v_mfma_f32_16x16x32_bf16 v[52:55], v[160:163], v[168:171], v[52:55]
	v_mfma_f32_16x16x32_bf16 v[40:43], v[152:155], v[176:179], v[40:43]
	v_mfma_f32_16x16x32_bf16 v[36:39], v[160:163], v[176:179], v[36:39]
	v_mfma_f32_16x16x32_bf16 v[24:27], v[152:155], v[184:187], v[24:27]
	v_mfma_f32_16x16x32_bf16 v[20:23], v[160:163], v[184:187], v[20:23]
	v_mfma_f32_16x16x32_bf16 v[8:11], v[152:155], v[192:195], v[8:11]
	v_mfma_f32_16x16x32_bf16 v[4:7], v[160:163], v[192:195], v[4:7]
	s_barrier
	s_setprio 0
	s_add_i32 s14, 0, 0x18000
	s_add_i32 s15, 0, 0x1c000
	v_add_u32_e32 v144, s14, v230
	v_add_u32_e32 v160, s15, v230
	ds_read_b128 v[124:127], v144
	ds_read_b128 v[128:131], v144 offset:1024
	ds_read_b128 v[136:139], v144 offset:2048
	ds_read_b128 v[144:147], v144 offset:3072
	ds_read_b128 v[148:151], v160
	ds_read_b128 v[152:155], v160 offset:1024
	ds_read_b128 v[156:159], v160 offset:2048
	ds_read_b128 v[160:163], v160 offset:3072
	s_add_u32 s12, s62, 0x80000
	s_addc_u32 s13, s63, 0
	s_mov_b32 m0, s84
	v_lshl_add_u64 v[204:205], s[12:13], 0, v[0:1]
	ds_read_b128 v[164:167], v243 offset:32768
	ds_read_b128 v[168:171], v243 offset:33792
	ds_read_b128 v[172:175], v243 offset:34816
	ds_read_b128 v[176:179], v243 offset:35840
	ds_read_b128 v[180:183], v243 offset:36864
	ds_read_b128 v[184:187], v243 offset:37888
	ds_read_b128 v[188:191], v243 offset:38912
	ds_read_b128 v[192:195], v243 offset:39936
	global_load_lds_dwordx4 v[204:205], off
	v_lshl_add_u64 v[204:205], s[12:13], 0, v[216:217]
	s_mov_b32 m0, s85
	s_nop 0
	global_load_lds_dwordx4 v[204:205], off
	s_waitcnt vmcnt(8) lgkmcnt(0)
	s_barrier
	s_setprio 1
	v_mfma_f32_16x16x32_bf16 v[140:143], v[124:127], v[164:167], v[140:143]
	v_mfma_f32_16x16x32_bf16 v[132:135], v[136:139], v[164:167], v[132:135]
	v_mfma_f32_16x16x32_bf16 v[112:115], v[124:127], v[172:175], v[112:115]
	v_mfma_f32_16x16x32_bf16 v[108:111], v[136:139], v[172:175], v[108:111]
	v_mfma_f32_16x16x32_bf16 v[96:99], v[124:127], v[180:183], v[96:99]
	v_mfma_f32_16x16x32_bf16 v[92:95], v[136:139], v[180:183], v[92:95]
	v_mfma_f32_16x16x32_bf16 v[80:83], v[124:127], v[188:191], v[80:83]
	v_mfma_f32_16x16x32_bf16 v[76:79], v[136:139], v[188:191], v[76:79]
	v_mfma_f32_16x16x32_bf16 v[140:143], v[128:131], v[168:171], v[140:143]
	v_mfma_f32_16x16x32_bf16 v[132:135], v[144:147], v[168:171], v[132:135]
	v_mfma_f32_16x16x32_bf16 v[112:115], v[128:131], v[176:179], v[112:115]
	v_mfma_f32_16x16x32_bf16 v[108:111], v[144:147], v[176:179], v[108:111]
	v_mfma_f32_16x16x32_bf16 v[96:99], v[128:131], v[184:187], v[96:99]
	v_mfma_f32_16x16x32_bf16 v[92:95], v[144:147], v[184:187], v[92:95]
	v_mfma_f32_16x16x32_bf16 v[80:83], v[128:131], v[192:195], v[80:83]
	v_mfma_f32_16x16x32_bf16 v[76:79], v[144:147], v[192:195], v[76:79]
	s_setprio 0
	s_setprio 1
	v_mfma_f32_16x16x32_bf16 v[120:123], v[148:151], v[164:167], v[120:123]
	v_mfma_f32_16x16x32_bf16 v[116:119], v[156:159], v[164:167], v[116:119]
	v_mfma_f32_16x16x32_bf16 v[104:107], v[148:151], v[172:175], v[104:107]
	v_mfma_f32_16x16x32_bf16 v[100:103], v[156:159], v[172:175], v[100:103]
	v_mfma_f32_16x16x32_bf16 v[88:91], v[148:151], v[180:183], v[88:91]
	v_mfma_f32_16x16x32_bf16 v[84:87], v[156:159], v[180:183], v[84:87]
	v_mfma_f32_16x16x32_bf16 v[72:75], v[148:151], v[188:191], v[72:75]
	v_mfma_f32_16x16x32_bf16 v[68:71], v[156:159], v[188:191], v[68:71]
	v_mfma_f32_16x16x32_bf16 v[120:123], v[152:155], v[168:171], v[120:123]
	v_mfma_f32_16x16x32_bf16 v[116:119], v[160:163], v[168:171], v[116:119]
	v_mfma_f32_16x16x32_bf16 v[104:107], v[152:155], v[176:179], v[104:107]
	v_mfma_f32_16x16x32_bf16 v[100:103], v[160:163], v[176:179], v[100:103]
	v_mfma_f32_16x16x32_bf16 v[88:91], v[152:155], v[184:187], v[88:91]
	v_mfma_f32_16x16x32_bf16 v[84:87], v[160:163], v[184:187], v[84:87]
	v_mfma_f32_16x16x32_bf16 v[72:75], v[152:155], v[192:195], v[72:75]
	v_mfma_f32_16x16x32_bf16 v[68:71], v[160:163], v[192:195], v[68:71]
	s_barrier
	s_setprio 0
	s_add_i32 s12, s14, s82
	v_lshl_add_u64 v[196:197], v[196:197], 0, s[68:69]
	s_mov_b32 m0, s12
	ds_read_b128 v[164:167], v243 offset:49152
	ds_read_b128 v[168:171], v243 offset:50176
	ds_read_b128 v[172:175], v243 offset:51200
	ds_read_b128 v[176:179], v243 offset:52224
	ds_read_b128 v[180:183], v243 offset:53248
	ds_read_b128 v[184:187], v243 offset:54272
	ds_read_b128 v[188:191], v243 offset:55296
	ds_read_b128 v[192:195], v243 offset:56320
	global_load_lds_dwordx4 v[196:197], off
	s_add_i32 m0, s12, 0x2000
	s_add_u32 s12, s38, 0x80080
	v_lshl_add_u64 v[196:197], v[198:199], 0, s[68:69]
	s_addc_u32 s13, s39, 0
	s_add_i32 s14, s15, s82
	global_load_lds_dwordx4 v[196:197], off
	v_lshl_add_u64 v[196:197], s[12:13], 0, v[2:3]
	s_mov_b32 m0, s14
	s_nop 0
	global_load_lds_dwordx4 v[196:197], off
	v_lshl_add_u64 v[196:197], s[12:13], 0, v[218:219]
	s_add_i32 m0, s14, 0x2000
	s_nop 0
	global_load_lds_dwordx4 v[196:197], off
	v_lshl_add_u64 v[196:197], v[200:201], 0, s[68:69]
	s_mov_b32 m0, s89
	s_nop 0
	global_load_lds_dwordx4 v[196:197], off
	v_lshl_add_u64 v[196:197], v[202:203], 0, s[68:69]
	s_mov_b32 m0, s90
	s_nop 0
	global_load_lds_dwordx4 v[196:197], off
	s_waitcnt vmcnt(8) lgkmcnt(0)
	s_barrier
	s_setprio 1
	v_mfma_f32_16x16x32_bf16 v[64:67], v[124:127], v[164:167], v[64:67]
	v_mfma_f32_16x16x32_bf16 v[60:63], v[136:139], v[164:167], v[60:63]
	v_mfma_f32_16x16x32_bf16 v[48:51], v[124:127], v[172:175], v[48:51]
	v_mfma_f32_16x16x32_bf16 v[44:47], v[136:139], v[172:175], v[44:47]
	v_mfma_f32_16x16x32_bf16 v[32:35], v[124:127], v[180:183], v[32:35]
	v_mfma_f32_16x16x32_bf16 v[28:31], v[136:139], v[180:183], v[28:31]
	v_mfma_f32_16x16x32_bf16 v[16:19], v[124:127], v[188:191], v[16:19]
	v_mfma_f32_16x16x32_bf16 v[12:15], v[136:139], v[188:191], v[12:15]
	v_mfma_f32_16x16x32_bf16 v[64:67], v[128:131], v[168:171], v[64:67]
	v_mfma_f32_16x16x32_bf16 v[60:63], v[144:147], v[168:171], v[60:63]
	v_mfma_f32_16x16x32_bf16 v[48:51], v[128:131], v[176:179], v[48:51]
	v_mfma_f32_16x16x32_bf16 v[44:47], v[144:147], v[176:179], v[44:47]
	v_mfma_f32_16x16x32_bf16 v[32:35], v[128:131], v[184:187], v[32:35]
	v_mfma_f32_16x16x32_bf16 v[28:31], v[144:147], v[184:187], v[28:31]
	v_mfma_f32_16x16x32_bf16 v[16:19], v[128:131], v[192:195], v[16:19]
	v_mfma_f32_16x16x32_bf16 v[12:15], v[144:147], v[192:195], v[12:15]
	s_setprio 0
	s_setprio 1
	v_mfma_f32_16x16x32_bf16 v[56:59], v[148:151], v[164:167], v[56:59]
	v_mfma_f32_16x16x32_bf16 v[52:55], v[156:159], v[164:167], v[52:55]
	v_mfma_f32_16x16x32_bf16 v[40:43], v[148:151], v[172:175], v[40:43]
	v_mfma_f32_16x16x32_bf16 v[36:39], v[156:159], v[172:175], v[36:39]
	v_mfma_f32_16x16x32_bf16 v[24:27], v[148:151], v[180:183], v[24:27]
	v_mfma_f32_16x16x32_bf16 v[20:23], v[156:159], v[180:183], v[20:23]
	v_mfma_f32_16x16x32_bf16 v[8:11], v[148:151], v[188:191], v[8:11]
	v_mfma_f32_16x16x32_bf16 v[4:7], v[156:159], v[188:191], v[4:7]
	v_mfma_f32_16x16x32_bf16 v[56:59], v[152:155], v[168:171], v[56:59]
	v_mfma_f32_16x16x32_bf16 v[52:55], v[160:163], v[168:171], v[52:55]
	v_mfma_f32_16x16x32_bf16 v[40:43], v[152:155], v[176:179], v[40:43]
	v_mfma_f32_16x16x32_bf16 v[36:39], v[160:163], v[176:179], v[36:39]
	v_mfma_f32_16x16x32_bf16 v[24:27], v[152:155], v[184:187], v[24:27]
	v_mfma_f32_16x16x32_bf16 v[20:23], v[160:163], v[184:187], v[20:23]
	v_mfma_f32_16x16x32_bf16 v[8:11], v[152:155], v[192:195], v[8:11]
	v_mfma_f32_16x16x32_bf16 v[4:7], v[160:163], v[192:195], v[4:7]
	s_barrier
	s_setprio 0
	s_add_i32 s11, s11, 2
	s_add_u32 s9, s9, 0x100
	s_addc_u32 s10, s10, 0
	s_add_u32 s36, s36, 0x100
	s_addc_u32 s37, s37, 0
	s_cmp_gt_u32 s11, 29
.LBB0_741:
	s_add_u32 s12, s36, 0xfff80080
	s_addc_u32 s13, s37, -1
	s_add_i32 s14, 0, 0x10000
	s_cmp_eq_u32 s11, 28
	s_cselect_b32 s63, s5, s13
	s_cselect_b32 s62, s6, s12
	s_cselect_b32 s39, s7, s10
	s_cselect_b32 s38, s8, s9
	s_add_i32 s15, 0, 0x14000
	v_add_u32_e32 v144, s14, v230
	v_add_u32_e32 v160, s15, v230
	ds_read_b128 v[124:127], v144
	ds_read_b128 v[128:131], v144 offset:1024
	ds_read_b128 v[136:139], v144 offset:2048
	ds_read_b128 v[144:147], v144 offset:3072
	ds_read_b128 v[148:151], v160
	ds_read_b128 v[152:155], v160 offset:1024
	ds_read_b128 v[156:159], v160 offset:2048
	ds_read_b128 v[160:163], v160 offset:3072
	v_lshl_add_u64 v[196:197], s[36:37], 0, v[222:223]
	s_add_i32 m0, s21, 0xc000
	ds_read_b128 v[164:167], v243
	ds_read_b128 v[168:171], v243 offset:1024
	ds_read_b128 v[172:175], v243 offset:2048
	ds_read_b128 v[176:179], v243 offset:3072
	ds_read_b128 v[180:183], v243 offset:4096
	ds_read_b128 v[184:187], v243 offset:5120
	ds_read_b128 v[188:191], v243 offset:6144
	ds_read_b128 v[192:195], v243 offset:7168
	global_load_lds_dwordx4 v[196:197], off
	v_lshl_add_u64 v[196:197], s[36:37], 0, v[220:221]
	s_add_i32 m0, s21, 0xe000
	s_nop 0
	global_load_lds_dwordx4 v[196:197], off
	s_waitcnt vmcnt(8) lgkmcnt(0)
	s_barrier
	s_setprio 1
	v_mfma_f32_16x16x32_bf16 v[140:143], v[124:127], v[164:167], v[140:143]
	v_mfma_f32_16x16x32_bf16 v[132:135], v[136:139], v[164:167], v[132:135]
	v_mfma_f32_16x16x32_bf16 v[112:115], v[124:127], v[172:175], v[112:115]
	v_mfma_f32_16x16x32_bf16 v[108:111], v[136:139], v[172:175], v[108:111]
	v_mfma_f32_16x16x32_bf16 v[96:99], v[124:127], v[180:183], v[96:99]
	v_mfma_f32_16x16x32_bf16 v[92:95], v[136:139], v[180:183], v[92:95]
	v_mfma_f32_16x16x32_bf16 v[80:83], v[124:127], v[188:191], v[80:83]
	v_mfma_f32_16x16x32_bf16 v[76:79], v[136:139], v[188:191], v[76:79]
	v_mfma_f32_16x16x32_bf16 v[140:143], v[128:131], v[168:171], v[140:143]
	v_mfma_f32_16x16x32_bf16 v[132:135], v[144:147], v[168:171], v[132:135]
	v_mfma_f32_16x16x32_bf16 v[112:115], v[128:131], v[176:179], v[112:115]
	v_mfma_f32_16x16x32_bf16 v[108:111], v[144:147], v[176:179], v[108:111]
	v_mfma_f32_16x16x32_bf16 v[96:99], v[128:131], v[184:187], v[96:99]
	v_mfma_f32_16x16x32_bf16 v[92:95], v[144:147], v[184:187], v[92:95]
	v_mfma_f32_16x16x32_bf16 v[80:83], v[128:131], v[192:195], v[80:83]
	v_mfma_f32_16x16x32_bf16 v[76:79], v[144:147], v[192:195], v[76:79]
	s_setprio 0
	s_setprio 1
	v_mfma_f32_16x16x32_bf16 v[120:123], v[148:151], v[164:167], v[120:123]
	v_mfma_f32_16x16x32_bf16 v[116:119], v[156:159], v[164:167], v[116:119]
	v_mfma_f32_16x16x32_bf16 v[104:107], v[148:151], v[172:175], v[104:107]
	v_mfma_f32_16x16x32_bf16 v[100:103], v[156:159], v[172:175], v[100:103]
	v_mfma_f32_16x16x32_bf16 v[88:91], v[148:151], v[180:183], v[88:91]
	v_mfma_f32_16x16x32_bf16 v[84:87], v[156:159], v[180:183], v[84:87]
	v_mfma_f32_16x16x32_bf16 v[72:75], v[148:151], v[188:191], v[72:75]
	v_mfma_f32_16x16x32_bf16 v[68:71], v[156:159], v[188:191], v[68:71]
	v_mfma_f32_16x16x32_bf16 v[120:123], v[152:155], v[168:171], v[120:123]
	v_mfma_f32_16x16x32_bf16 v[116:119], v[160:163], v[168:171], v[116:119]
	v_mfma_f32_16x16x32_bf16 v[104:107], v[152:155], v[176:179], v[104:107]
	v_mfma_f32_16x16x32_bf16 v[100:103], v[160:163], v[176:179], v[100:103]
	v_mfma_f32_16x16x32_bf16 v[88:91], v[152:155], v[184:187], v[88:91]
	v_mfma_f32_16x16x32_bf16 v[84:87], v[160:163], v[184:187], v[84:87]
	v_mfma_f32_16x16x32_bf16 v[72:75], v[152:155], v[192:195], v[72:75]
	v_mfma_f32_16x16x32_bf16 v[68:71], v[160:163], v[192:195], v[68:71]
	s_barrier
	s_setprio 0
	s_add_i32 s12, s14, s82
	v_lshl_add_u64 v[196:197], s[38:39], 0, v[2:3]
	s_mov_b32 m0, s12
	ds_read_b128 v[164:167], v243 offset:16384
	ds_read_b128 v[168:171], v243 offset:17408
	ds_read_b128 v[172:175], v243 offset:18432
	ds_read_b128 v[176:179], v243 offset:19456
	ds_read_b128 v[180:183], v243 offset:20480
	ds_read_b128 v[184:187], v243 offset:21504
	ds_read_b128 v[188:191], v243 offset:22528
	ds_read_b128 v[192:195], v243 offset:23552
	global_load_lds_dwordx4 v[196:197], off
	s_add_i32 m0, s12, 0x2000
	s_add_u32 s12, s38, 0x80000
	v_lshl_add_u64 v[198:199], s[38:39], 0, v[218:219]
	s_addc_u32 s13, s39, 0
	s_add_i32 s14, s15, s82
	global_load_lds_dwordx4 v[198:199], off
	v_lshl_add_u64 v[200:201], s[12:13], 0, v[2:3]
	s_mov_b32 m0, s14
	v_lshl_add_u64 v[202:203], s[62:63], 0, v[216:217]
	global_load_lds_dwordx4 v[200:201], off
	v_lshl_add_u64 v[200:201], s[12:13], 0, v[218:219]
	s_add_i32 m0, s14, 0x2000
	s_nop 0
	global_load_lds_dwordx4 v[200:201], off
	v_lshl_add_u64 v[200:201], s[62:63], 0, v[0:1]
	s_mov_b32 m0, s21
	s_nop 0
	global_load_lds_dwordx4 v[200:201], off
	s_mov_b32 m0, s83
	s_nop 0
	global_load_lds_dwordx4 v[202:203], off
	s_waitcnt vmcnt(8) lgkmcnt(0)
	s_barrier
	s_setprio 1
	v_mfma_f32_16x16x32_bf16 v[64:67], v[124:127], v[164:167], v[64:67]
	v_mfma_f32_16x16x32_bf16 v[60:63], v[136:139], v[164:167], v[60:63]
	v_mfma_f32_16x16x32_bf16 v[48:51], v[124:127], v[172:175], v[48:51]
	v_mfma_f32_16x16x32_bf16 v[44:47], v[136:139], v[172:175], v[44:47]
	v_mfma_f32_16x16x32_bf16 v[32:35], v[124:127], v[180:183], v[32:35]
	v_mfma_f32_16x16x32_bf16 v[28:31], v[136:139], v[180:183], v[28:31]
	v_mfma_f32_16x16x32_bf16 v[16:19], v[124:127], v[188:191], v[16:19]
	v_mfma_f32_16x16x32_bf16 v[12:15], v[136:139], v[188:191], v[12:15]
	v_mfma_f32_16x16x32_bf16 v[64:67], v[128:131], v[168:171], v[64:67]
	v_mfma_f32_16x16x32_bf16 v[60:63], v[144:147], v[168:171], v[60:63]
	v_mfma_f32_16x16x32_bf16 v[48:51], v[128:131], v[176:179], v[48:51]
	v_mfma_f32_16x16x32_bf16 v[44:47], v[144:147], v[176:179], v[44:47]
	v_mfma_f32_16x16x32_bf16 v[32:35], v[128:131], v[184:187], v[32:35]
	v_mfma_f32_16x16x32_bf16 v[28:31], v[144:147], v[184:187], v[28:31]
	v_mfma_f32_16x16x32_bf16 v[16:19], v[128:131], v[192:195], v[16:19]
	v_mfma_f32_16x16x32_bf16 v[12:15], v[144:147], v[192:195], v[12:15]
	s_setprio 0
	s_setprio 1
	v_mfma_f32_16x16x32_bf16 v[56:59], v[148:151], v[164:167], v[56:59]
	v_mfma_f32_16x16x32_bf16 v[52:55], v[156:159], v[164:167], v[52:55]
	v_mfma_f32_16x16x32_bf16 v[40:43], v[148:151], v[172:175], v[40:43]
	v_mfma_f32_16x16x32_bf16 v[36:39], v[156:159], v[172:175], v[36:39]
	v_mfma_f32_16x16x32_bf16 v[24:27], v[148:151], v[180:183], v[24:27]
	v_mfma_f32_16x16x32_bf16 v[20:23], v[156:159], v[180:183], v[20:23]
	v_mfma_f32_16x16x32_bf16 v[8:11], v[148:151], v[188:191], v[8:11]
	v_mfma_f32_16x16x32_bf16 v[4:7], v[156:159], v[188:191], v[4:7]
	v_mfma_f32_16x16x32_bf16 v[56:59], v[152:155], v[168:171], v[56:59]
	v_mfma_f32_16x16x32_bf16 v[52:55], v[160:163], v[168:171], v[52:55]
	v_mfma_f32_16x16x32_bf16 v[40:43], v[152:155], v[176:179], v[40:43]
	v_mfma_f32_16x16x32_bf16 v[36:39], v[160:163], v[176:179], v[36:39]
	v_mfma_f32_16x16x32_bf16 v[24:27], v[152:155], v[184:187], v[24:27]
	v_mfma_f32_16x16x32_bf16 v[20:23], v[160:163], v[184:187], v[20:23]
	v_mfma_f32_16x16x32_bf16 v[8:11], v[152:155], v[192:195], v[8:11]
	v_mfma_f32_16x16x32_bf16 v[4:7], v[160:163], v[192:195], v[4:7]
	s_barrier
	s_setprio 0
	s_add_i32 s14, 0, 0x18000
	s_add_i32 s15, 0, 0x1c000
	v_add_u32_e32 v144, s14, v230
	v_add_u32_e32 v160, s15, v230
	ds_read_b128 v[124:127], v144
	ds_read_b128 v[128:131], v144 offset:1024
	ds_read_b128 v[136:139], v144 offset:2048
	ds_read_b128 v[144:147], v144 offset:3072
	ds_read_b128 v[148:151], v160
	ds_read_b128 v[152:155], v160 offset:1024
	ds_read_b128 v[156:159], v160 offset:2048
	ds_read_b128 v[160:163], v160 offset:3072
	s_add_u32 s12, s62, 0x80000
	s_addc_u32 s13, s63, 0
	s_mov_b32 m0, s84
	v_lshl_add_u64 v[204:205], s[12:13], 0, v[0:1]
	ds_read_b128 v[164:167], v243 offset:32768
	ds_read_b128 v[168:171], v243 offset:33792
	ds_read_b128 v[172:175], v243 offset:34816
	ds_read_b128 v[176:179], v243 offset:35840
	ds_read_b128 v[180:183], v243 offset:36864
	ds_read_b128 v[184:187], v243 offset:37888
	ds_read_b128 v[188:191], v243 offset:38912
	ds_read_b128 v[192:195], v243 offset:39936
	global_load_lds_dwordx4 v[204:205], off
	v_lshl_add_u64 v[204:205], s[12:13], 0, v[216:217]
	s_mov_b32 m0, s85
	s_nop 0
	global_load_lds_dwordx4 v[204:205], off
	s_waitcnt vmcnt(8) lgkmcnt(0)
	s_barrier
	s_setprio 1
	v_mfma_f32_16x16x32_bf16 v[140:143], v[124:127], v[164:167], v[140:143]
	v_mfma_f32_16x16x32_bf16 v[132:135], v[136:139], v[164:167], v[132:135]
	v_mfma_f32_16x16x32_bf16 v[112:115], v[124:127], v[172:175], v[112:115]
	v_mfma_f32_16x16x32_bf16 v[108:111], v[136:139], v[172:175], v[108:111]
	v_mfma_f32_16x16x32_bf16 v[96:99], v[124:127], v[180:183], v[96:99]
	v_mfma_f32_16x16x32_bf16 v[92:95], v[136:139], v[180:183], v[92:95]
	v_mfma_f32_16x16x32_bf16 v[80:83], v[124:127], v[188:191], v[80:83]
	v_mfma_f32_16x16x32_bf16 v[76:79], v[136:139], v[188:191], v[76:79]
	v_mfma_f32_16x16x32_bf16 v[140:143], v[128:131], v[168:171], v[140:143]
	v_mfma_f32_16x16x32_bf16 v[132:135], v[144:147], v[168:171], v[132:135]
	v_mfma_f32_16x16x32_bf16 v[112:115], v[128:131], v[176:179], v[112:115]
	v_mfma_f32_16x16x32_bf16 v[108:111], v[144:147], v[176:179], v[108:111]
	v_mfma_f32_16x16x32_bf16 v[96:99], v[128:131], v[184:187], v[96:99]
	v_mfma_f32_16x16x32_bf16 v[92:95], v[144:147], v[184:187], v[92:95]
	v_mfma_f32_16x16x32_bf16 v[80:83], v[128:131], v[192:195], v[80:83]
	v_mfma_f32_16x16x32_bf16 v[76:79], v[144:147], v[192:195], v[76:79]
	s_setprio 0
	s_setprio 1
	v_mfma_f32_16x16x32_bf16 v[120:123], v[148:151], v[164:167], v[120:123]
	v_mfma_f32_16x16x32_bf16 v[116:119], v[156:159], v[164:167], v[116:119]
	v_mfma_f32_16x16x32_bf16 v[104:107], v[148:151], v[172:175], v[104:107]
	v_mfma_f32_16x16x32_bf16 v[100:103], v[156:159], v[172:175], v[100:103]
	v_mfma_f32_16x16x32_bf16 v[88:91], v[148:151], v[180:183], v[88:91]
	v_mfma_f32_16x16x32_bf16 v[84:87], v[156:159], v[180:183], v[84:87]
	v_mfma_f32_16x16x32_bf16 v[72:75], v[148:151], v[188:191], v[72:75]
	v_mfma_f32_16x16x32_bf16 v[68:71], v[156:159], v[188:191], v[68:71]
	v_mfma_f32_16x16x32_bf16 v[120:123], v[152:155], v[168:171], v[120:123]
	v_mfma_f32_16x16x32_bf16 v[116:119], v[160:163], v[168:171], v[116:119]
	v_mfma_f32_16x16x32_bf16 v[104:107], v[152:155], v[176:179], v[104:107]
	v_mfma_f32_16x16x32_bf16 v[100:103], v[160:163], v[176:179], v[100:103]
	v_mfma_f32_16x16x32_bf16 v[88:91], v[152:155], v[184:187], v[88:91]
	v_mfma_f32_16x16x32_bf16 v[84:87], v[160:163], v[184:187], v[84:87]
	v_mfma_f32_16x16x32_bf16 v[72:75], v[152:155], v[192:195], v[72:75]
	v_mfma_f32_16x16x32_bf16 v[68:71], v[160:163], v[192:195], v[68:71]
	s_barrier
	s_setprio 0
	s_add_i32 s12, s14, s82
	v_lshl_add_u64 v[196:197], v[196:197], 0, s[68:69]
	s_mov_b32 m0, s12
	ds_read_b128 v[164:167], v243 offset:49152
	ds_read_b128 v[168:171], v243 offset:50176
	ds_read_b128 v[172:175], v243 offset:51200
	ds_read_b128 v[176:179], v243 offset:52224
	ds_read_b128 v[180:183], v243 offset:53248
	ds_read_b128 v[184:187], v243 offset:54272
	ds_read_b128 v[188:191], v243 offset:55296
	ds_read_b128 v[192:195], v243 offset:56320
	global_load_lds_dwordx4 v[196:197], off
	s_add_i32 m0, s12, 0x2000
	s_add_u32 s12, s38, 0x80080
	v_lshl_add_u64 v[196:197], v[198:199], 0, s[68:69]
	s_addc_u32 s13, s39, 0
	s_add_i32 s14, s15, s82
	global_load_lds_dwordx4 v[196:197], off
	v_lshl_add_u64 v[196:197], s[12:13], 0, v[2:3]
	s_mov_b32 m0, s14
	s_nop 0
	global_load_lds_dwordx4 v[196:197], off
	v_lshl_add_u64 v[196:197], s[12:13], 0, v[218:219]
	s_add_i32 m0, s14, 0x2000
	s_nop 0
	global_load_lds_dwordx4 v[196:197], off
	v_lshl_add_u64 v[196:197], v[200:201], 0, s[68:69]
	s_mov_b32 m0, s89
	s_nop 0
	global_load_lds_dwordx4 v[196:197], off
	v_lshl_add_u64 v[196:197], v[202:203], 0, s[68:69]
	s_mov_b32 m0, s90
	s_nop 0
	global_load_lds_dwordx4 v[196:197], off
	s_waitcnt vmcnt(8) lgkmcnt(0)
	s_barrier
	s_setprio 1
	v_mfma_f32_16x16x32_bf16 v[64:67], v[124:127], v[164:167], v[64:67]
	v_mfma_f32_16x16x32_bf16 v[60:63], v[136:139], v[164:167], v[60:63]
	v_mfma_f32_16x16x32_bf16 v[48:51], v[124:127], v[172:175], v[48:51]
	v_mfma_f32_16x16x32_bf16 v[44:47], v[136:139], v[172:175], v[44:47]
	v_mfma_f32_16x16x32_bf16 v[32:35], v[124:127], v[180:183], v[32:35]
	v_mfma_f32_16x16x32_bf16 v[28:31], v[136:139], v[180:183], v[28:31]
	v_mfma_f32_16x16x32_bf16 v[16:19], v[124:127], v[188:191], v[16:19]
	v_mfma_f32_16x16x32_bf16 v[12:15], v[136:139], v[188:191], v[12:15]
	v_mfma_f32_16x16x32_bf16 v[64:67], v[128:131], v[168:171], v[64:67]
	v_mfma_f32_16x16x32_bf16 v[60:63], v[144:147], v[168:171], v[60:63]
	v_mfma_f32_16x16x32_bf16 v[48:51], v[128:131], v[176:179], v[48:51]
	v_mfma_f32_16x16x32_bf16 v[44:47], v[144:147], v[176:179], v[44:47]
	v_mfma_f32_16x16x32_bf16 v[32:35], v[128:131], v[184:187], v[32:35]
	v_mfma_f32_16x16x32_bf16 v[28:31], v[144:147], v[184:187], v[28:31]
	v_mfma_f32_16x16x32_bf16 v[16:19], v[128:131], v[192:195], v[16:19]
	v_mfma_f32_16x16x32_bf16 v[12:15], v[144:147], v[192:195], v[12:15]
	s_setprio 0
	s_setprio 1
	v_mfma_f32_16x16x32_bf16 v[56:59], v[148:151], v[164:167], v[56:59]
	v_mfma_f32_16x16x32_bf16 v[52:55], v[156:159], v[164:167], v[52:55]
	v_mfma_f32_16x16x32_bf16 v[40:43], v[148:151], v[172:175], v[40:43]
	v_mfma_f32_16x16x32_bf16 v[36:39], v[156:159], v[172:175], v[36:39]
	v_mfma_f32_16x16x32_bf16 v[24:27], v[148:151], v[180:183], v[24:27]
	v_mfma_f32_16x16x32_bf16 v[20:23], v[156:159], v[180:183], v[20:23]
	v_mfma_f32_16x16x32_bf16 v[8:11], v[148:151], v[188:191], v[8:11]
	v_mfma_f32_16x16x32_bf16 v[4:7], v[156:159], v[188:191], v[4:7]
	v_mfma_f32_16x16x32_bf16 v[56:59], v[152:155], v[168:171], v[56:59]
	v_mfma_f32_16x16x32_bf16 v[52:55], v[160:163], v[168:171], v[52:55]
	v_mfma_f32_16x16x32_bf16 v[40:43], v[152:155], v[176:179], v[40:43]
	v_mfma_f32_16x16x32_bf16 v[36:39], v[160:163], v[176:179], v[36:39]
	v_mfma_f32_16x16x32_bf16 v[24:27], v[152:155], v[184:187], v[24:27]
	v_mfma_f32_16x16x32_bf16 v[20:23], v[160:163], v[184:187], v[20:23]
	v_mfma_f32_16x16x32_bf16 v[8:11], v[152:155], v[192:195], v[8:11]
	v_mfma_f32_16x16x32_bf16 v[4:7], v[160:163], v[192:195], v[4:7]
	s_barrier
	s_setprio 0
	s_add_i32 s11, s11, 2
	s_add_u32 s9, s9, 0x100
	s_addc_u32 s10, s10, 0
	s_add_u32 s36, s36, 0x100
	s_addc_u32 s37, s37, 0
	s_cmp_gt_u32 s11, 29
	s_cbranch_scc0 .LBB0_741
	s_and_b64 vcc, exec, s[46:47]
	s_cbranch_vccz .LBB0_744
	s_barrier

.LBB0_853:
	v_and_b32_e32 v203, 15, v16
	v_bfe_u32 v201, v16, 4, 2
	s_and_b32 s5, s5, 3
	v_lshlrev_b32_e32 v16, 4, v201
	v_lshlrev_b32_e32 v202, 2, v203
	v_lshl_or_b32 v16, v203, 6, v16
	v_and_b32_e32 v19, 32, v202
	s_lshl_b32 s14, s8, 13
	s_lshl_b32 s15, s5, 12
	s_add_i32 m0, s10, 0x18000
	v_lshl_add_u64 v[10:11], v[10:11], 0, s[68:69]
	v_bitop3_b32 v140, v16, s15, v19 bitop3:0xde
	v_bitop3_b32 v16, v16, s14, v19 bitop3:0xde
	s_nop 0
	global_load_lds_dwordx4 v[10:11], off
	v_lshl_add_u64 v[8:9], v[8:9], 0, s[68:69]
	s_add_i32 m0, s10, 0x1a000
	s_add_i32 s14, s10, 0x8000
	s_add_i32 s15, s10, 0xa000
	global_load_lds_dwordx4 v[8:9], off
	v_lshl_add_u64 v[6:7], v[6:7], 0, s[68:69]
	s_mov_b32 m0, s14
	s_add_u32 s16, s20, 0x80080
	global_load_lds_dwordx4 v[6:7], off
	v_lshl_add_u64 v[4:5], v[4:5], 0, s[68:69]
	s_mov_b32 m0, s15
	s_addc_u32 s17, s21, 0
	global_load_lds_dwordx4 v[4:5], off
	s_add_i32 m0, s10, 0x1c000
	v_lshl_add_u64 v[4:5], s[16:17], 0, v[2:3]
	global_load_lds_dwordx4 v[4:5], off
	v_lshl_add_u64 v[4:5], s[16:17], 0, v[134:135]
	s_add_i32 m0, s10, 0x1e000
	v_readlane_b32 s16, v254, 25
	global_load_lds_dwordx4 v[4:5], off
	v_readlane_b32 s17, v254, 26
	s_add_u32 s16, s16, s24
	s_addc_u32 s17, s17, s25
	s_add_u32 s16, s2, s16
	s_addc_u32 s17, s3, s17
	s_and_b32 s18, s18, 7
	s_lshl_b32 s18, s18, 23
	s_lshl_b32 s19, s19, 20
	v_lshlrev_b32_e32 v4, 15, v15
	s_or_b32 s18, s18, s19
	v_and_b32_e32 v4, 0xffff0000, v4
	s_add_u32 s18, s2, s18
	v_lshl_add_u32 v4, v17, 12, v4
	v_and_b32_e32 v5, 1, v15
	s_addc_u32 s19, s3, 0
	v_lshl_or_b32 v4, v5, 6, v4
	s_add_u32 s24, s18, 0x22180080
	v_lshl_add_u32 v4, v18, 1, v4
	v_mov_b32_e32 v5, v3
	s_addc_u32 s25, s19, 0
	v_lshl_add_u64 v[136:137], s[24:25], 0, v[4:5]
	v_lshlrev_b32_e32 v4, 15, v12
	v_and_b32_e32 v4, 0xffff0000, v4
	v_lshl_add_u32 v4, v13, 12, v4
	v_and_b32_e32 v5, 1, v12
	v_lshl_or_b32 v4, v5, 6, v4
	s_waitcnt vmcnt(8)
	s_barrier
	s_waitcnt vmcnt(6)
	v_lshl_add_u32 v4, v14, 1, v4
	v_mov_b32_e32 v5, v3
	v_lshl_add_u64 v[138:139], s[24:25], 0, v[4:5]
	v_lshl_or_b32 v200, s8, 6, v203
	s_mov_b32 s28, -2
	s_mov_b64 s[24:25], 0
	v_add_u32_e32 v141, 0, v16
	s_barrier
	s_add_u32 s26, s18, s24
	s_addc_u32 s27, s19, s25
	s_add_u32 s26, s26, 0x22100100
	s_addc_u32 s27, s27, 0
	s_add_u32 s29, s16, s24
	s_addc_u32 s30, s17, s25
	s_add_i32 s31, 0, 0x10000
	s_cmpk_eq_i32 s24, 0xf00
	s_cselect_b32 s37, s23, s27
	s_cselect_b32 s36, s22, s26
	s_cselect_b32 s27, s21, s30
	s_cselect_b32 s26, s20, s29
	s_add_i32 s29, 0, 0x14000
	v_add_u32_e32 v154, s31, v140
	v_add_u32_e32 v170, s29, v140
	ds_read_b128 v[142:145], v154
	ds_read_b128 v[146:149], v154 offset:1024
	ds_read_b128 v[150:153], v154 offset:2048
	ds_read_b128 v[154:157], v154 offset:3072
	ds_read_b128 v[158:161], v170
	ds_read_b128 v[162:165], v170 offset:1024
	ds_read_b128 v[166:169], v170 offset:2048
	ds_read_b128 v[170:173], v170 offset:3072
	v_lshl_add_u64 v[198:199], v[138:139], 0, s[24:25]
	s_add_i32 m0, s10, 0xc000
	ds_read_b128 v[174:177], v141
	ds_read_b128 v[178:181], v141 offset:1024
	ds_read_b128 v[182:185], v141 offset:2048
	ds_read_b128 v[186:189], v141 offset:3072
	ds_read_b128 v[190:193], v141 offset:4096
	ds_read_b128 v[194:197], v141 offset:5120
	ds_read_b128 v[204:207], v141 offset:6144
	ds_read_b128 v[208:211], v141 offset:7168
	global_load_lds_dwordx4 v[198:199], off
	v_lshl_add_u64 v[198:199], v[136:137], 0, s[24:25]
	s_add_i32 m0, s10, 0xe000
	s_nop 0
	global_load_lds_dwordx4 v[198:199], off
	s_waitcnt vmcnt(8) lgkmcnt(0)
	s_barrier
	s_setprio 1
	v_mfma_f32_16x16x32_bf16 v[128:131], v[142:145], v[174:177], 0
	v_mfma_f32_16x16x32_bf16 v[124:127], v[150:153], v[174:177], 0
	v_mfma_f32_16x16x32_bf16 v[112:115], v[142:145], v[182:185], 0
	v_mfma_f32_16x16x32_bf16 v[108:111], v[150:153], v[182:185], 0
	v_mfma_f32_16x16x32_bf16 v[96:99], v[142:145], v[190:193], 0
	v_mfma_f32_16x16x32_bf16 v[92:95], v[150:153], v[190:193], 0
	v_mfma_f32_16x16x32_bf16 v[80:83], v[142:145], v[204:207], 0
	v_mfma_f32_16x16x32_bf16 v[76:79], v[150:153], v[204:207], 0
	v_mfma_f32_16x16x32_bf16 v[128:131], v[146:149], v[178:181], v[128:131]
	v_mfma_f32_16x16x32_bf16 v[124:127], v[154:157], v[178:181], v[124:127]
	v_mfma_f32_16x16x32_bf16 v[112:115], v[146:149], v[186:189], v[112:115]
	v_mfma_f32_16x16x32_bf16 v[108:111], v[154:157], v[186:189], v[108:111]
	v_mfma_f32_16x16x32_bf16 v[96:99], v[146:149], v[194:197], v[96:99]
	v_mfma_f32_16x16x32_bf16 v[92:95], v[154:157], v[194:197], v[92:95]
	v_mfma_f32_16x16x32_bf16 v[80:83], v[146:149], v[208:211], v[80:83]
	v_mfma_f32_16x16x32_bf16 v[76:79], v[154:157], v[208:211], v[76:79]
	s_setprio 0
	s_setprio 1
	v_mfma_f32_16x16x32_bf16 v[120:123], v[158:161], v[174:177], 0
	v_mfma_f32_16x16x32_bf16 v[116:119], v[166:169], v[174:177], 0
	v_mfma_f32_16x16x32_bf16 v[104:107], v[158:161], v[182:185], 0
	v_mfma_f32_16x16x32_bf16 v[100:103], v[166:169], v[182:185], 0
	v_mfma_f32_16x16x32_bf16 v[88:91], v[158:161], v[190:193], 0
	v_mfma_f32_16x16x32_bf16 v[84:87], v[166:169], v[190:193], 0
	v_mfma_f32_16x16x32_bf16 v[72:75], v[158:161], v[204:207], 0
	v_mfma_f32_16x16x32_bf16 v[68:71], v[166:169], v[204:207], 0
	v_mfma_f32_16x16x32_bf16 v[120:123], v[162:165], v[178:181], v[120:123]
	v_mfma_f32_16x16x32_bf16 v[116:119], v[170:173], v[178:181], v[116:119]
	v_mfma_f32_16x16x32_bf16 v[104:107], v[162:165], v[186:189], v[104:107]
	v_mfma_f32_16x16x32_bf16 v[100:103], v[170:173], v[186:189], v[100:103]
	v_mfma_f32_16x16x32_bf16 v[88:91], v[162:165], v[194:197], v[88:91]
	v_mfma_f32_16x16x32_bf16 v[84:87], v[170:173], v[194:197], v[84:87]
	v_mfma_f32_16x16x32_bf16 v[72:75], v[162:165], v[208:211], v[72:75]
	v_mfma_f32_16x16x32_bf16 v[68:71], v[170:173], v[208:211], v[68:71]
	s_barrier
	s_setprio 0
	s_add_i32 s30, s31, s9
	v_lshl_add_u64 v[198:199], s[26:27], 0, v[2:3]
	s_mov_b32 m0, s30
	ds_read_b128 v[174:177], v141 offset:16384
	ds_read_b128 v[178:181], v141 offset:17408
	ds_read_b128 v[182:185], v141 offset:18432
	ds_read_b128 v[186:189], v141 offset:19456
	ds_read_b128 v[190:193], v141 offset:20480
	ds_read_b128 v[194:197], v141 offset:21504
	ds_read_b128 v[204:207], v141 offset:22528
	ds_read_b128 v[208:211], v141 offset:23552
	global_load_lds_dwordx4 v[198:199], off
	s_add_i32 m0, s30, 0x2000
	s_add_u32 s30, s26, 0x80000
	v_lshl_add_u64 v[212:213], s[26:27], 0, v[134:135]
	s_addc_u32 s31, s27, 0
	s_add_i32 s29, s29, s9
	global_load_lds_dwordx4 v[212:213], off
	v_lshl_add_u64 v[214:215], s[30:31], 0, v[2:3]
	s_mov_b32 m0, s29
	v_lshl_add_u64 v[216:217], s[36:37], 0, v[132:133]
	global_load_lds_dwordx4 v[214:215], off
	v_lshl_add_u64 v[214:215], s[30:31], 0, v[134:135]
	s_add_i32 m0, s29, 0x2000
	s_nop 0
	global_load_lds_dwordx4 v[214:215], off
	v_lshl_add_u64 v[214:215], s[36:37], 0, v[0:1]
	s_mov_b32 m0, s10
	s_nop 0
	global_load_lds_dwordx4 v[214:215], off
	s_mov_b32 m0, s11
	s_nop 0
	global_load_lds_dwordx4 v[216:217], off
	s_waitcnt vmcnt(8) lgkmcnt(0)
	s_barrier
	s_setprio 1
	v_mfma_f32_16x16x32_bf16 v[64:67], v[142:145], v[174:177], 0
	v_mfma_f32_16x16x32_bf16 v[60:63], v[150:153], v[174:177], 0
	v_mfma_f32_16x16x32_bf16 v[48:51], v[142:145], v[182:185], 0
	v_mfma_f32_16x16x32_bf16 v[44:47], v[150:153], v[182:185], 0
	v_mfma_f32_16x16x32_bf16 v[32:35], v[142:145], v[190:193], 0
	v_mfma_f32_16x16x32_bf16 v[28:31], v[150:153], v[190:193], 0
	v_mfma_f32_16x16x32_bf16 v[16:19], v[142:145], v[204:207], 0
	v_mfma_f32_16x16x32_bf16 v[12:15], v[150:153], v[204:207], 0
	v_mfma_f32_16x16x32_bf16 v[64:67], v[146:149], v[178:181], v[64:67]
	v_mfma_f32_16x16x32_bf16 v[60:63], v[154:157], v[178:181], v[60:63]
	v_mfma_f32_16x16x32_bf16 v[48:51], v[146:149], v[186:189], v[48:51]
	v_mfma_f32_16x16x32_bf16 v[44:47], v[154:157], v[186:189], v[44:47]
	v_mfma_f32_16x16x32_bf16 v[32:35], v[146:149], v[194:197], v[32:35]
	v_mfma_f32_16x16x32_bf16 v[28:31], v[154:157], v[194:197], v[28:31]
	v_mfma_f32_16x16x32_bf16 v[16:19], v[146:149], v[208:211], v[16:19]
	v_mfma_f32_16x16x32_bf16 v[12:15], v[154:157], v[208:211], v[12:15]
	s_setprio 0
	s_setprio 1
	v_mfma_f32_16x16x32_bf16 v[56:59], v[158:161], v[174:177], 0
	v_mfma_f32_16x16x32_bf16 v[52:55], v[166:169], v[174:177], 0
	v_mfma_f32_16x16x32_bf16 v[40:43], v[158:161], v[182:185], 0
	v_mfma_f32_16x16x32_bf16 v[36:39], v[166:169], v[182:185], 0
	v_mfma_f32_16x16x32_bf16 v[24:27], v[158:161], v[190:193], 0
	v_mfma_f32_16x16x32_bf16 v[20:23], v[166:169], v[190:193], 0
	v_mfma_f32_16x16x32_bf16 v[8:11], v[158:161], v[204:207], 0
	v_mfma_f32_16x16x32_bf16 v[4:7], v[166:169], v[204:207], 0
	v_mfma_f32_16x16x32_bf16 v[56:59], v[162:165], v[178:181], v[56:59]
	v_mfma_f32_16x16x32_bf16 v[52:55], v[170:173], v[178:181], v[52:55]
	v_mfma_f32_16x16x32_bf16 v[40:43], v[162:165], v[186:189], v[40:43]
	v_mfma_f32_16x16x32_bf16 v[36:39], v[170:173], v[186:189], v[36:39]
	v_mfma_f32_16x16x32_bf16 v[24:27], v[162:165], v[194:197], v[24:27]
	v_mfma_f32_16x16x32_bf16 v[20:23], v[170:173], v[194:197], v[20:23]
	v_mfma_f32_16x16x32_bf16 v[8:11], v[162:165], v[208:211], v[8:11]
	v_mfma_f32_16x16x32_bf16 v[4:7], v[170:173], v[208:211], v[4:7]
	s_barrier
	s_setprio 0
	s_add_i32 s29, 0, 0x18000
	s_add_i32 s33, 0, 0x1c000
	v_add_u32_e32 v154, s29, v140
	v_add_u32_e32 v170, s33, v140
	ds_read_b128 v[142:145], v154
	ds_read_b128 v[146:149], v154 offset:1024
	ds_read_b128 v[150:153], v154 offset:2048
	ds_read_b128 v[154:157], v154 offset:3072
	ds_read_b128 v[158:161], v170
	ds_read_b128 v[162:165], v170 offset:1024
	ds_read_b128 v[166:169], v170 offset:2048
	ds_read_b128 v[170:173], v170 offset:3072
	s_add_u32 s30, s36, 0x80000
	s_addc_u32 s31, s37, 0
	s_mov_b32 m0, s12
	v_lshl_add_u64 v[218:219], s[30:31], 0, v[0:1]
	ds_read_b128 v[174:177], v141 offset:32768
	ds_read_b128 v[178:181], v141 offset:33792
	ds_read_b128 v[182:185], v141 offset:34816
	ds_read_b128 v[186:189], v141 offset:35840
	ds_read_b128 v[190:193], v141 offset:36864
	ds_read_b128 v[194:197], v141 offset:37888
	ds_read_b128 v[204:207], v141 offset:38912
	ds_read_b128 v[208:211], v141 offset:39936
	global_load_lds_dwordx4 v[218:219], off
	v_lshl_add_u64 v[218:219], s[30:31], 0, v[132:133]
	s_mov_b32 m0, s13
	s_nop 0
	global_load_lds_dwordx4 v[218:219], off
	s_waitcnt vmcnt(8) lgkmcnt(0)
	s_barrier
	s_setprio 1
	v_mfma_f32_16x16x32_bf16 v[128:131], v[142:145], v[174:177], v[128:131]
	v_mfma_f32_16x16x32_bf16 v[124:127], v[150:153], v[174:177], v[124:127]
	v_mfma_f32_16x16x32_bf16 v[112:115], v[142:145], v[182:185], v[112:115]
	v_mfma_f32_16x16x32_bf16 v[108:111], v[150:153], v[182:185], v[108:111]
	v_mfma_f32_16x16x32_bf16 v[96:99], v[142:145], v[190:193], v[96:99]
	v_mfma_f32_16x16x32_bf16 v[92:95], v[150:153], v[190:193], v[92:95]
	v_mfma_f32_16x16x32_bf16 v[80:83], v[142:145], v[204:207], v[80:83]
	v_mfma_f32_16x16x32_bf16 v[76:79], v[150:153], v[204:207], v[76:79]
	v_mfma_f32_16x16x32_bf16 v[128:131], v[146:149], v[178:181], v[128:131]
	v_mfma_f32_16x16x32_bf16 v[124:127], v[154:157], v[178:181], v[124:127]
	v_mfma_f32_16x16x32_bf16 v[112:115], v[146:149], v[186:189], v[112:115]
	v_mfma_f32_16x16x32_bf16 v[108:111], v[154:157], v[186:189], v[108:111]
	v_mfma_f32_16x16x32_bf16 v[96:99], v[146:149], v[194:197], v[96:99]
	v_mfma_f32_16x16x32_bf16 v[92:95], v[154:157], v[194:197], v[92:95]
	v_mfma_f32_16x16x32_bf16 v[80:83], v[146:149], v[208:211], v[80:83]
	v_mfma_f32_16x16x32_bf16 v[76:79], v[154:157], v[208:211], v[76:79]
	s_setprio 0
	s_setprio 1
	v_mfma_f32_16x16x32_bf16 v[120:123], v[158:161], v[174:177], v[120:123]
	v_mfma_f32_16x16x32_bf16 v[116:119], v[166:169], v[174:177], v[116:119]
	v_mfma_f32_16x16x32_bf16 v[104:107], v[158:161], v[182:185], v[104:107]
	v_mfma_f32_16x16x32_bf16 v[100:103], v[166:169], v[182:185], v[100:103]
	v_mfma_f32_16x16x32_bf16 v[88:91], v[158:161], v[190:193], v[88:91]
	v_mfma_f32_16x16x32_bf16 v[84:87], v[166:169], v[190:193], v[84:87]
	v_mfma_f32_16x16x32_bf16 v[72:75], v[158:161], v[204:207], v[72:75]
	v_mfma_f32_16x16x32_bf16 v[68:71], v[166:169], v[204:207], v[68:71]
	v_mfma_f32_16x16x32_bf16 v[120:123], v[162:165], v[178:181], v[120:123]
	v_mfma_f32_16x16x32_bf16 v[116:119], v[170:173], v[178:181], v[116:119]
	v_mfma_f32_16x16x32_bf16 v[104:107], v[162:165], v[186:189], v[104:107]
	v_mfma_f32_16x16x32_bf16 v[100:103], v[170:173], v[186:189], v[100:103]
	v_mfma_f32_16x16x32_bf16 v[88:91], v[162:165], v[194:197], v[88:91]
	v_mfma_f32_16x16x32_bf16 v[84:87], v[170:173], v[194:197], v[84:87]
	v_mfma_f32_16x16x32_bf16 v[72:75], v[162:165], v[208:211], v[72:75]
	v_mfma_f32_16x16x32_bf16 v[68:71], v[170:173], v[208:211], v[68:71]
	s_barrier
	s_setprio 0
	s_add_i32 s29, s29, s9
	v_lshl_add_u64 v[198:199], v[198:199], 0, s[68:69]
	s_mov_b32 m0, s29
	ds_read_b128 v[174:177], v141 offset:49152
	ds_read_b128 v[178:181], v141 offset:50176
	ds_read_b128 v[182:185], v141 offset:51200
	ds_read_b128 v[186:189], v141 offset:52224
	ds_read_b128 v[190:193], v141 offset:53248
	ds_read_b128 v[194:197], v141 offset:54272
	ds_read_b128 v[204:207], v141 offset:55296
	ds_read_b128 v[208:211], v141 offset:56320
	global_load_lds_dwordx4 v[198:199], off
	s_add_i32 m0, s29, 0x2000
	s_add_u32 s26, s26, 0x80080
	v_lshl_add_u64 v[198:199], v[212:213], 0, s[68:69]
	s_addc_u32 s27, s27, 0
	s_add_i32 s29, s33, s9
	global_load_lds_dwordx4 v[198:199], off
	v_lshl_add_u64 v[198:199], s[26:27], 0, v[2:3]
	s_mov_b32 m0, s29
	s_nop 0
	global_load_lds_dwordx4 v[198:199], off
	v_lshl_add_u64 v[198:199], s[26:27], 0, v[134:135]
	s_add_i32 m0, s29, 0x2000
	s_nop 0
	global_load_lds_dwordx4 v[198:199], off
	v_lshl_add_u64 v[198:199], v[214:215], 0, s[68:69]
	s_mov_b32 m0, s14
	s_nop 0
	global_load_lds_dwordx4 v[198:199], off
	v_lshl_add_u64 v[198:199], v[216:217], 0, s[68:69]
	s_mov_b32 m0, s15
	s_nop 0
	global_load_lds_dwordx4 v[198:199], off
	s_waitcnt vmcnt(8) lgkmcnt(0)
	s_barrier
	s_setprio 1
	v_mfma_f32_16x16x32_bf16 v[64:67], v[142:145], v[174:177], v[64:67]
	v_mfma_f32_16x16x32_bf16 v[60:63], v[150:153], v[174:177], v[60:63]
	v_mfma_f32_16x16x32_bf16 v[48:51], v[142:145], v[182:185], v[48:51]
	v_mfma_f32_16x16x32_bf16 v[44:47], v[150:153], v[182:185], v[44:47]
	v_mfma_f32_16x16x32_bf16 v[32:35], v[142:145], v[190:193], v[32:35]
	v_mfma_f32_16x16x32_bf16 v[28:31], v[150:153], v[190:193], v[28:31]
	v_mfma_f32_16x16x32_bf16 v[16:19], v[142:145], v[204:207], v[16:19]
	v_mfma_f32_16x16x32_bf16 v[12:15], v[150:153], v[204:207], v[12:15]
	v_mfma_f32_16x16x32_bf16 v[64:67], v[146:149], v[178:181], v[64:67]
	v_mfma_f32_16x16x32_bf16 v[60:63], v[154:157], v[178:181], v[60:63]
	v_mfma_f32_16x16x32_bf16 v[48:51], v[146:149], v[186:189], v[48:51]
	v_mfma_f32_16x16x32_bf16 v[44:47], v[154:157], v[186:189], v[44:47]
	v_mfma_f32_16x16x32_bf16 v[32:35], v[146:149], v[194:197], v[32:35]
	v_mfma_f32_16x16x32_bf16 v[28:31], v[154:157], v[194:197], v[28:31]
	v_mfma_f32_16x16x32_bf16 v[16:19], v[146:149], v[208:211], v[16:19]
	v_mfma_f32_16x16x32_bf16 v[12:15], v[154:157], v[208:211], v[12:15]
	s_setprio 0
	s_setprio 1
	v_mfma_f32_16x16x32_bf16 v[56:59], v[158:161], v[174:177], v[56:59]
	v_mfma_f32_16x16x32_bf16 v[52:55], v[166:169], v[174:177], v[52:55]
	v_mfma_f32_16x16x32_bf16 v[40:43], v[158:161], v[182:185], v[40:43]
	v_mfma_f32_16x16x32_bf16 v[36:39], v[166:169], v[182:185], v[36:39]
	v_mfma_f32_16x16x32_bf16 v[24:27], v[158:161], v[190:193], v[24:27]
	v_mfma_f32_16x16x32_bf16 v[20:23], v[166:169], v[190:193], v[20:23]
	v_mfma_f32_16x16x32_bf16 v[8:11], v[158:161], v[204:207], v[8:11]
	v_mfma_f32_16x16x32_bf16 v[4:7], v[166:169], v[204:207], v[4:7]
	v_mfma_f32_16x16x32_bf16 v[56:59], v[162:165], v[178:181], v[56:59]
	v_mfma_f32_16x16x32_bf16 v[52:55], v[170:173], v[178:181], v[52:55]
	v_mfma_f32_16x16x32_bf16 v[40:43], v[162:165], v[186:189], v[40:43]
	v_mfma_f32_16x16x32_bf16 v[36:39], v[170:173], v[186:189], v[36:39]
	v_mfma_f32_16x16x32_bf16 v[24:27], v[162:165], v[194:197], v[24:27]
	v_mfma_f32_16x16x32_bf16 v[20:23], v[170:173], v[194:197], v[20:23]
	v_mfma_f32_16x16x32_bf16 v[8:11], v[162:165], v[208:211], v[8:11]
	v_mfma_f32_16x16x32_bf16 v[4:7], v[170:173], v[208:211], v[4:7]
	s_barrier
	s_setprio 0
	s_add_i32 s28, s28, 2
	s_add_u32 s24, s24, 0x100
	s_addc_u32 s25, s25, 0
	s_cmp_lt_u32 s28, 30
.LBB0_854:
	s_add_u32 s26, s18, s24
	s_addc_u32 s27, s19, s25
	s_add_u32 s26, s26, 0x22100100
	s_addc_u32 s27, s27, 0
	s_add_u32 s29, s16, s24
	s_addc_u32 s30, s17, s25
	s_add_i32 s31, 0, 0x10000
	s_cmpk_eq_i32 s24, 0xf00
	s_cselect_b32 s37, s23, s27
	s_cselect_b32 s36, s22, s26
	s_cselect_b32 s27, s21, s30
	s_cselect_b32 s26, s20, s29
	s_add_i32 s29, 0, 0x14000
	v_add_u32_e32 v154, s31, v140
	v_add_u32_e32 v170, s29, v140
	ds_read_b128 v[142:145], v154
	ds_read_b128 v[146:149], v154 offset:1024
	ds_read_b128 v[150:153], v154 offset:2048
	ds_read_b128 v[154:157], v154 offset:3072
	ds_read_b128 v[158:161], v170
	ds_read_b128 v[162:165], v170 offset:1024
	ds_read_b128 v[166:169], v170 offset:2048
	ds_read_b128 v[170:173], v170 offset:3072
	v_lshl_add_u64 v[198:199], v[138:139], 0, s[24:25]
	s_add_i32 m0, s10, 0xc000
	ds_read_b128 v[174:177], v141
	ds_read_b128 v[178:181], v141 offset:1024
	ds_read_b128 v[182:185], v141 offset:2048
	ds_read_b128 v[186:189], v141 offset:3072
	ds_read_b128 v[190:193], v141 offset:4096
	ds_read_b128 v[194:197], v141 offset:5120
	ds_read_b128 v[204:207], v141 offset:6144
	ds_read_b128 v[208:211], v141 offset:7168
	global_load_lds_dwordx4 v[198:199], off
	v_lshl_add_u64 v[198:199], v[136:137], 0, s[24:25]
	s_add_i32 m0, s10, 0xe000
	s_nop 0
	global_load_lds_dwordx4 v[198:199], off
	s_waitcnt vmcnt(8) lgkmcnt(0)
	s_barrier
	s_setprio 1
	v_mfma_f32_16x16x32_bf16 v[128:131], v[142:145], v[174:177], v[128:131]
	v_mfma_f32_16x16x32_bf16 v[124:127], v[150:153], v[174:177], v[124:127]
	v_mfma_f32_16x16x32_bf16 v[112:115], v[142:145], v[182:185], v[112:115]
	v_mfma_f32_16x16x32_bf16 v[108:111], v[150:153], v[182:185], v[108:111]
	v_mfma_f32_16x16x32_bf16 v[96:99], v[142:145], v[190:193], v[96:99]
	v_mfma_f32_16x16x32_bf16 v[92:95], v[150:153], v[190:193], v[92:95]
	v_mfma_f32_16x16x32_bf16 v[80:83], v[142:145], v[204:207], v[80:83]
	v_mfma_f32_16x16x32_bf16 v[76:79], v[150:153], v[204:207], v[76:79]
	v_mfma_f32_16x16x32_bf16 v[128:131], v[146:149], v[178:181], v[128:131]
	v_mfma_f32_16x16x32_bf16 v[124:127], v[154:157], v[178:181], v[124:127]
	v_mfma_f32_16x16x32_bf16 v[112:115], v[146:149], v[186:189], v[112:115]
	v_mfma_f32_16x16x32_bf16 v[108:111], v[154:157], v[186:189], v[108:111]
	v_mfma_f32_16x16x32_bf16 v[96:99], v[146:149], v[194:197], v[96:99]
	v_mfma_f32_16x16x32_bf16 v[92:95], v[154:157], v[194:197], v[92:95]
	v_mfma_f32_16x16x32_bf16 v[80:83], v[146:149], v[208:211], v[80:83]
	v_mfma_f32_16x16x32_bf16 v[76:79], v[154:157], v[208:211], v[76:79]
	s_setprio 0
	s_setprio 1
	v_mfma_f32_16x16x32_bf16 v[120:123], v[158:161], v[174:177], v[120:123]
	v_mfma_f32_16x16x32_bf16 v[116:119], v[166:169], v[174:177], v[116:119]
	v_mfma_f32_16x16x32_bf16 v[104:107], v[158:161], v[182:185], v[104:107]
	v_mfma_f32_16x16x32_bf16 v[100:103], v[166:169], v[182:185], v[100:103]
	v_mfma_f32_16x16x32_bf16 v[88:91], v[158:161], v[190:193], v[88:91]
	v_mfma_f32_16x16x32_bf16 v[84:87], v[166:169], v[190:193], v[84:87]
	v_mfma_f32_16x16x32_bf16 v[72:75], v[158:161], v[204:207], v[72:75]
	v_mfma_f32_16x16x32_bf16 v[68:71], v[166:169], v[204:207], v[68:71]
	v_mfma_f32_16x16x32_bf16 v[120:123], v[162:165], v[178:181], v[120:123]
	v_mfma_f32_16x16x32_bf16 v[116:119], v[170:173], v[178:181], v[116:119]
	v_mfma_f32_16x16x32_bf16 v[104:107], v[162:165], v[186:189], v[104:107]
	v_mfma_f32_16x16x32_bf16 v[100:103], v[170:173], v[186:189], v[100:103]
	v_mfma_f32_16x16x32_bf16 v[88:91], v[162:165], v[194:197], v[88:91]
	v_mfma_f32_16x16x32_bf16 v[84:87], v[170:173], v[194:197], v[84:87]
	v_mfma_f32_16x16x32_bf16 v[72:75], v[162:165], v[208:211], v[72:75]
	v_mfma_f32_16x16x32_bf16 v[68:71], v[170:173], v[208:211], v[68:71]
	s_barrier
	s_setprio 0
	s_add_i32 s30, s31, s9
	v_lshl_add_u64 v[198:199], s[26:27], 0, v[2:3]
	s_mov_b32 m0, s30
	ds_read_b128 v[174:177], v141 offset:16384
	ds_read_b128 v[178:181], v141 offset:17408
	ds_read_b128 v[182:185], v141 offset:18432
	ds_read_b128 v[186:189], v141 offset:19456
	ds_read_b128 v[190:193], v141 offset:20480
	ds_read_b128 v[194:197], v141 offset:21504
	ds_read_b128 v[204:207], v141 offset:22528
	ds_read_b128 v[208:211], v141 offset:23552
	global_load_lds_dwordx4 v[198:199], off
	s_add_i32 m0, s30, 0x2000
	s_add_u32 s30, s26, 0x80000
	v_lshl_add_u64 v[212:213], s[26:27], 0, v[134:135]
	s_addc_u32 s31, s27, 0
	s_add_i32 s29, s29, s9
	global_load_lds_dwordx4 v[212:213], off
	v_lshl_add_u64 v[214:215], s[30:31], 0, v[2:3]
	s_mov_b32 m0, s29
	v_lshl_add_u64 v[216:217], s[36:37], 0, v[132:133]
	global_load_lds_dwordx4 v[214:215], off
	v_lshl_add_u64 v[214:215], s[30:31], 0, v[134:135]
	s_add_i32 m0, s29, 0x2000
	s_nop 0
	global_load_lds_dwordx4 v[214:215], off
	v_lshl_add_u64 v[214:215], s[36:37], 0, v[0:1]
	s_mov_b32 m0, s10
	s_nop 0
	global_load_lds_dwordx4 v[214:215], off
	s_mov_b32 m0, s11
	s_nop 0
	global_load_lds_dwordx4 v[216:217], off
	s_waitcnt vmcnt(8) lgkmcnt(0)
	s_barrier
	s_setprio 1
	v_mfma_f32_16x16x32_bf16 v[64:67], v[142:145], v[174:177], v[64:67]
	v_mfma_f32_16x16x32_bf16 v[60:63], v[150:153], v[174:177], v[60:63]
	v_mfma_f32_16x16x32_bf16 v[48:51], v[142:145], v[182:185], v[48:51]
	v_mfma_f32_16x16x32_bf16 v[44:47], v[150:153], v[182:185], v[44:47]
	v_mfma_f32_16x16x32_bf16 v[32:35], v[142:145], v[190:193], v[32:35]
	v_mfma_f32_16x16x32_bf16 v[28:31], v[150:153], v[190:193], v[28:31]
	v_mfma_f32_16x16x32_bf16 v[16:19], v[142:145], v[204:207], v[16:19]
	v_mfma_f32_16x16x32_bf16 v[12:15], v[150:153], v[204:207], v[12:15]
	v_mfma_f32_16x16x32_bf16 v[64:67], v[146:149], v[178:181], v[64:67]
	v_mfma_f32_16x16x32_bf16 v[60:63], v[154:157], v[178:181], v[60:63]
	v_mfma_f32_16x16x32_bf16 v[48:51], v[146:149], v[186:189], v[48:51]
	v_mfma_f32_16x16x32_bf16 v[44:47], v[154:157], v[186:189], v[44:47]
	v_mfma_f32_16x16x32_bf16 v[32:35], v[146:149], v[194:197], v[32:35]
	v_mfma_f32_16x16x32_bf16 v[28:31], v[154:157], v[194:197], v[28:31]
	v_mfma_f32_16x16x32_bf16 v[16:19], v[146:149], v[208:211], v[16:19]
	v_mfma_f32_16x16x32_bf16 v[12:15], v[154:157], v[208:211], v[12:15]
	s_setprio 0
	s_setprio 1
	v_mfma_f32_16x16x32_bf16 v[56:59], v[158:161], v[174:177], v[56:59]
	v_mfma_f32_16x16x32_bf16 v[52:55], v[166:169], v[174:177], v[52:55]
	v_mfma_f32_16x16x32_bf16 v[40:43], v[158:161], v[182:185], v[40:43]
	v_mfma_f32_16x16x32_bf16 v[36:39], v[166:169], v[182:185], v[36:39]
	v_mfma_f32_16x16x32_bf16 v[24:27], v[158:161], v[190:193], v[24:27]
	v_mfma_f32_16x16x32_bf16 v[20:23], v[166:169], v[190:193], v[20:23]
	v_mfma_f32_16x16x32_bf16 v[8:11], v[158:161], v[204:207], v[8:11]
	v_mfma_f32_16x16x32_bf16 v[4:7], v[166:169], v[204:207], v[4:7]
	v_mfma_f32_16x16x32_bf16 v[56:59], v[162:165], v[178:181], v[56:59]
	v_mfma_f32_16x16x32_bf16 v[52:55], v[170:173], v[178:181], v[52:55]
	v_mfma_f32_16x16x32_bf16 v[40:43], v[162:165], v[186:189], v[40:43]
	v_mfma_f32_16x16x32_bf16 v[36:39], v[170:173], v[186:189], v[36:39]
	v_mfma_f32_16x16x32_bf16 v[24:27], v[162:165], v[194:197], v[24:27]
	v_mfma_f32_16x16x32_bf16 v[20:23], v[170:173], v[194:197], v[20:23]
	v_mfma_f32_16x16x32_bf16 v[8:11], v[162:165], v[208:211], v[8:11]
	v_mfma_f32_16x16x32_bf16 v[4:7], v[170:173], v[208:211], v[4:7]
	s_barrier
	s_setprio 0
	s_add_i32 s29, 0, 0x18000
	s_add_i32 s33, 0, 0x1c000
	v_add_u32_e32 v154, s29, v140
	v_add_u32_e32 v170, s33, v140
	ds_read_b128 v[142:145], v154
	ds_read_b128 v[146:149], v154 offset:1024
	ds_read_b128 v[150:153], v154 offset:2048
	ds_read_b128 v[154:157], v154 offset:3072
	ds_read_b128 v[158:161], v170
	ds_read_b128 v[162:165], v170 offset:1024
	ds_read_b128 v[166:169], v170 offset:2048
	ds_read_b128 v[170:173], v170 offset:3072
	s_add_u32 s30, s36, 0x80000
	s_addc_u32 s31, s37, 0
	s_mov_b32 m0, s12
	v_lshl_add_u64 v[218:219], s[30:31], 0, v[0:1]
	ds_read_b128 v[174:177], v141 offset:32768
	ds_read_b128 v[178:181], v141 offset:33792
	ds_read_b128 v[182:185], v141 offset:34816
	ds_read_b128 v[186:189], v141 offset:35840
	ds_read_b128 v[190:193], v141 offset:36864
	ds_read_b128 v[194:197], v141 offset:37888
	ds_read_b128 v[204:207], v141 offset:38912
	ds_read_b128 v[208:211], v141 offset:39936
	global_load_lds_dwordx4 v[218:219], off
	v_lshl_add_u64 v[218:219], s[30:31], 0, v[132:133]
	s_mov_b32 m0, s13
	s_nop 0
	global_load_lds_dwordx4 v[218:219], off
	s_waitcnt vmcnt(8) lgkmcnt(0)
	s_barrier
	s_setprio 1
	v_mfma_f32_16x16x32_bf16 v[128:131], v[142:145], v[174:177], v[128:131]
	v_mfma_f32_16x16x32_bf16 v[124:127], v[150:153], v[174:177], v[124:127]
	v_mfma_f32_16x16x32_bf16 v[112:115], v[142:145], v[182:185], v[112:115]
	v_mfma_f32_16x16x32_bf16 v[108:111], v[150:153], v[182:185], v[108:111]
	v_mfma_f32_16x16x32_bf16 v[96:99], v[142:145], v[190:193], v[96:99]
	v_mfma_f32_16x16x32_bf16 v[92:95], v[150:153], v[190:193], v[92:95]
	v_mfma_f32_16x16x32_bf16 v[80:83], v[142:145], v[204:207], v[80:83]
	v_mfma_f32_16x16x32_bf16 v[76:79], v[150:153], v[204:207], v[76:79]
	v_mfma_f32_16x16x32_bf16 v[128:131], v[146:149], v[178:181], v[128:131]
	v_mfma_f32_16x16x32_bf16 v[124:127], v[154:157], v[178:181], v[124:127]
	v_mfma_f32_16x16x32_bf16 v[112:115], v[146:149], v[186:189], v[112:115]
	v_mfma_f32_16x16x32_bf16 v[108:111], v[154:157], v[186:189], v[108:111]
	v_mfma_f32_16x16x32_bf16 v[96:99], v[146:149], v[194:197], v[96:99]
	v_mfma_f32_16x16x32_bf16 v[92:95], v[154:157], v[194:197], v[92:95]
	v_mfma_f32_16x16x32_bf16 v[80:83], v[146:149], v[208:211], v[80:83]
	v_mfma_f32_16x16x32_bf16 v[76:79], v[154:157], v[208:211], v[76:79]
	s_setprio 0
	s_setprio 1
	v_mfma_f32_16x16x32_bf16 v[120:123], v[158:161], v[174:177], v[120:123]
	v_mfma_f32_16x16x32_bf16 v[116:119], v[166:169], v[174:177], v[116:119]
	v_mfma_f32_16x16x32_bf16 v[104:107], v[158:161], v[182:185], v[104:107]
	v_mfma_f32_16x16x32_bf16 v[100:103], v[166:169], v[182:185], v[100:103]
	v_mfma_f32_16x16x32_bf16 v[88:91], v[158:161], v[190:193], v[88:91]
	v_mfma_f32_16x16x32_bf16 v[84:87], v[166:169], v[190:193], v[84:87]
	v_mfma_f32_16x16x32_bf16 v[72:75], v[158:161], v[204:207], v[72:75]
	v_mfma_f32_16x16x32_bf16 v[68:71], v[166:169], v[204:207], v[68:71]
	v_mfma_f32_16x16x32_bf16 v[120:123], v[162:165], v[178:181], v[120:123]
	v_mfma_f32_16x16x32_bf16 v[116:119], v[170:173], v[178:181], v[116:119]
	v_mfma_f32_16x16x32_bf16 v[104:107], v[162:165], v[186:189], v[104:107]
	v_mfma_f32_16x16x32_bf16 v[100:103], v[170:173], v[186:189], v[100:103]
	v_mfma_f32_16x16x32_bf16 v[88:91], v[162:165], v[194:197], v[88:91]
	v_mfma_f32_16x16x32_bf16 v[84:87], v[170:173], v[194:197], v[84:87]
	v_mfma_f32_16x16x32_bf16 v[72:75], v[162:165], v[208:211], v[72:75]
	v_mfma_f32_16x16x32_bf16 v[68:71], v[170:173], v[208:211], v[68:71]
	s_barrier
	s_setprio 0
	s_add_i32 s29, s29, s9
	v_lshl_add_u64 v[198:199], v[198:199], 0, s[68:69]
	s_mov_b32 m0, s29
	ds_read_b128 v[174:177], v141 offset:49152
	ds_read_b128 v[178:181], v141 offset:50176
	ds_read_b128 v[182:185], v141 offset:51200
	ds_read_b128 v[186:189], v141 offset:52224
	ds_read_b128 v[190:193], v141 offset:53248
	ds_read_b128 v[194:197], v141 offset:54272
	ds_read_b128 v[204:207], v141 offset:55296
	ds_read_b128 v[208:211], v141 offset:56320
	global_load_lds_dwordx4 v[198:199], off
	s_add_i32 m0, s29, 0x2000
	s_add_u32 s26, s26, 0x80080
	v_lshl_add_u64 v[198:199], v[212:213], 0, s[68:69]
	s_addc_u32 s27, s27, 0
	s_add_i32 s29, s33, s9
	global_load_lds_dwordx4 v[198:199], off
	v_lshl_add_u64 v[198:199], s[26:27], 0, v[2:3]
	s_mov_b32 m0, s29
	s_nop 0
	global_load_lds_dwordx4 v[198:199], off
	v_lshl_add_u64 v[198:199], s[26:27], 0, v[134:135]
	s_add_i32 m0, s29, 0x2000
	s_nop 0
	global_load_lds_dwordx4 v[198:199], off
	v_lshl_add_u64 v[198:199], v[214:215], 0, s[68:69]
	s_mov_b32 m0, s14
	s_nop 0
	global_load_lds_dwordx4 v[198:199], off
	v_lshl_add_u64 v[198:199], v[216:217], 0, s[68:69]
	s_mov_b32 m0, s15
	s_nop 0
	global_load_lds_dwordx4 v[198:199], off
	s_waitcnt vmcnt(8) lgkmcnt(0)
	s_barrier
	s_setprio 1
	v_mfma_f32_16x16x32_bf16 v[64:67], v[142:145], v[174:177], v[64:67]
	v_mfma_f32_16x16x32_bf16 v[60:63], v[150:153], v[174:177], v[60:63]
	v_mfma_f32_16x16x32_bf16 v[48:51], v[142:145], v[182:185], v[48:51]
	v_mfma_f32_16x16x32_bf16 v[44:47], v[150:153], v[182:185], v[44:47]
	v_mfma_f32_16x16x32_bf16 v[32:35], v[142:145], v[190:193], v[32:35]
	v_mfma_f32_16x16x32_bf16 v[28:31], v[150:153], v[190:193], v[28:31]
	v_mfma_f32_16x16x32_bf16 v[16:19], v[142:145], v[204:207], v[16:19]
	v_mfma_f32_16x16x32_bf16 v[12:15], v[150:153], v[204:207], v[12:15]
	v_mfma_f32_16x16x32_bf16 v[64:67], v[146:149], v[178:181], v[64:67]
	v_mfma_f32_16x16x32_bf16 v[60:63], v[154:157], v[178:181], v[60:63]
	v_mfma_f32_16x16x32_bf16 v[48:51], v[146:149], v[186:189], v[48:51]
	v_mfma_f32_16x16x32_bf16 v[44:47], v[154:157], v[186:189], v[44:47]
	v_mfma_f32_16x16x32_bf16 v[32:35], v[146:149], v[194:197], v[32:35]
	v_mfma_f32_16x16x32_bf16 v[28:31], v[154:157], v[194:197], v[28:31]
	v_mfma_f32_16x16x32_bf16 v[16:19], v[146:149], v[208:211], v[16:19]
	v_mfma_f32_16x16x32_bf16 v[12:15], v[154:157], v[208:211], v[12:15]
	s_setprio 0
	s_setprio 1
	v_mfma_f32_16x16x32_bf16 v[56:59], v[158:161], v[174:177], v[56:59]
	v_mfma_f32_16x16x32_bf16 v[52:55], v[166:169], v[174:177], v[52:55]
	v_mfma_f32_16x16x32_bf16 v[40:43], v[158:161], v[182:185], v[40:43]
	v_mfma_f32_16x16x32_bf16 v[36:39], v[166:169], v[182:185], v[36:39]
	v_mfma_f32_16x16x32_bf16 v[24:27], v[158:161], v[190:193], v[24:27]
	v_mfma_f32_16x16x32_bf16 v[20:23], v[166:169], v[190:193], v[20:23]
	v_mfma_f32_16x16x32_bf16 v[8:11], v[158:161], v[204:207], v[8:11]
	v_mfma_f32_16x16x32_bf16 v[4:7], v[166:169], v[204:207], v[4:7]
	v_mfma_f32_16x16x32_bf16 v[56:59], v[162:165], v[178:181], v[56:59]
	v_mfma_f32_16x16x32_bf16 v[52:55], v[170:173], v[178:181], v[52:55]
	v_mfma_f32_16x16x32_bf16 v[40:43], v[162:165], v[186:189], v[40:43]
	v_mfma_f32_16x16x32_bf16 v[36:39], v[170:173], v[186:189], v[36:39]
	v_mfma_f32_16x16x32_bf16 v[24:27], v[162:165], v[194:197], v[24:27]
	v_mfma_f32_16x16x32_bf16 v[20:23], v[170:173], v[194:197], v[20:23]
	v_mfma_f32_16x16x32_bf16 v[8:11], v[162:165], v[208:211], v[8:11]
	v_mfma_f32_16x16x32_bf16 v[4:7], v[170:173], v[208:211], v[4:7]
	s_barrier
	s_setprio 0
	s_add_i32 s28, s28, 2
	s_add_u32 s24, s24, 0x100
	s_addc_u32 s25, s25, 0
	s_cmp_lt_u32 s28, 30
	s_cbranch_scc1 .LBB0_854
	s_waitcnt vmcnt(0)
	s_cmpk_gt_u32 s6, 0xff
	s_cbranch_scc1 .LBB0_857
	s_barrier

.LBB0_946:
	s_ashr_i32 s49, s48, 31
	s_andn2_b64 vcc, exec, s[56:57]
	s_lshl_b64 s[6:7], s[48:49], 19
	s_add_u32 s52, s62, s6
	s_addc_u32 s53, s63, s7
	s_and_b64 s[6:7], s[56:57], exec
	s_cselect_b32 s5, s53, s41
	s_cselect_b32 s6, s52, s40
	s_ashr_i32 s51, s50, 31
	s_lshl_b64 s[8:9], s[50:51], 19
	s_add_u32 s54, s64, s8
	s_addc_u32 s55, s65, s9
	s_and_b64 s[8:9], s[56:57], exec
	s_cselect_b32 s7, s55, s39
	s_cselect_b32 s8, s54, s38
	s_add_u32 s9, s38, 0x100
	v_cndmask_b32_e64 v4, 0, 1, s[56:57]
	s_addc_u32 s10, s39, 0
	v_cmp_ne_u32_e64 s[36:37], 1, v4
	s_add_u32 s38, s40, 0x40080
	s_addc_u32 s39, s41, 0
	s_mov_b32 s11, -2
	s_waitcnt lgkmcnt(0)
	s_add_u32 s12, s38, 0xfffc0080
	s_addc_u32 s13, s39, -1
	s_add_i32 s14, 0, 0x10000
	s_cmp_eq_u32 s11, 12
	s_cselect_b32 s57, s5, s13
	s_cselect_b32 s56, s6, s12
	s_cselect_b32 s41, s7, s10
	s_cselect_b32 s40, s8, s9
	s_add_i32 s15, 0, 0x14000
	v_add_u32_e32 v144, s14, v230
	v_add_u32_e32 v160, s15, v230
	ds_read_b128 v[124:127], v144
	ds_read_b128 v[128:131], v144 offset:1024
	ds_read_b128 v[136:139], v144 offset:2048
	ds_read_b128 v[144:147], v144 offset:3072
	ds_read_b128 v[148:151], v160
	ds_read_b128 v[152:155], v160 offset:1024
	ds_read_b128 v[156:159], v160 offset:2048
	ds_read_b128 v[160:163], v160 offset:3072
	v_lshl_add_u64 v[196:197], s[38:39], 0, v[222:223]
	s_add_i32 m0, s71, 0xc000
	ds_read_b128 v[164:167], v243
	ds_read_b128 v[168:171], v243 offset:1024
	ds_read_b128 v[172:175], v243 offset:2048
	ds_read_b128 v[176:179], v243 offset:3072
	ds_read_b128 v[180:183], v243 offset:4096
	ds_read_b128 v[184:187], v243 offset:5120
	ds_read_b128 v[188:191], v243 offset:6144
	ds_read_b128 v[192:195], v243 offset:7168
	global_load_lds_dwordx4 v[196:197], off
	v_lshl_add_u64 v[196:197], s[38:39], 0, v[220:221]
	s_add_i32 m0, s71, 0xe000
	s_nop 0
	global_load_lds_dwordx4 v[196:197], off
	s_waitcnt vmcnt(8) lgkmcnt(0)
	s_barrier
	s_setprio 1
	v_mfma_f32_16x16x32_bf16 v[140:143], v[124:127], v[164:167], 0
	v_mfma_f32_16x16x32_bf16 v[132:135], v[136:139], v[164:167], 0
	v_mfma_f32_16x16x32_bf16 v[112:115], v[124:127], v[172:175], 0
	v_mfma_f32_16x16x32_bf16 v[108:111], v[136:139], v[172:175], 0
	v_mfma_f32_16x16x32_bf16 v[96:99], v[124:127], v[180:183], 0
	v_mfma_f32_16x16x32_bf16 v[92:95], v[136:139], v[180:183], 0
	v_mfma_f32_16x16x32_bf16 v[80:83], v[124:127], v[188:191], 0
	v_mfma_f32_16x16x32_bf16 v[76:79], v[136:139], v[188:191], 0
	v_mfma_f32_16x16x32_bf16 v[140:143], v[128:131], v[168:171], v[140:143]
	v_mfma_f32_16x16x32_bf16 v[132:135], v[144:147], v[168:171], v[132:135]
	v_mfma_f32_16x16x32_bf16 v[112:115], v[128:131], v[176:179], v[112:115]
	v_mfma_f32_16x16x32_bf16 v[108:111], v[144:147], v[176:179], v[108:111]
	v_mfma_f32_16x16x32_bf16 v[96:99], v[128:131], v[184:187], v[96:99]
	v_mfma_f32_16x16x32_bf16 v[92:95], v[144:147], v[184:187], v[92:95]
	v_mfma_f32_16x16x32_bf16 v[80:83], v[128:131], v[192:195], v[80:83]
	v_mfma_f32_16x16x32_bf16 v[76:79], v[144:147], v[192:195], v[76:79]
	s_setprio 0
	s_setprio 1
	v_mfma_f32_16x16x32_bf16 v[120:123], v[148:151], v[164:167], 0
	v_mfma_f32_16x16x32_bf16 v[116:119], v[156:159], v[164:167], 0
	v_mfma_f32_16x16x32_bf16 v[104:107], v[148:151], v[172:175], 0
	v_mfma_f32_16x16x32_bf16 v[100:103], v[156:159], v[172:175], 0
	v_mfma_f32_16x16x32_bf16 v[88:91], v[148:151], v[180:183], 0
	v_mfma_f32_16x16x32_bf16 v[84:87], v[156:159], v[180:183], 0
	v_mfma_f32_16x16x32_bf16 v[72:75], v[148:151], v[188:191], 0
	v_mfma_f32_16x16x32_bf16 v[68:71], v[156:159], v[188:191], 0
	v_mfma_f32_16x16x32_bf16 v[120:123], v[152:155], v[168:171], v[120:123]
	v_mfma_f32_16x16x32_bf16 v[116:119], v[160:163], v[168:171], v[116:119]
	v_mfma_f32_16x16x32_bf16 v[104:107], v[152:155], v[176:179], v[104:107]
	v_mfma_f32_16x16x32_bf16 v[100:103], v[160:163], v[176:179], v[100:103]
	v_mfma_f32_16x16x32_bf16 v[88:91], v[152:155], v[184:187], v[88:91]
	v_mfma_f32_16x16x32_bf16 v[84:87], v[160:163], v[184:187], v[84:87]
	v_mfma_f32_16x16x32_bf16 v[72:75], v[152:155], v[192:195], v[72:75]
	v_mfma_f32_16x16x32_bf16 v[68:71], v[160:163], v[192:195], v[68:71]
	s_barrier
	s_setprio 0
	s_add_i32 s12, s14, s70
	v_lshl_add_u64 v[196:197], s[40:41], 0, v[2:3]
	s_mov_b32 m0, s12
	ds_read_b128 v[164:167], v243 offset:16384
	ds_read_b128 v[168:171], v243 offset:17408
	ds_read_b128 v[172:175], v243 offset:18432
	ds_read_b128 v[176:179], v243 offset:19456
	ds_read_b128 v[180:183], v243 offset:20480
	ds_read_b128 v[184:187], v243 offset:21504
	ds_read_b128 v[188:191], v243 offset:22528
	ds_read_b128 v[192:195], v243 offset:23552
	global_load_lds_dwordx4 v[196:197], off
	s_add_i32 m0, s12, 0x2000
	s_add_u32 s12, s40, 0x40000
	v_lshl_add_u64 v[198:199], s[40:41], 0, v[218:219]
	s_addc_u32 s13, s41, 0
	s_add_i32 s14, s15, s70
	global_load_lds_dwordx4 v[198:199], off
	v_lshl_add_u64 v[200:201], s[12:13], 0, v[2:3]
	s_mov_b32 m0, s14
	v_lshl_add_u64 v[202:203], s[56:57], 0, v[216:217]
	global_load_lds_dwordx4 v[200:201], off
	v_lshl_add_u64 v[200:201], s[12:13], 0, v[218:219]
	s_add_i32 m0, s14, 0x2000
	s_nop 0
	global_load_lds_dwordx4 v[200:201], off
	v_lshl_add_u64 v[200:201], s[56:57], 0, v[0:1]
	s_mov_b32 m0, s71
	s_nop 0
	global_load_lds_dwordx4 v[200:201], off
	s_mov_b32 m0, s80
	s_nop 0
	global_load_lds_dwordx4 v[202:203], off
	s_waitcnt vmcnt(8) lgkmcnt(0)
	s_barrier
	s_setprio 1
	v_mfma_f32_16x16x32_bf16 v[64:67], v[124:127], v[164:167], 0
	v_mfma_f32_16x16x32_bf16 v[60:63], v[136:139], v[164:167], 0
	v_mfma_f32_16x16x32_bf16 v[48:51], v[124:127], v[172:175], 0
	v_mfma_f32_16x16x32_bf16 v[44:47], v[136:139], v[172:175], 0
	v_mfma_f32_16x16x32_bf16 v[32:35], v[124:127], v[180:183], 0
	v_mfma_f32_16x16x32_bf16 v[28:31], v[136:139], v[180:183], 0
	v_mfma_f32_16x16x32_bf16 v[16:19], v[124:127], v[188:191], 0
	v_mfma_f32_16x16x32_bf16 v[12:15], v[136:139], v[188:191], 0
	v_mfma_f32_16x16x32_bf16 v[64:67], v[128:131], v[168:171], v[64:67]
	v_mfma_f32_16x16x32_bf16 v[60:63], v[144:147], v[168:171], v[60:63]
	v_mfma_f32_16x16x32_bf16 v[48:51], v[128:131], v[176:179], v[48:51]
	v_mfma_f32_16x16x32_bf16 v[44:47], v[144:147], v[176:179], v[44:47]
	v_mfma_f32_16x16x32_bf16 v[32:35], v[128:131], v[184:187], v[32:35]
	v_mfma_f32_16x16x32_bf16 v[28:31], v[144:147], v[184:187], v[28:31]
	v_mfma_f32_16x16x32_bf16 v[16:19], v[128:131], v[192:195], v[16:19]
	v_mfma_f32_16x16x32_bf16 v[12:15], v[144:147], v[192:195], v[12:15]
	s_setprio 0
	s_setprio 1
	v_mfma_f32_16x16x32_bf16 v[56:59], v[148:151], v[164:167], 0
	v_mfma_f32_16x16x32_bf16 v[52:55], v[156:159], v[164:167], 0
	v_mfma_f32_16x16x32_bf16 v[40:43], v[148:151], v[172:175], 0
	v_mfma_f32_16x16x32_bf16 v[36:39], v[156:159], v[172:175], 0
	v_mfma_f32_16x16x32_bf16 v[24:27], v[148:151], v[180:183], 0
	v_mfma_f32_16x16x32_bf16 v[20:23], v[156:159], v[180:183], 0
	v_mfma_f32_16x16x32_bf16 v[8:11], v[148:151], v[188:191], 0
	v_mfma_f32_16x16x32_bf16 v[4:7], v[156:159], v[188:191], 0
	v_mfma_f32_16x16x32_bf16 v[56:59], v[152:155], v[168:171], v[56:59]
	v_mfma_f32_16x16x32_bf16 v[52:55], v[160:163], v[168:171], v[52:55]
	v_mfma_f32_16x16x32_bf16 v[40:43], v[152:155], v[176:179], v[40:43]
	v_mfma_f32_16x16x32_bf16 v[36:39], v[160:163], v[176:179], v[36:39]
	v_mfma_f32_16x16x32_bf16 v[24:27], v[152:155], v[184:187], v[24:27]
	v_mfma_f32_16x16x32_bf16 v[20:23], v[160:163], v[184:187], v[20:23]
	v_mfma_f32_16x16x32_bf16 v[8:11], v[152:155], v[192:195], v[8:11]
	v_mfma_f32_16x16x32_bf16 v[4:7], v[160:163], v[192:195], v[4:7]
	s_barrier
	s_setprio 0
	s_add_i32 s14, 0, 0x18000
	s_add_i32 s15, 0, 0x1c000
	v_add_u32_e32 v144, s14, v230
	v_add_u32_e32 v160, s15, v230
	ds_read_b128 v[124:127], v144
	ds_read_b128 v[128:131], v144 offset:1024
	ds_read_b128 v[136:139], v144 offset:2048
	ds_read_b128 v[144:147], v144 offset:3072
	ds_read_b128 v[148:151], v160
	ds_read_b128 v[152:155], v160 offset:1024
	ds_read_b128 v[156:159], v160 offset:2048
	ds_read_b128 v[160:163], v160 offset:3072
	s_add_u32 s12, s56, 0x40000
	s_addc_u32 s13, s57, 0
	s_mov_b32 m0, s81
	v_lshl_add_u64 v[204:205], s[12:13], 0, v[0:1]
	ds_read_b128 v[164:167], v243 offset:32768
	ds_read_b128 v[168:171], v243 offset:33792
	ds_read_b128 v[172:175], v243 offset:34816
	ds_read_b128 v[176:179], v243 offset:35840
	ds_read_b128 v[180:183], v243 offset:36864
	ds_read_b128 v[184:187], v243 offset:37888
	ds_read_b128 v[188:191], v243 offset:38912
	ds_read_b128 v[192:195], v243 offset:39936
	global_load_lds_dwordx4 v[204:205], off
	v_lshl_add_u64 v[204:205], s[12:13], 0, v[216:217]
	s_mov_b32 m0, s82
	s_nop 0
	global_load_lds_dwordx4 v[204:205], off
	s_waitcnt vmcnt(8) lgkmcnt(0)
	s_barrier
	s_setprio 1
	v_mfma_f32_16x16x32_bf16 v[140:143], v[124:127], v[164:167], v[140:143]
	v_mfma_f32_16x16x32_bf16 v[132:135], v[136:139], v[164:167], v[132:135]
	v_mfma_f32_16x16x32_bf16 v[112:115], v[124:127], v[172:175], v[112:115]
	v_mfma_f32_16x16x32_bf16 v[108:111], v[136:139], v[172:175], v[108:111]
	v_mfma_f32_16x16x32_bf16 v[96:99], v[124:127], v[180:183], v[96:99]
	v_mfma_f32_16x16x32_bf16 v[92:95], v[136:139], v[180:183], v[92:95]
	v_mfma_f32_16x16x32_bf16 v[80:83], v[124:127], v[188:191], v[80:83]
	v_mfma_f32_16x16x32_bf16 v[76:79], v[136:139], v[188:191], v[76:79]
	v_mfma_f32_16x16x32_bf16 v[140:143], v[128:131], v[168:171], v[140:143]
	v_mfma_f32_16x16x32_bf16 v[132:135], v[144:147], v[168:171], v[132:135]
	v_mfma_f32_16x16x32_bf16 v[112:115], v[128:131], v[176:179], v[112:115]
	v_mfma_f32_16x16x32_bf16 v[108:111], v[144:147], v[176:179], v[108:111]
	v_mfma_f32_16x16x32_bf16 v[96:99], v[128:131], v[184:187], v[96:99]
	v_mfma_f32_16x16x32_bf16 v[92:95], v[144:147], v[184:187], v[92:95]
	v_mfma_f32_16x16x32_bf16 v[80:83], v[128:131], v[192:195], v[80:83]
	v_mfma_f32_16x16x32_bf16 v[76:79], v[144:147], v[192:195], v[76:79]
	s_setprio 0
	s_setprio 1
	v_mfma_f32_16x16x32_bf16 v[120:123], v[148:151], v[164:167], v[120:123]
	v_mfma_f32_16x16x32_bf16 v[116:119], v[156:159], v[164:167], v[116:119]
	v_mfma_f32_16x16x32_bf16 v[104:107], v[148:151], v[172:175], v[104:107]
	v_mfma_f32_16x16x32_bf16 v[100:103], v[156:159], v[172:175], v[100:103]
	v_mfma_f32_16x16x32_bf16 v[88:91], v[148:151], v[180:183], v[88:91]
	v_mfma_f32_16x16x32_bf16 v[84:87], v[156:159], v[180:183], v[84:87]
	v_mfma_f32_16x16x32_bf16 v[72:75], v[148:151], v[188:191], v[72:75]
	v_mfma_f32_16x16x32_bf16 v[68:71], v[156:159], v[188:191], v[68:71]
	v_mfma_f32_16x16x32_bf16 v[120:123], v[152:155], v[168:171], v[120:123]
	v_mfma_f32_16x16x32_bf16 v[116:119], v[160:163], v[168:171], v[116:119]
	v_mfma_f32_16x16x32_bf16 v[104:107], v[152:155], v[176:179], v[104:107]
	v_mfma_f32_16x16x32_bf16 v[100:103], v[160:163], v[176:179], v[100:103]
	v_mfma_f32_16x16x32_bf16 v[88:91], v[152:155], v[184:187], v[88:91]
	v_mfma_f32_16x16x32_bf16 v[84:87], v[160:163], v[184:187], v[84:87]
	v_mfma_f32_16x16x32_bf16 v[72:75], v[152:155], v[192:195], v[72:75]
	v_mfma_f32_16x16x32_bf16 v[68:71], v[160:163], v[192:195], v[68:71]
	s_barrier
	s_setprio 0
	s_add_i32 s12, s14, s70
	v_lshl_add_u64 v[196:197], v[196:197], 0, s[68:69]
	s_mov_b32 m0, s12
	ds_read_b128 v[164:167], v243 offset:49152
	ds_read_b128 v[168:171], v243 offset:50176
	ds_read_b128 v[172:175], v243 offset:51200
	ds_read_b128 v[176:179], v243 offset:52224
	ds_read_b128 v[180:183], v243 offset:53248
	ds_read_b128 v[184:187], v243 offset:54272
	ds_read_b128 v[188:191], v243 offset:55296
	ds_read_b128 v[192:195], v243 offset:56320
	global_load_lds_dwordx4 v[196:197], off
	s_add_i32 m0, s12, 0x2000
	s_add_u32 s12, s40, 0x40080
	v_lshl_add_u64 v[196:197], v[198:199], 0, s[68:69]
	s_addc_u32 s13, s41, 0
	s_add_i32 s14, s15, s70
	global_load_lds_dwordx4 v[196:197], off
	v_lshl_add_u64 v[196:197], s[12:13], 0, v[2:3]
	s_mov_b32 m0, s14
	s_nop 0
	global_load_lds_dwordx4 v[196:197], off
	v_lshl_add_u64 v[196:197], s[12:13], 0, v[218:219]
	s_add_i32 m0, s14, 0x2000
	s_nop 0
	global_load_lds_dwordx4 v[196:197], off
	v_lshl_add_u64 v[196:197], v[200:201], 0, s[68:69]
	s_mov_b32 m0, s85
	s_nop 0
	global_load_lds_dwordx4 v[196:197], off
	v_lshl_add_u64 v[196:197], v[202:203], 0, s[68:69]
	s_mov_b32 m0, s87
	s_nop 0
	global_load_lds_dwordx4 v[196:197], off
	s_waitcnt vmcnt(8) lgkmcnt(0)
	s_barrier
	s_setprio 1
	v_mfma_f32_16x16x32_bf16 v[64:67], v[124:127], v[164:167], v[64:67]
	v_mfma_f32_16x16x32_bf16 v[60:63], v[136:139], v[164:167], v[60:63]
	v_mfma_f32_16x16x32_bf16 v[48:51], v[124:127], v[172:175], v[48:51]
	v_mfma_f32_16x16x32_bf16 v[44:47], v[136:139], v[172:175], v[44:47]
	v_mfma_f32_16x16x32_bf16 v[32:35], v[124:127], v[180:183], v[32:35]
	v_mfma_f32_16x16x32_bf16 v[28:31], v[136:139], v[180:183], v[28:31]
	v_mfma_f32_16x16x32_bf16 v[16:19], v[124:127], v[188:191], v[16:19]
	v_mfma_f32_16x16x32_bf16 v[12:15], v[136:139], v[188:191], v[12:15]
	v_mfma_f32_16x16x32_bf16 v[64:67], v[128:131], v[168:171], v[64:67]
	v_mfma_f32_16x16x32_bf16 v[60:63], v[144:147], v[168:171], v[60:63]
	v_mfma_f32_16x16x32_bf16 v[48:51], v[128:131], v[176:179], v[48:51]
	v_mfma_f32_16x16x32_bf16 v[44:47], v[144:147], v[176:179], v[44:47]
	v_mfma_f32_16x16x32_bf16 v[32:35], v[128:131], v[184:187], v[32:35]
	v_mfma_f32_16x16x32_bf16 v[28:31], v[144:147], v[184:187], v[28:31]
	v_mfma_f32_16x16x32_bf16 v[16:19], v[128:131], v[192:195], v[16:19]
	v_mfma_f32_16x16x32_bf16 v[12:15], v[144:147], v[192:195], v[12:15]
	s_setprio 0
	s_setprio 1
	v_mfma_f32_16x16x32_bf16 v[56:59], v[148:151], v[164:167], v[56:59]
	v_mfma_f32_16x16x32_bf16 v[52:55], v[156:159], v[164:167], v[52:55]
	v_mfma_f32_16x16x32_bf16 v[40:43], v[148:151], v[172:175], v[40:43]
	v_mfma_f32_16x16x32_bf16 v[36:39], v[156:159], v[172:175], v[36:39]
	v_mfma_f32_16x16x32_bf16 v[24:27], v[148:151], v[180:183], v[24:27]
	v_mfma_f32_16x16x32_bf16 v[20:23], v[156:159], v[180:183], v[20:23]
	v_mfma_f32_16x16x32_bf16 v[8:11], v[148:151], v[188:191], v[8:11]
	v_mfma_f32_16x16x32_bf16 v[4:7], v[156:159], v[188:191], v[4:7]
	v_mfma_f32_16x16x32_bf16 v[56:59], v[152:155], v[168:171], v[56:59]
	v_mfma_f32_16x16x32_bf16 v[52:55], v[160:163], v[168:171], v[52:55]
	v_mfma_f32_16x16x32_bf16 v[40:43], v[152:155], v[176:179], v[40:43]
	v_mfma_f32_16x16x32_bf16 v[36:39], v[160:163], v[176:179], v[36:39]
	v_mfma_f32_16x16x32_bf16 v[24:27], v[152:155], v[184:187], v[24:27]
	v_mfma_f32_16x16x32_bf16 v[20:23], v[160:163], v[184:187], v[20:23]
	v_mfma_f32_16x16x32_bf16 v[8:11], v[152:155], v[192:195], v[8:11]
	v_mfma_f32_16x16x32_bf16 v[4:7], v[160:163], v[192:195], v[4:7]
	s_barrier
	s_setprio 0
	s_add_i32 s11, s11, 2
	s_add_u32 s9, s9, 0x100
	s_addc_u32 s10, s10, 0
	s_add_u32 s38, s38, 0x100
	s_addc_u32 s39, s39, 0
	s_cmp_gt_u32 s11, 13
.LBB0_947:
	s_add_u32 s12, s38, 0xfffc0080
	s_addc_u32 s13, s39, -1
	s_add_i32 s14, 0, 0x10000
	s_cmp_eq_u32 s11, 12
	s_cselect_b32 s57, s5, s13
	s_cselect_b32 s56, s6, s12
	s_cselect_b32 s41, s7, s10
	s_cselect_b32 s40, s8, s9
	s_add_i32 s15, 0, 0x14000
	v_add_u32_e32 v144, s14, v230
	v_add_u32_e32 v160, s15, v230
	ds_read_b128 v[124:127], v144
	ds_read_b128 v[128:131], v144 offset:1024
	ds_read_b128 v[136:139], v144 offset:2048
	ds_read_b128 v[144:147], v144 offset:3072
	ds_read_b128 v[148:151], v160
	ds_read_b128 v[152:155], v160 offset:1024
	ds_read_b128 v[156:159], v160 offset:2048
	ds_read_b128 v[160:163], v160 offset:3072
	v_lshl_add_u64 v[196:197], s[38:39], 0, v[222:223]
	s_add_i32 m0, s71, 0xc000
	ds_read_b128 v[164:167], v243
	ds_read_b128 v[168:171], v243 offset:1024
	ds_read_b128 v[172:175], v243 offset:2048
	ds_read_b128 v[176:179], v243 offset:3072
	ds_read_b128 v[180:183], v243 offset:4096
	ds_read_b128 v[184:187], v243 offset:5120
	ds_read_b128 v[188:191], v243 offset:6144
	ds_read_b128 v[192:195], v243 offset:7168
	global_load_lds_dwordx4 v[196:197], off
	v_lshl_add_u64 v[196:197], s[38:39], 0, v[220:221]
	s_add_i32 m0, s71, 0xe000
	s_nop 0
	global_load_lds_dwordx4 v[196:197], off
	s_waitcnt vmcnt(8) lgkmcnt(0)
	s_barrier
	s_setprio 1
	v_mfma_f32_16x16x32_bf16 v[140:143], v[124:127], v[164:167], v[140:143]
	v_mfma_f32_16x16x32_bf16 v[132:135], v[136:139], v[164:167], v[132:135]
	v_mfma_f32_16x16x32_bf16 v[112:115], v[124:127], v[172:175], v[112:115]
	v_mfma_f32_16x16x32_bf16 v[108:111], v[136:139], v[172:175], v[108:111]
	v_mfma_f32_16x16x32_bf16 v[96:99], v[124:127], v[180:183], v[96:99]
	v_mfma_f32_16x16x32_bf16 v[92:95], v[136:139], v[180:183], v[92:95]
	v_mfma_f32_16x16x32_bf16 v[80:83], v[124:127], v[188:191], v[80:83]
	v_mfma_f32_16x16x32_bf16 v[76:79], v[136:139], v[188:191], v[76:79]
	v_mfma_f32_16x16x32_bf16 v[140:143], v[128:131], v[168:171], v[140:143]
	v_mfma_f32_16x16x32_bf16 v[132:135], v[144:147], v[168:171], v[132:135]
	v_mfma_f32_16x16x32_bf16 v[112:115], v[128:131], v[176:179], v[112:115]
	v_mfma_f32_16x16x32_bf16 v[108:111], v[144:147], v[176:179], v[108:111]
	v_mfma_f32_16x16x32_bf16 v[96:99], v[128:131], v[184:187], v[96:99]
	v_mfma_f32_16x16x32_bf16 v[92:95], v[144:147], v[184:187], v[92:95]
	v_mfma_f32_16x16x32_bf16 v[80:83], v[128:131], v[192:195], v[80:83]
	v_mfma_f32_16x16x32_bf16 v[76:79], v[144:147], v[192:195], v[76:79]
	s_setprio 0
	s_setprio 1
	v_mfma_f32_16x16x32_bf16 v[120:123], v[148:151], v[164:167], v[120:123]
	v_mfma_f32_16x16x32_bf16 v[116:119], v[156:159], v[164:167], v[116:119]
	v_mfma_f32_16x16x32_bf16 v[104:107], v[148:151], v[172:175], v[104:107]
	v_mfma_f32_16x16x32_bf16 v[100:103], v[156:159], v[172:175], v[100:103]
	v_mfma_f32_16x16x32_bf16 v[88:91], v[148:151], v[180:183], v[88:91]
	v_mfma_f32_16x16x32_bf16 v[84:87], v[156:159], v[180:183], v[84:87]
	v_mfma_f32_16x16x32_bf16 v[72:75], v[148:151], v[188:191], v[72:75]
	v_mfma_f32_16x16x32_bf16 v[68:71], v[156:159], v[188:191], v[68:71]
	v_mfma_f32_16x16x32_bf16 v[120:123], v[152:155], v[168:171], v[120:123]
	v_mfma_f32_16x16x32_bf16 v[116:119], v[160:163], v[168:171], v[116:119]
	v_mfma_f32_16x16x32_bf16 v[104:107], v[152:155], v[176:179], v[104:107]
	v_mfma_f32_16x16x32_bf16 v[100:103], v[160:163], v[176:179], v[100:103]
	v_mfma_f32_16x16x32_bf16 v[88:91], v[152:155], v[184:187], v[88:91]
	v_mfma_f32_16x16x32_bf16 v[84:87], v[160:163], v[184:187], v[84:87]
	v_mfma_f32_16x16x32_bf16 v[72:75], v[152:155], v[192:195], v[72:75]
	v_mfma_f32_16x16x32_bf16 v[68:71], v[160:163], v[192:195], v[68:71]
	s_barrier
	s_setprio 0
	s_add_i32 s12, s14, s70
	v_lshl_add_u64 v[196:197], s[40:41], 0, v[2:3]
	s_mov_b32 m0, s12
	ds_read_b128 v[164:167], v243 offset:16384
	ds_read_b128 v[168:171], v243 offset:17408
	ds_read_b128 v[172:175], v243 offset:18432
	ds_read_b128 v[176:179], v243 offset:19456
	ds_read_b128 v[180:183], v243 offset:20480
	ds_read_b128 v[184:187], v243 offset:21504
	ds_read_b128 v[188:191], v243 offset:22528
	ds_read_b128 v[192:195], v243 offset:23552
	global_load_lds_dwordx4 v[196:197], off
	s_add_i32 m0, s12, 0x2000
	s_add_u32 s12, s40, 0x40000
	v_lshl_add_u64 v[198:199], s[40:41], 0, v[218:219]
	s_addc_u32 s13, s41, 0
	s_add_i32 s14, s15, s70
	global_load_lds_dwordx4 v[198:199], off
	v_lshl_add_u64 v[200:201], s[12:13], 0, v[2:3]
	s_mov_b32 m0, s14
	v_lshl_add_u64 v[202:203], s[56:57], 0, v[216:217]
	global_load_lds_dwordx4 v[200:201], off
	v_lshl_add_u64 v[200:201], s[12:13], 0, v[218:219]
	s_add_i32 m0, s14, 0x2000
	s_nop 0
	global_load_lds_dwordx4 v[200:201], off
	v_lshl_add_u64 v[200:201], s[56:57], 0, v[0:1]
	s_mov_b32 m0, s71
	s_nop 0
	global_load_lds_dwordx4 v[200:201], off
	s_mov_b32 m0, s80
	s_nop 0
	global_load_lds_dwordx4 v[202:203], off
	s_waitcnt vmcnt(8) lgkmcnt(0)
	s_barrier
	s_setprio 1
	v_mfma_f32_16x16x32_bf16 v[64:67], v[124:127], v[164:167], v[64:67]
	v_mfma_f32_16x16x32_bf16 v[60:63], v[136:139], v[164:167], v[60:63]
	v_mfma_f32_16x16x32_bf16 v[48:51], v[124:127], v[172:175], v[48:51]
	v_mfma_f32_16x16x32_bf16 v[44:47], v[136:139], v[172:175], v[44:47]
	v_mfma_f32_16x16x32_bf16 v[32:35], v[124:127], v[180:183], v[32:35]
	v_mfma_f32_16x16x32_bf16 v[28:31], v[136:139], v[180:183], v[28:31]
	v_mfma_f32_16x16x32_bf16 v[16:19], v[124:127], v[188:191], v[16:19]
	v_mfma_f32_16x16x32_bf16 v[12:15], v[136:139], v[188:191], v[12:15]
	v_mfma_f32_16x16x32_bf16 v[64:67], v[128:131], v[168:171], v[64:67]
	v_mfma_f32_16x16x32_bf16 v[60:63], v[144:147], v[168:171], v[60:63]
	v_mfma_f32_16x16x32_bf16 v[48:51], v[128:131], v[176:179], v[48:51]
	v_mfma_f32_16x16x32_bf16 v[44:47], v[144:147], v[176:179], v[44:47]
	v_mfma_f32_16x16x32_bf16 v[32:35], v[128:131], v[184:187], v[32:35]
	v_mfma_f32_16x16x32_bf16 v[28:31], v[144:147], v[184:187], v[28:31]
	v_mfma_f32_16x16x32_bf16 v[16:19], v[128:131], v[192:195], v[16:19]
	v_mfma_f32_16x16x32_bf16 v[12:15], v[144:147], v[192:195], v[12:15]
	s_setprio 0
	s_setprio 1
	v_mfma_f32_16x16x32_bf16 v[56:59], v[148:151], v[164:167], v[56:59]
	v_mfma_f32_16x16x32_bf16 v[52:55], v[156:159], v[164:167], v[52:55]
	v_mfma_f32_16x16x32_bf16 v[40:43], v[148:151], v[172:175], v[40:43]
	v_mfma_f32_16x16x32_bf16 v[36:39], v[156:159], v[172:175], v[36:39]
	v_mfma_f32_16x16x32_bf16 v[24:27], v[148:151], v[180:183], v[24:27]
	v_mfma_f32_16x16x32_bf16 v[20:23], v[156:159], v[180:183], v[20:23]
	v_mfma_f32_16x16x32_bf16 v[8:11], v[148:151], v[188:191], v[8:11]
	v_mfma_f32_16x16x32_bf16 v[4:7], v[156:159], v[188:191], v[4:7]
	v_mfma_f32_16x16x32_bf16 v[56:59], v[152:155], v[168:171], v[56:59]
	v_mfma_f32_16x16x32_bf16 v[52:55], v[160:163], v[168:171], v[52:55]
	v_mfma_f32_16x16x32_bf16 v[40:43], v[152:155], v[176:179], v[40:43]
	v_mfma_f32_16x16x32_bf16 v[36:39], v[160:163], v[176:179], v[36:39]
	v_mfma_f32_16x16x32_bf16 v[24:27], v[152:155], v[184:187], v[24:27]
	v_mfma_f32_16x16x32_bf16 v[20:23], v[160:163], v[184:187], v[20:23]
	v_mfma_f32_16x16x32_bf16 v[8:11], v[152:155], v[192:195], v[8:11]
	v_mfma_f32_16x16x32_bf16 v[4:7], v[160:163], v[192:195], v[4:7]
	s_barrier
	s_setprio 0
	s_add_i32 s14, 0, 0x18000
	s_add_i32 s15, 0, 0x1c000
	v_add_u32_e32 v144, s14, v230
	v_add_u32_e32 v160, s15, v230
	ds_read_b128 v[124:127], v144
	ds_read_b128 v[128:131], v144 offset:1024
	ds_read_b128 v[136:139], v144 offset:2048
	ds_read_b128 v[144:147], v144 offset:3072
	ds_read_b128 v[148:151], v160
	ds_read_b128 v[152:155], v160 offset:1024
	ds_read_b128 v[156:159], v160 offset:2048
	ds_read_b128 v[160:163], v160 offset:3072
	s_add_u32 s12, s56, 0x40000
	s_addc_u32 s13, s57, 0
	s_mov_b32 m0, s81
	v_lshl_add_u64 v[204:205], s[12:13], 0, v[0:1]
	ds_read_b128 v[164:167], v243 offset:32768
	ds_read_b128 v[168:171], v243 offset:33792
	ds_read_b128 v[172:175], v243 offset:34816
	ds_read_b128 v[176:179], v243 offset:35840
	ds_read_b128 v[180:183], v243 offset:36864
	ds_read_b128 v[184:187], v243 offset:37888
	ds_read_b128 v[188:191], v243 offset:38912
	ds_read_b128 v[192:195], v243 offset:39936
	global_load_lds_dwordx4 v[204:205], off
	v_lshl_add_u64 v[204:205], s[12:13], 0, v[216:217]
	s_mov_b32 m0, s82
	s_nop 0
	global_load_lds_dwordx4 v[204:205], off
	s_waitcnt vmcnt(8) lgkmcnt(0)
	s_barrier
	s_setprio 1
	v_mfma_f32_16x16x32_bf16 v[140:143], v[124:127], v[164:167], v[140:143]
	v_mfma_f32_16x16x32_bf16 v[132:135], v[136:139], v[164:167], v[132:135]
	v_mfma_f32_16x16x32_bf16 v[112:115], v[124:127], v[172:175], v[112:115]
	v_mfma_f32_16x16x32_bf16 v[108:111], v[136:139], v[172:175], v[108:111]
	v_mfma_f32_16x16x32_bf16 v[96:99], v[124:127], v[180:183], v[96:99]
	v_mfma_f32_16x16x32_bf16 v[92:95], v[136:139], v[180:183], v[92:95]
	v_mfma_f32_16x16x32_bf16 v[80:83], v[124:127], v[188:191], v[80:83]
	v_mfma_f32_16x16x32_bf16 v[76:79], v[136:139], v[188:191], v[76:79]
	v_mfma_f32_16x16x32_bf16 v[140:143], v[128:131], v[168:171], v[140:143]
	v_mfma_f32_16x16x32_bf16 v[132:135], v[144:147], v[168:171], v[132:135]
	v_mfma_f32_16x16x32_bf16 v[112:115], v[128:131], v[176:179], v[112:115]
	v_mfma_f32_16x16x32_bf16 v[108:111], v[144:147], v[176:179], v[108:111]
	v_mfma_f32_16x16x32_bf16 v[96:99], v[128:131], v[184:187], v[96:99]
	v_mfma_f32_16x16x32_bf16 v[92:95], v[144:147], v[184:187], v[92:95]
	v_mfma_f32_16x16x32_bf16 v[80:83], v[128:131], v[192:195], v[80:83]
	v_mfma_f32_16x16x32_bf16 v[76:79], v[144:147], v[192:195], v[76:79]
	s_setprio 0
	s_setprio 1
	v_mfma_f32_16x16x32_bf16 v[120:123], v[148:151], v[164:167], v[120:123]
	v_mfma_f32_16x16x32_bf16 v[116:119], v[156:159], v[164:167], v[116:119]
	v_mfma_f32_16x16x32_bf16 v[104:107], v[148:151], v[172:175], v[104:107]
	v_mfma_f32_16x16x32_bf16 v[100:103], v[156:159], v[172:175], v[100:103]
	v_mfma_f32_16x16x32_bf16 v[88:91], v[148:151], v[180:183], v[88:91]
	v_mfma_f32_16x16x32_bf16 v[84:87], v[156:159], v[180:183], v[84:87]
	v_mfma_f32_16x16x32_bf16 v[72:75], v[148:151], v[188:191], v[72:75]
	v_mfma_f32_16x16x32_bf16 v[68:71], v[156:159], v[188:191], v[68:71]
	v_mfma_f32_16x16x32_bf16 v[120:123], v[152:155], v[168:171], v[120:123]
	v_mfma_f32_16x16x32_bf16 v[116:119], v[160:163], v[168:171], v[116:119]
	v_mfma_f32_16x16x32_bf16 v[104:107], v[152:155], v[176:179], v[104:107]
	v_mfma_f32_16x16x32_bf16 v[100:103], v[160:163], v[176:179], v[100:103]
	v_mfma_f32_16x16x32_bf16 v[88:91], v[152:155], v[184:187], v[88:91]
	v_mfma_f32_16x16x32_bf16 v[84:87], v[160:163], v[184:187], v[84:87]
	v_mfma_f32_16x16x32_bf16 v[72:75], v[152:155], v[192:195], v[72:75]
	v_mfma_f32_16x16x32_bf16 v[68:71], v[160:163], v[192:195], v[68:71]
	s_barrier
	s_setprio 0
	s_add_i32 s12, s14, s70
	v_lshl_add_u64 v[196:197], v[196:197], 0, s[68:69]
	s_mov_b32 m0, s12
	ds_read_b128 v[164:167], v243 offset:49152
	ds_read_b128 v[168:171], v243 offset:50176
	ds_read_b128 v[172:175], v243 offset:51200
	ds_read_b128 v[176:179], v243 offset:52224
	ds_read_b128 v[180:183], v243 offset:53248
	ds_read_b128 v[184:187], v243 offset:54272
	ds_read_b128 v[188:191], v243 offset:55296
	ds_read_b128 v[192:195], v243 offset:56320
	global_load_lds_dwordx4 v[196:197], off
	s_add_i32 m0, s12, 0x2000
	s_add_u32 s12, s40, 0x40080
	v_lshl_add_u64 v[196:197], v[198:199], 0, s[68:69]
	s_addc_u32 s13, s41, 0
	s_add_i32 s14, s15, s70
	global_load_lds_dwordx4 v[196:197], off
	v_lshl_add_u64 v[196:197], s[12:13], 0, v[2:3]
	s_mov_b32 m0, s14
	s_nop 0
	global_load_lds_dwordx4 v[196:197], off
	v_lshl_add_u64 v[196:197], s[12:13], 0, v[218:219]
	s_add_i32 m0, s14, 0x2000
	s_nop 0
	global_load_lds_dwordx4 v[196:197], off
	v_lshl_add_u64 v[196:197], v[200:201], 0, s[68:69]
	s_mov_b32 m0, s85
	s_nop 0
	global_load_lds_dwordx4 v[196:197], off
	v_lshl_add_u64 v[196:197], v[202:203], 0, s[68:69]
	s_mov_b32 m0, s87
	s_nop 0
	global_load_lds_dwordx4 v[196:197], off
	s_waitcnt vmcnt(8) lgkmcnt(0)
	s_barrier
	s_setprio 1
	v_mfma_f32_16x16x32_bf16 v[64:67], v[124:127], v[164:167], v[64:67]
	v_mfma_f32_16x16x32_bf16 v[60:63], v[136:139], v[164:167], v[60:63]
	v_mfma_f32_16x16x32_bf16 v[48:51], v[124:127], v[172:175], v[48:51]
	v_mfma_f32_16x16x32_bf16 v[44:47], v[136:139], v[172:175], v[44:47]
	v_mfma_f32_16x16x32_bf16 v[32:35], v[124:127], v[180:183], v[32:35]
	v_mfma_f32_16x16x32_bf16 v[28:31], v[136:139], v[180:183], v[28:31]
	v_mfma_f32_16x16x32_bf16 v[16:19], v[124:127], v[188:191], v[16:19]
	v_mfma_f32_16x16x32_bf16 v[12:15], v[136:139], v[188:191], v[12:15]
	v_mfma_f32_16x16x32_bf16 v[64:67], v[128:131], v[168:171], v[64:67]
	v_mfma_f32_16x16x32_bf16 v[60:63], v[144:147], v[168:171], v[60:63]
	v_mfma_f32_16x16x32_bf16 v[48:51], v[128:131], v[176:179], v[48:51]
	v_mfma_f32_16x16x32_bf16 v[44:47], v[144:147], v[176:179], v[44:47]
	v_mfma_f32_16x16x32_bf16 v[32:35], v[128:131], v[184:187], v[32:35]
	v_mfma_f32_16x16x32_bf16 v[28:31], v[144:147], v[184:187], v[28:31]
	v_mfma_f32_16x16x32_bf16 v[16:19], v[128:131], v[192:195], v[16:19]
	v_mfma_f32_16x16x32_bf16 v[12:15], v[144:147], v[192:195], v[12:15]
	s_setprio 0
	s_setprio 1
	v_mfma_f32_16x16x32_bf16 v[56:59], v[148:151], v[164:167], v[56:59]
	v_mfma_f32_16x16x32_bf16 v[52:55], v[156:159], v[164:167], v[52:55]
	v_mfma_f32_16x16x32_bf16 v[40:43], v[148:151], v[172:175], v[40:43]
	v_mfma_f32_16x16x32_bf16 v[36:39], v[156:159], v[172:175], v[36:39]
	v_mfma_f32_16x16x32_bf16 v[24:27], v[148:151], v[180:183], v[24:27]
	v_mfma_f32_16x16x32_bf16 v[20:23], v[156:159], v[180:183], v[20:23]
	v_mfma_f32_16x16x32_bf16 v[8:11], v[148:151], v[188:191], v[8:11]
	v_mfma_f32_16x16x32_bf16 v[4:7], v[156:159], v[188:191], v[4:7]
	v_mfma_f32_16x16x32_bf16 v[56:59], v[152:155], v[168:171], v[56:59]
	v_mfma_f32_16x16x32_bf16 v[52:55], v[160:163], v[168:171], v[52:55]
	v_mfma_f32_16x16x32_bf16 v[40:43], v[152:155], v[176:179], v[40:43]
	v_mfma_f32_16x16x32_bf16 v[36:39], v[160:163], v[176:179], v[36:39]
	v_mfma_f32_16x16x32_bf16 v[24:27], v[152:155], v[184:187], v[24:27]
	v_mfma_f32_16x16x32_bf16 v[20:23], v[160:163], v[184:187], v[20:23]
	v_mfma_f32_16x16x32_bf16 v[8:11], v[152:155], v[192:195], v[8:11]
	v_mfma_f32_16x16x32_bf16 v[4:7], v[160:163], v[192:195], v[4:7]
	s_barrier
	s_setprio 0
	s_add_i32 s11, s11, 2
	s_add_u32 s9, s9, 0x100
	s_addc_u32 s10, s10, 0
	s_add_u32 s38, s38, 0x100
	s_addc_u32 s39, s39, 0
	s_cmp_gt_u32 s11, 13
	s_cbranch_scc0 .LBB0_947
	s_and_b64 vcc, exec, s[46:47]
	s_cbranch_vccz .LBB0_950
	s_barrier

.Lgu_skip2_p:
	s_mov_b32 s32, 0
	s_waitcnt lgkmcnt(0)
	s_barrier
	s_setprio 1
	v_mfma_f32_16x16x32_bf16 v[64:67], v[142:145], v[184:187], 0
	v_mfma_f32_16x16x32_bf16 v[56:59], v[150:153], v[184:187], 0
	v_mfma_f32_16x16x32_bf16 v[48:51], v[142:145], v[192:195], 0
	v_mfma_f32_16x16x32_bf16 v[40:43], v[150:153], v[192:195], 0
	v_mfma_f32_16x16x32_bf16 v[32:35], v[142:145], v[200:203], 0
	v_mfma_f32_16x16x32_bf16 v[24:27], v[150:153], v[200:203], 0
	v_mfma_f32_16x16x32_bf16 v[16:19], v[142:145], v[208:211], 0
	v_mfma_f32_16x16x32_bf16 v[8:11], v[150:153], v[208:211], 0
	v_mfma_f32_16x16x32_bf16 v[64:67], v[146:149], v[188:191], v[64:67]
	v_mfma_f32_16x16x32_bf16 v[56:59], v[154:157], v[188:191], v[56:59]
	v_mfma_f32_16x16x32_bf16 v[48:51], v[146:149], v[196:199], v[48:51]
	v_mfma_f32_16x16x32_bf16 v[40:43], v[154:157], v[196:199], v[40:43]
	v_mfma_f32_16x16x32_bf16 v[32:35], v[146:149], v[204:207], v[32:35]
	v_mfma_f32_16x16x32_bf16 v[24:27], v[154:157], v[204:207], v[24:27]
	v_mfma_f32_16x16x32_bf16 v[16:19], v[146:149], v[212:215], v[16:19]
	v_mfma_f32_16x16x32_bf16 v[8:11], v[154:157], v[212:215], v[8:11]
	v_mfma_f32_16x16x32_bf16 v[60:63], v[168:171], v[184:187], 0
	v_mfma_f32_16x16x32_bf16 v[52:55], v[176:179], v[184:187], 0
	v_mfma_f32_16x16x32_bf16 v[44:47], v[168:171], v[192:195], 0
	v_mfma_f32_16x16x32_bf16 v[36:39], v[176:179], v[192:195], 0
	v_mfma_f32_16x16x32_bf16 v[28:31], v[168:171], v[200:203], 0
	v_mfma_f32_16x16x32_bf16 v[20:23], v[176:179], v[200:203], 0
	v_mfma_f32_16x16x32_bf16 v[12:15], v[168:171], v[208:211], 0
	v_mfma_f32_16x16x32_bf16 v[4:7], v[176:179], v[208:211], 0
	v_mfma_f32_16x16x32_bf16 v[60:63], v[172:175], v[188:191], v[60:63]
	v_mfma_f32_16x16x32_bf16 v[52:55], v[180:183], v[188:191], v[52:55]
	v_mfma_f32_16x16x32_bf16 v[44:47], v[172:175], v[196:199], v[44:47]
	v_mfma_f32_16x16x32_bf16 v[36:39], v[180:183], v[196:199], v[36:39]
	v_mfma_f32_16x16x32_bf16 v[28:31], v[172:175], v[204:207], v[28:31]
	v_mfma_f32_16x16x32_bf16 v[20:23], v[180:183], v[204:207], v[20:23]
	v_mfma_f32_16x16x32_bf16 v[12:15], v[172:175], v[212:215], v[12:15]
	v_mfma_f32_16x16x32_bf16 v[4:7], v[180:183], v[212:215], v[4:7]
	s_barrier
	s_setprio 0
	s_add_i32 s14, 0, 0x18000
	s_add_i32 s15, 0, 0x1c000
	ds_read_b128 v[142:145], v133 offset:32768
	ds_read_b128 v[146:149], v133 offset:33792
	ds_read_b128 v[150:153], v133 offset:34816
	ds_read_b128 v[154:157], v133 offset:35840
	ds_read_b128 v[168:171], v133 offset:49152
	ds_read_b128 v[172:175], v133 offset:50176
	ds_read_b128 v[176:179], v133 offset:51200
	ds_read_b128 v[180:183], v133 offset:52224
	s_add_u32 s12, s48, 0x80000
	s_addc_u32 s13, s49, 0
	s_mov_b32 m0, s62
	ds_read_b128 v[184:187], v167 offset:32768
	ds_read_b128 v[188:191], v167 offset:33792
	ds_read_b128 v[192:195], v167 offset:34816
	ds_read_b128 v[196:199], v167 offset:35840
	ds_read_b128 v[200:203], v167 offset:36864
	ds_read_b128 v[204:207], v167 offset:37888
	ds_read_b128 v[208:211], v167 offset:38912
	ds_read_b128 v[212:215], v167 offset:39936
	global_load_lds_dwordx4 v134, s[12:13]
	s_mov_b32 m0, s63
	s_nop 0
	global_load_lds_dwordx4 v132, s[12:13]
	s_waitcnt vmcnt(8) lgkmcnt(0)
	s_barrier
	s_setprio 1
	v_mfma_f32_16x16x32_bf16 v[124:127], v[142:145], v[184:187], v[124:127]
	v_mfma_f32_16x16x32_bf16 v[120:123], v[150:153], v[184:187], v[120:123]
	v_mfma_f32_16x16x32_bf16 v[112:115], v[142:145], v[192:195], v[112:115]
	v_mfma_f32_16x16x32_bf16 v[104:107], v[150:153], v[192:195], v[104:107]
	v_mfma_f32_16x16x32_bf16 v[96:99], v[142:145], v[200:203], v[96:99]
	v_mfma_f32_16x16x32_bf16 v[88:91], v[150:153], v[200:203], v[88:91]
	v_mfma_f32_16x16x32_bf16 v[80:83], v[142:145], v[208:211], v[80:83]
	v_mfma_f32_16x16x32_bf16 v[72:75], v[150:153], v[208:211], v[72:75]
	v_mfma_f32_16x16x32_bf16 v[124:127], v[146:149], v[188:191], v[124:127]
	v_mfma_f32_16x16x32_bf16 v[120:123], v[154:157], v[188:191], v[120:123]
	v_mfma_f32_16x16x32_bf16 v[112:115], v[146:149], v[196:199], v[112:115]
	v_mfma_f32_16x16x32_bf16 v[104:107], v[154:157], v[196:199], v[104:107]
	v_mfma_f32_16x16x32_bf16 v[96:99], v[146:149], v[204:207], v[96:99]
	v_mfma_f32_16x16x32_bf16 v[88:91], v[154:157], v[204:207], v[88:91]
	v_mfma_f32_16x16x32_bf16 v[80:83], v[146:149], v[212:215], v[80:83]
	v_mfma_f32_16x16x32_bf16 v[72:75], v[154:157], v[212:215], v[72:75]
	v_mfma_f32_16x16x32_bf16 v[128:131], v[168:171], v[184:187], v[128:131]
	v_mfma_f32_16x16x32_bf16 v[116:119], v[176:179], v[184:187], v[116:119]
	v_mfma_f32_16x16x32_bf16 v[108:111], v[168:171], v[192:195], v[108:111]
	v_mfma_f32_16x16x32_bf16 v[100:103], v[176:179], v[192:195], v[100:103]
	v_mfma_f32_16x16x32_bf16 v[92:95], v[168:171], v[200:203], v[92:95]
	v_mfma_f32_16x16x32_bf16 v[84:87], v[176:179], v[200:203], v[84:87]
	v_mfma_f32_16x16x32_bf16 v[76:79], v[168:171], v[208:211], v[76:79]
	v_mfma_f32_16x16x32_bf16 v[68:71], v[176:179], v[208:211], v[68:71]
	v_mfma_f32_16x16x32_bf16 v[128:131], v[172:175], v[188:191], v[128:131]
	v_mfma_f32_16x16x32_bf16 v[116:119], v[180:183], v[188:191], v[116:119]
	v_mfma_f32_16x16x32_bf16 v[108:111], v[172:175], v[196:199], v[108:111]
	v_mfma_f32_16x16x32_bf16 v[100:103], v[180:183], v[196:199], v[100:103]
	v_mfma_f32_16x16x32_bf16 v[92:95], v[172:175], v[204:207], v[92:95]
	v_mfma_f32_16x16x32_bf16 v[84:87], v[180:183], v[204:207], v[84:87]
	v_mfma_f32_16x16x32_bf16 v[76:79], v[172:175], v[212:215], v[76:79]
	v_mfma_f32_16x16x32_bf16 v[68:71], v[180:183], v[212:215], v[68:71]
	s_barrier
	s_setprio 0
	s_add_i32 s12, s14, s56
	s_mov_b32 m0, s12
	ds_read_b128 v[184:187], v167 offset:49152
	ds_read_b128 v[188:191], v167 offset:50176
	ds_read_b128 v[192:195], v167 offset:51200
	ds_read_b128 v[196:199], v167 offset:52224
	ds_read_b128 v[200:203], v167 offset:53248
	ds_read_b128 v[204:207], v167 offset:54272
	ds_read_b128 v[208:211], v167 offset:55296
	ds_read_b128 v[212:215], v167 offset:56320
	s_add_u32 s100, s46, 0x80
	s_addc_u32 s101, s47, 0
	global_load_lds_dwordx4 v2, s[100:101]
	s_add_i32 m0, s12, 0x2000
	s_add_u32 s12, s46, 0x80080
	s_addc_u32 s13, s47, 0
	s_add_i32 s14, s15, s56
	s_add_u32 s100, s46, 0x80
	s_addc_u32 s101, s47, 0
	global_load_lds_dwordx4 v0, s[100:101]
	s_mov_b32 m0, s14
	s_nop 0
	global_load_lds_dwordx4 v2, s[12:13]
	s_add_i32 m0, s14, 0x2000
	s_nop 0
	global_load_lds_dwordx4 v0, s[12:13]
	s_mov_b32 m0, s64
	s_nop 0
	s_add_u32 s100, s48, 0x80
	s_addc_u32 s101, s49, 0
	global_load_lds_dwordx4 v134, s[100:101]
	s_mov_b32 m0, s65
	s_nop 0
	s_add_u32 s100, s48, 0x80
	s_addc_u32 s101, s49, 0
	global_load_lds_dwordx4 v132, s[100:101]
	s_add_i32 s11, s11, 2
	s_add_u32 s9, s9, 0x100
	s_addc_u32 s10, s10, 0
	s_add_u32 s44, s44, 0x100
	s_addc_u32 s45, s45, 0
	s_add_u32 s12, s44, 0xfff80080
	s_addc_u32 s13, s45, -1
	s_cmp_eq_u32 s11, 28
	s_cselect_b32 s49, s5, s13
	s_cselect_b32 s48, s6, s12
	s_cselect_b32 s47, s7, s10
	s_cselect_b32 s46, s8, s9
	s_waitcnt vmcnt(8) lgkmcnt(0)
	s_barrier
	s_setprio 1
	v_mfma_f32_16x16x32_bf16 v[64:67], v[142:145], v[184:187], v[64:67]
	v_mfma_f32_16x16x32_bf16 v[56:59], v[150:153], v[184:187], v[56:59]
	v_mfma_f32_16x16x32_bf16 v[48:51], v[142:145], v[192:195], v[48:51]
	v_mfma_f32_16x16x32_bf16 v[40:43], v[150:153], v[192:195], v[40:43]
	v_mfma_f32_16x16x32_bf16 v[32:35], v[142:145], v[200:203], v[32:35]
	v_mfma_f32_16x16x32_bf16 v[24:27], v[150:153], v[200:203], v[24:27]
	v_mfma_f32_16x16x32_bf16 v[16:19], v[142:145], v[208:211], v[16:19]
	v_mfma_f32_16x16x32_bf16 v[8:11], v[150:153], v[208:211], v[8:11]
	v_mfma_f32_16x16x32_bf16 v[64:67], v[146:149], v[188:191], v[64:67]
	v_mfma_f32_16x16x32_bf16 v[56:59], v[154:157], v[188:191], v[56:59]
	v_mfma_f32_16x16x32_bf16 v[48:51], v[146:149], v[196:199], v[48:51]
	v_mfma_f32_16x16x32_bf16 v[40:43], v[154:157], v[196:199], v[40:43]
	v_mfma_f32_16x16x32_bf16 v[32:35], v[146:149], v[204:207], v[32:35]
	v_mfma_f32_16x16x32_bf16 v[24:27], v[154:157], v[204:207], v[24:27]
	v_mfma_f32_16x16x32_bf16 v[16:19], v[146:149], v[212:215], v[16:19]
	v_mfma_f32_16x16x32_bf16 v[8:11], v[154:157], v[212:215], v[8:11]
	v_mfma_f32_16x16x32_bf16 v[60:63], v[168:171], v[184:187], v[60:63]
	v_mfma_f32_16x16x32_bf16 v[52:55], v[176:179], v[184:187], v[52:55]
	v_mfma_f32_16x16x32_bf16 v[44:47], v[168:171], v[192:195], v[44:47]
	v_mfma_f32_16x16x32_bf16 v[36:39], v[176:179], v[192:195], v[36:39]
	v_mfma_f32_16x16x32_bf16 v[28:31], v[168:171], v[200:203], v[28:31]
	v_mfma_f32_16x16x32_bf16 v[20:23], v[176:179], v[200:203], v[20:23]
	v_mfma_f32_16x16x32_bf16 v[12:15], v[168:171], v[208:211], v[12:15]
	v_mfma_f32_16x16x32_bf16 v[4:7], v[176:179], v[208:211], v[4:7]
	v_mfma_f32_16x16x32_bf16 v[60:63], v[172:175], v[188:191], v[60:63]
	v_mfma_f32_16x16x32_bf16 v[52:55], v[180:183], v[188:191], v[52:55]
	v_mfma_f32_16x16x32_bf16 v[44:47], v[172:175], v[196:199], v[44:47]
	v_mfma_f32_16x16x32_bf16 v[36:39], v[180:183], v[196:199], v[36:39]
	v_mfma_f32_16x16x32_bf16 v[28:31], v[172:175], v[204:207], v[28:31]
	v_mfma_f32_16x16x32_bf16 v[20:23], v[180:183], v[204:207], v[20:23]
	v_mfma_f32_16x16x32_bf16 v[12:15], v[172:175], v[212:215], v[12:15]
	v_mfma_f32_16x16x32_bf16 v[4:7], v[180:183], v[212:215], v[4:7]
	s_barrier
	s_setprio 0
.LBB0_1066:
	s_add_i32 s14, 0, 0x10000
	s_add_i32 s15, 0, 0x14000
	ds_read_b128 v[142:145], v133
	ds_read_b128 v[146:149], v133 offset:1024
	ds_read_b128 v[150:153], v133 offset:2048
	ds_read_b128 v[154:157], v133 offset:3072
	ds_read_b128 v[168:171], v133 offset:16384
	ds_read_b128 v[172:175], v133 offset:17408
	ds_read_b128 v[176:179], v133 offset:18432
	ds_read_b128 v[180:183], v133 offset:19456
	s_add_i32 m0, s60, 0xc000
	ds_read_b128 v[184:187], v167
	ds_read_b128 v[188:191], v167 offset:1024
	ds_read_b128 v[192:195], v167 offset:2048
	ds_read_b128 v[196:199], v167 offset:3072
	ds_read_b128 v[200:203], v167 offset:4096
	ds_read_b128 v[204:207], v167 offset:5120
	ds_read_b128 v[208:211], v167 offset:6144
	ds_read_b128 v[212:215], v167 offset:7168
	global_load_lds_dwordx4 v140, s[44:45]
	s_add_i32 m0, s60, 0xe000
	s_nop 0
	global_load_lds_dwordx4 v138, s[44:45]
	s_waitcnt vmcnt(8) lgkmcnt(0)
	s_barrier
	s_setprio 1
	v_mfma_f32_16x16x32_bf16 v[124:127], v[142:145], v[184:187], v[124:127]
	v_mfma_f32_16x16x32_bf16 v[120:123], v[150:153], v[184:187], v[120:123]
	v_mfma_f32_16x16x32_bf16 v[112:115], v[142:145], v[192:195], v[112:115]
	v_mfma_f32_16x16x32_bf16 v[104:107], v[150:153], v[192:195], v[104:107]
	v_mfma_f32_16x16x32_bf16 v[96:99], v[142:145], v[200:203], v[96:99]
	v_mfma_f32_16x16x32_bf16 v[88:91], v[150:153], v[200:203], v[88:91]
	v_mfma_f32_16x16x32_bf16 v[80:83], v[142:145], v[208:211], v[80:83]
	v_mfma_f32_16x16x32_bf16 v[72:75], v[150:153], v[208:211], v[72:75]
	v_mfma_f32_16x16x32_bf16 v[124:127], v[146:149], v[188:191], v[124:127]
	v_mfma_f32_16x16x32_bf16 v[120:123], v[154:157], v[188:191], v[120:123]
	v_mfma_f32_16x16x32_bf16 v[112:115], v[146:149], v[196:199], v[112:115]
	v_mfma_f32_16x16x32_bf16 v[104:107], v[154:157], v[196:199], v[104:107]
	v_mfma_f32_16x16x32_bf16 v[96:99], v[146:149], v[204:207], v[96:99]
	v_mfma_f32_16x16x32_bf16 v[88:91], v[154:157], v[204:207], v[88:91]
	v_mfma_f32_16x16x32_bf16 v[80:83], v[146:149], v[212:215], v[80:83]
	v_mfma_f32_16x16x32_bf16 v[72:75], v[154:157], v[212:215], v[72:75]
	v_mfma_f32_16x16x32_bf16 v[128:131], v[168:171], v[184:187], v[128:131]
	v_mfma_f32_16x16x32_bf16 v[116:119], v[176:179], v[184:187], v[116:119]
	v_mfma_f32_16x16x32_bf16 v[108:111], v[168:171], v[192:195], v[108:111]
	v_mfma_f32_16x16x32_bf16 v[100:103], v[176:179], v[192:195], v[100:103]
	v_mfma_f32_16x16x32_bf16 v[92:95], v[168:171], v[200:203], v[92:95]
	v_mfma_f32_16x16x32_bf16 v[84:87], v[176:179], v[200:203], v[84:87]
	v_mfma_f32_16x16x32_bf16 v[76:79], v[168:171], v[208:211], v[76:79]
	v_mfma_f32_16x16x32_bf16 v[68:71], v[176:179], v[208:211], v[68:71]
	v_mfma_f32_16x16x32_bf16 v[128:131], v[172:175], v[188:191], v[128:131]
	v_mfma_f32_16x16x32_bf16 v[116:119], v[180:183], v[188:191], v[116:119]
	v_mfma_f32_16x16x32_bf16 v[108:111], v[172:175], v[196:199], v[108:111]
	v_mfma_f32_16x16x32_bf16 v[100:103], v[180:183], v[196:199], v[100:103]
	v_mfma_f32_16x16x32_bf16 v[92:95], v[172:175], v[204:207], v[92:95]
	v_mfma_f32_16x16x32_bf16 v[84:87], v[180:183], v[204:207], v[84:87]
	v_mfma_f32_16x16x32_bf16 v[76:79], v[172:175], v[212:215], v[76:79]
	v_mfma_f32_16x16x32_bf16 v[68:71], v[180:183], v[212:215], v[68:71]
	s_barrier
	s_setprio 0
	s_add_i32 s12, s14, s56
	s_mov_b32 m0, s12
	ds_read_b128 v[184:187], v167 offset:16384
	ds_read_b128 v[188:191], v167 offset:17408
	ds_read_b128 v[192:195], v167 offset:18432
	ds_read_b128 v[196:199], v167 offset:19456
	ds_read_b128 v[200:203], v167 offset:20480
	ds_read_b128 v[204:207], v167 offset:21504
	ds_read_b128 v[208:211], v167 offset:22528
	ds_read_b128 v[212:215], v167 offset:23552
	global_load_lds_dwordx4 v2, s[46:47]
	s_add_i32 m0, s12, 0x2000
	s_add_u32 s12, s46, 0x80000
	s_addc_u32 s13, s47, 0
	s_add_i32 s14, s15, s56
	global_load_lds_dwordx4 v0, s[46:47]
	s_mov_b32 m0, s14
	s_nop 0
	global_load_lds_dwordx4 v2, s[12:13]
	s_add_i32 m0, s14, 0x2000
	s_nop 0
	global_load_lds_dwordx4 v0, s[12:13]
	s_mov_b32 m0, s60
	s_nop 0
	global_load_lds_dwordx4 v134, s[48:49]
	s_mov_b32 m0, s61
	s_nop 0
	global_load_lds_dwordx4 v132, s[48:49]
	s_waitcnt vmcnt(8) lgkmcnt(0)
	s_barrier
	s_setprio 1
	v_mfma_f32_16x16x32_bf16 v[64:67], v[142:145], v[184:187], v[64:67]
	v_mfma_f32_16x16x32_bf16 v[56:59], v[150:153], v[184:187], v[56:59]
	v_mfma_f32_16x16x32_bf16 v[48:51], v[142:145], v[192:195], v[48:51]
	v_mfma_f32_16x16x32_bf16 v[40:43], v[150:153], v[192:195], v[40:43]
	v_mfma_f32_16x16x32_bf16 v[32:35], v[142:145], v[200:203], v[32:35]
	v_mfma_f32_16x16x32_bf16 v[24:27], v[150:153], v[200:203], v[24:27]
	v_mfma_f32_16x16x32_bf16 v[16:19], v[142:145], v[208:211], v[16:19]
	v_mfma_f32_16x16x32_bf16 v[8:11], v[150:153], v[208:211], v[8:11]
	v_mfma_f32_16x16x32_bf16 v[64:67], v[146:149], v[188:191], v[64:67]
	v_mfma_f32_16x16x32_bf16 v[56:59], v[154:157], v[188:191], v[56:59]
	v_mfma_f32_16x16x32_bf16 v[48:51], v[146:149], v[196:199], v[48:51]
	v_mfma_f32_16x16x32_bf16 v[40:43], v[154:157], v[196:199], v[40:43]
	v_mfma_f32_16x16x32_bf16 v[32:35], v[146:149], v[204:207], v[32:35]
	v_mfma_f32_16x16x32_bf16 v[24:27], v[154:157], v[204:207], v[24:27]
	v_mfma_f32_16x16x32_bf16 v[16:19], v[146:149], v[212:215], v[16:19]
	v_mfma_f32_16x16x32_bf16 v[8:11], v[154:157], v[212:215], v[8:11]
	v_mfma_f32_16x16x32_bf16 v[60:63], v[168:171], v[184:187], v[60:63]
	v_mfma_f32_16x16x32_bf16 v[52:55], v[176:179], v[184:187], v[52:55]
	v_mfma_f32_16x16x32_bf16 v[44:47], v[168:171], v[192:195], v[44:47]
	v_mfma_f32_16x16x32_bf16 v[36:39], v[176:179], v[192:195], v[36:39]
	v_mfma_f32_16x16x32_bf16 v[28:31], v[168:171], v[200:203], v[28:31]
	v_mfma_f32_16x16x32_bf16 v[20:23], v[176:179], v[200:203], v[20:23]
	v_mfma_f32_16x16x32_bf16 v[12:15], v[168:171], v[208:211], v[12:15]
	v_mfma_f32_16x16x32_bf16 v[4:7], v[176:179], v[208:211], v[4:7]
	v_mfma_f32_16x16x32_bf16 v[60:63], v[172:175], v[188:191], v[60:63]
	v_mfma_f32_16x16x32_bf16 v[52:55], v[180:183], v[188:191], v[52:55]
	v_mfma_f32_16x16x32_bf16 v[44:47], v[172:175], v[196:199], v[44:47]
	v_mfma_f32_16x16x32_bf16 v[36:39], v[180:183], v[196:199], v[36:39]
	v_mfma_f32_16x16x32_bf16 v[28:31], v[172:175], v[204:207], v[28:31]
	v_mfma_f32_16x16x32_bf16 v[20:23], v[180:183], v[204:207], v[20:23]
	v_mfma_f32_16x16x32_bf16 v[12:15], v[172:175], v[212:215], v[12:15]
	v_mfma_f32_16x16x32_bf16 v[4:7], v[180:183], v[212:215], v[4:7]
	s_barrier
	s_setprio 0
	s_add_i32 s14, 0, 0x18000
	s_add_i32 s15, 0, 0x1c000
	ds_read_b128 v[142:145], v133 offset:32768
	ds_read_b128 v[146:149], v133 offset:33792
	ds_read_b128 v[150:153], v133 offset:34816
	ds_read_b128 v[154:157], v133 offset:35840
	ds_read_b128 v[168:171], v133 offset:49152
	ds_read_b128 v[172:175], v133 offset:50176
	ds_read_b128 v[176:179], v133 offset:51200
	ds_read_b128 v[180:183], v133 offset:52224
	s_add_u32 s12, s48, 0x80000
	s_addc_u32 s13, s49, 0
	s_mov_b32 m0, s62
	ds_read_b128 v[184:187], v167 offset:32768
	ds_read_b128 v[188:191], v167 offset:33792
	ds_read_b128 v[192:195], v167 offset:34816
	ds_read_b128 v[196:199], v167 offset:35840
	ds_read_b128 v[200:203], v167 offset:36864
	ds_read_b128 v[204:207], v167 offset:37888
	ds_read_b128 v[208:211], v167 offset:38912
	ds_read_b128 v[212:215], v167 offset:39936
	global_load_lds_dwordx4 v134, s[12:13]
	s_mov_b32 m0, s63
	s_nop 0
	global_load_lds_dwordx4 v132, s[12:13]
	s_waitcnt vmcnt(8) lgkmcnt(0)
	s_barrier
	s_setprio 1
	v_mfma_f32_16x16x32_bf16 v[124:127], v[142:145], v[184:187], v[124:127]
	v_mfma_f32_16x16x32_bf16 v[120:123], v[150:153], v[184:187], v[120:123]
	v_mfma_f32_16x16x32_bf16 v[112:115], v[142:145], v[192:195], v[112:115]
	v_mfma_f32_16x16x32_bf16 v[104:107], v[150:153], v[192:195], v[104:107]
	v_mfma_f32_16x16x32_bf16 v[96:99], v[142:145], v[200:203], v[96:99]
	v_mfma_f32_16x16x32_bf16 v[88:91], v[150:153], v[200:203], v[88:91]
	v_mfma_f32_16x16x32_bf16 v[80:83], v[142:145], v[208:211], v[80:83]
	v_mfma_f32_16x16x32_bf16 v[72:75], v[150:153], v[208:211], v[72:75]
	v_mfma_f32_16x16x32_bf16 v[124:127], v[146:149], v[188:191], v[124:127]
	v_mfma_f32_16x16x32_bf16 v[120:123], v[154:157], v[188:191], v[120:123]
	v_mfma_f32_16x16x32_bf16 v[112:115], v[146:149], v[196:199], v[112:115]
	v_mfma_f32_16x16x32_bf16 v[104:107], v[154:157], v[196:199], v[104:107]
	v_mfma_f32_16x16x32_bf16 v[96:99], v[146:149], v[204:207], v[96:99]
	v_mfma_f32_16x16x32_bf16 v[88:91], v[154:157], v[204:207], v[88:91]
	v_mfma_f32_16x16x32_bf16 v[80:83], v[146:149], v[212:215], v[80:83]
	v_mfma_f32_16x16x32_bf16 v[72:75], v[154:157], v[212:215], v[72:75]
	v_mfma_f32_16x16x32_bf16 v[128:131], v[168:171], v[184:187], v[128:131]
	v_mfma_f32_16x16x32_bf16 v[116:119], v[176:179], v[184:187], v[116:119]
	v_mfma_f32_16x16x32_bf16 v[108:111], v[168:171], v[192:195], v[108:111]
	v_mfma_f32_16x16x32_bf16 v[100:103], v[176:179], v[192:195], v[100:103]
	v_mfma_f32_16x16x32_bf16 v[92:95], v[168:171], v[200:203], v[92:95]
	v_mfma_f32_16x16x32_bf16 v[84:87], v[176:179], v[200:203], v[84:87]
	v_mfma_f32_16x16x32_bf16 v[76:79], v[168:171], v[208:211], v[76:79]
	v_mfma_f32_16x16x32_bf16 v[68:71], v[176:179], v[208:211], v[68:71]
	v_mfma_f32_16x16x32_bf16 v[128:131], v[172:175], v[188:191], v[128:131]
	v_mfma_f32_16x16x32_bf16 v[116:119], v[180:183], v[188:191], v[116:119]
	v_mfma_f32_16x16x32_bf16 v[108:111], v[172:175], v[196:199], v[108:111]
	v_mfma_f32_16x16x32_bf16 v[100:103], v[180:183], v[196:199], v[100:103]
	v_mfma_f32_16x16x32_bf16 v[92:95], v[172:175], v[204:207], v[92:95]
	v_mfma_f32_16x16x32_bf16 v[84:87], v[180:183], v[204:207], v[84:87]
	v_mfma_f32_16x16x32_bf16 v[76:79], v[172:175], v[212:215], v[76:79]
	v_mfma_f32_16x16x32_bf16 v[68:71], v[180:183], v[212:215], v[68:71]
	s_barrier
	s_setprio 0
	s_add_i32 s12, s14, s56
	s_mov_b32 m0, s12
	ds_read_b128 v[184:187], v167 offset:49152
	ds_read_b128 v[188:191], v167 offset:50176
	ds_read_b128 v[192:195], v167 offset:51200
	ds_read_b128 v[196:199], v167 offset:52224
	ds_read_b128 v[200:203], v167 offset:53248
	ds_read_b128 v[204:207], v167 offset:54272
	ds_read_b128 v[208:211], v167 offset:55296
	ds_read_b128 v[212:215], v167 offset:56320
	s_add_u32 s100, s46, 0x80
	s_addc_u32 s101, s47, 0
	global_load_lds_dwordx4 v2, s[100:101]
	s_add_i32 m0, s12, 0x2000
	s_add_u32 s12, s46, 0x80080
	s_addc_u32 s13, s47, 0
	s_add_i32 s14, s15, s56
	s_add_u32 s100, s46, 0x80
	s_addc_u32 s101, s47, 0
	global_load_lds_dwordx4 v0, s[100:101]
	s_mov_b32 m0, s14
	s_nop 0
	global_load_lds_dwordx4 v2, s[12:13]
	s_add_i32 m0, s14, 0x2000
	s_nop 0
	global_load_lds_dwordx4 v0, s[12:13]
	s_mov_b32 m0, s64
	s_nop 0
	s_add_u32 s100, s48, 0x80
	s_addc_u32 s101, s49, 0
	global_load_lds_dwordx4 v134, s[100:101]
	s_mov_b32 m0, s65
	s_nop 0
	s_add_u32 s100, s48, 0x80
	s_addc_u32 s101, s49, 0
	global_load_lds_dwordx4 v132, s[100:101]
	s_add_i32 s11, s11, 2
	s_add_u32 s9, s9, 0x100
	s_addc_u32 s10, s10, 0
	s_add_u32 s44, s44, 0x100
	s_addc_u32 s45, s45, 0
	s_add_u32 s12, s44, 0xfff80080
	s_addc_u32 s13, s45, -1
	s_cmp_eq_u32 s11, 28
	s_cselect_b32 s49, s5, s13
	s_cselect_b32 s48, s6, s12
	s_cselect_b32 s47, s7, s10
	s_cselect_b32 s46, s8, s9
	s_cmp_gt_u32 s11, 29
	s_waitcnt vmcnt(8) lgkmcnt(0)
	s_barrier
	s_setprio 1
	v_mfma_f32_16x16x32_bf16 v[64:67], v[142:145], v[184:187], v[64:67]
	v_mfma_f32_16x16x32_bf16 v[56:59], v[150:153], v[184:187], v[56:59]
	v_mfma_f32_16x16x32_bf16 v[48:51], v[142:145], v[192:195], v[48:51]
	v_mfma_f32_16x16x32_bf16 v[40:43], v[150:153], v[192:195], v[40:43]
	v_mfma_f32_16x16x32_bf16 v[32:35], v[142:145], v[200:203], v[32:35]
	v_mfma_f32_16x16x32_bf16 v[24:27], v[150:153], v[200:203], v[24:27]
	v_mfma_f32_16x16x32_bf16 v[16:19], v[142:145], v[208:211], v[16:19]
	v_mfma_f32_16x16x32_bf16 v[8:11], v[150:153], v[208:211], v[8:11]
	v_mfma_f32_16x16x32_bf16 v[64:67], v[146:149], v[188:191], v[64:67]
	v_mfma_f32_16x16x32_bf16 v[56:59], v[154:157], v[188:191], v[56:59]
	v_mfma_f32_16x16x32_bf16 v[48:51], v[146:149], v[196:199], v[48:51]
	v_mfma_f32_16x16x32_bf16 v[40:43], v[154:157], v[196:199], v[40:43]
	v_mfma_f32_16x16x32_bf16 v[32:35], v[146:149], v[204:207], v[32:35]
	v_mfma_f32_16x16x32_bf16 v[24:27], v[154:157], v[204:207], v[24:27]
	v_mfma_f32_16x16x32_bf16 v[16:19], v[146:149], v[212:215], v[16:19]
	v_mfma_f32_16x16x32_bf16 v[8:11], v[154:157], v[212:215], v[8:11]
	v_mfma_f32_16x16x32_bf16 v[60:63], v[168:171], v[184:187], v[60:63]
	v_mfma_f32_16x16x32_bf16 v[52:55], v[176:179], v[184:187], v[52:55]
	v_mfma_f32_16x16x32_bf16 v[44:47], v[168:171], v[192:195], v[44:47]
	v_mfma_f32_16x16x32_bf16 v[36:39], v[176:179], v[192:195], v[36:39]
	v_mfma_f32_16x16x32_bf16 v[28:31], v[168:171], v[200:203], v[28:31]
	v_mfma_f32_16x16x32_bf16 v[20:23], v[176:179], v[200:203], v[20:23]
	v_mfma_f32_16x16x32_bf16 v[12:15], v[168:171], v[208:211], v[12:15]
	v_mfma_f32_16x16x32_bf16 v[4:7], v[176:179], v[208:211], v[4:7]
	v_mfma_f32_16x16x32_bf16 v[60:63], v[172:175], v[188:191], v[60:63]
	v_mfma_f32_16x16x32_bf16 v[52:55], v[180:183], v[188:191], v[52:55]
	v_mfma_f32_16x16x32_bf16 v[44:47], v[172:175], v[196:199], v[44:47]
	v_mfma_f32_16x16x32_bf16 v[36:39], v[180:183], v[196:199], v[36:39]
	v_mfma_f32_16x16x32_bf16 v[28:31], v[172:175], v[204:207], v[28:31]
	v_mfma_f32_16x16x32_bf16 v[20:23], v[180:183], v[204:207], v[20:23]
	v_mfma_f32_16x16x32_bf16 v[12:15], v[172:175], v[212:215], v[12:15]
	v_mfma_f32_16x16x32_bf16 v[4:7], v[180:183], v[212:215], v[4:7]
	s_barrier
	s_setprio 0
	s_cbranch_scc0 .LBB0_1066
	s_and_b64 vcc, exec, s[22:23]
	s_cbranch_vccz .LBB0_1069
	s_nop 0

.LBB0_1133:
	s_add_u32 s5, s40, 0x100
	s_addc_u32 s6, s41, 0
	s_mov_b32 s7, -2
	s_waitcnt lgkmcnt(0)
	s_add_u32 s40, s38, 0x100
	s_addc_u32 s41, s39, 0
	s_add_i32 s8, 0, 0x10000
	s_cmpk_eq_i32 s7, 0x54
	s_cselect_b32 s45, s61, s41
	s_cselect_b32 s44, s60, s40
	s_cselect_b32 s43, s63, s6
	s_cselect_b32 s42, s62, s5
	s_add_i32 s10, 0, 0x14000
	v_add_u32_e32 v112, s8, v242
	v_add_u32_e32 v148, s10, v242
	ds_read_b128 v[92:95], v112
	ds_read_b128 v[100:103], v112 offset:1024
	ds_read_b128 v[108:111], v112 offset:2048
	ds_read_b128 v[112:115], v112 offset:3072
	ds_read_b128 v[116:119], v148
	ds_read_b128 v[128:131], v148 offset:1024
	ds_read_b128 v[140:143], v148 offset:2048
	ds_read_b128 v[148:151], v148 offset:3072
	v_lshl_add_u64 v[196:197], s[38:39], 0, v[222:223]
	s_add_i32 m0, s83, 0xc000
	ds_read_b128 v[160:163], v245
	ds_read_b128 v[168:171], v245 offset:1024
	ds_read_b128 v[172:175], v245 offset:2048
	ds_read_b128 v[176:179], v245 offset:3072
	ds_read_b128 v[180:183], v245 offset:4096
	ds_read_b128 v[184:187], v245 offset:5120
	ds_read_b128 v[188:191], v245 offset:6144
	ds_read_b128 v[192:195], v245 offset:7168
	global_load_lds_dwordx4 v[196:197], off
	v_lshl_add_u64 v[196:197], s[38:39], 0, v[220:221]
	s_add_i32 m0, s83, 0xe000
	s_nop 0
	global_load_lds_dwordx4 v[196:197], off
	s_waitcnt vmcnt(8) lgkmcnt(0)
	s_barrier
	s_setprio 1
	v_mfma_f32_16x16x32_bf16 v[164:167], v[92:95], v[160:163], 0
	v_mfma_f32_16x16x32_bf16 v[156:159], v[108:111], v[160:163], 0
	v_mfma_f32_16x16x32_bf16 v[136:139], v[92:95], v[172:175], 0
	v_mfma_f32_16x16x32_bf16 v[132:135], v[108:111], v[172:175], 0
	v_mfma_f32_16x16x32_bf16 v[104:107], v[92:95], v[180:183], 0
	v_mfma_f32_16x16x32_bf16 v[96:99], v[108:111], v[180:183], 0
	v_mfma_f32_16x16x32_bf16 v[80:83], v[92:95], v[188:191], 0
	v_mfma_f32_16x16x32_bf16 v[76:79], v[108:111], v[188:191], 0
	v_mfma_f32_16x16x32_bf16 v[164:167], v[100:103], v[168:171], v[164:167]
	v_mfma_f32_16x16x32_bf16 v[156:159], v[112:115], v[168:171], v[156:159]
	v_mfma_f32_16x16x32_bf16 v[136:139], v[100:103], v[176:179], v[136:139]
	v_mfma_f32_16x16x32_bf16 v[132:135], v[112:115], v[176:179], v[132:135]
	v_mfma_f32_16x16x32_bf16 v[104:107], v[100:103], v[184:187], v[104:107]
	v_mfma_f32_16x16x32_bf16 v[96:99], v[112:115], v[184:187], v[96:99]
	v_mfma_f32_16x16x32_bf16 v[80:83], v[100:103], v[192:195], v[80:83]
	v_mfma_f32_16x16x32_bf16 v[76:79], v[112:115], v[192:195], v[76:79]
	s_setprio 0
	s_setprio 1
	v_mfma_f32_16x16x32_bf16 v[152:155], v[116:119], v[160:163], 0
	v_mfma_f32_16x16x32_bf16 v[144:147], v[140:143], v[160:163], 0
	v_mfma_f32_16x16x32_bf16 v[124:127], v[116:119], v[172:175], 0
	v_mfma_f32_16x16x32_bf16 v[120:123], v[140:143], v[172:175], 0
	v_mfma_f32_16x16x32_bf16 v[88:91], v[116:119], v[180:183], 0
	v_mfma_f32_16x16x32_bf16 v[84:87], v[140:143], v[180:183], 0
	v_mfma_f32_16x16x32_bf16 v[72:75], v[116:119], v[188:191], 0
	v_mfma_f32_16x16x32_bf16 v[68:71], v[140:143], v[188:191], 0
	v_mfma_f32_16x16x32_bf16 v[152:155], v[128:131], v[168:171], v[152:155]
	v_mfma_f32_16x16x32_bf16 v[144:147], v[148:151], v[168:171], v[144:147]
	v_mfma_f32_16x16x32_bf16 v[124:127], v[128:131], v[176:179], v[124:127]
	v_mfma_f32_16x16x32_bf16 v[120:123], v[148:151], v[176:179], v[120:123]
	v_mfma_f32_16x16x32_bf16 v[88:91], v[128:131], v[184:187], v[88:91]
	v_mfma_f32_16x16x32_bf16 v[84:87], v[148:151], v[184:187], v[84:87]
	v_mfma_f32_16x16x32_bf16 v[72:75], v[128:131], v[192:195], v[72:75]
	v_mfma_f32_16x16x32_bf16 v[68:71], v[148:151], v[192:195], v[68:71]
	s_barrier
	s_setprio 0
	s_add_i32 s8, s8, s82
	v_lshl_add_u64 v[196:197], s[42:43], 0, v[2:3]
	s_mov_b32 m0, s8
	ds_read_b128 v[160:163], v245 offset:16384
	ds_read_b128 v[168:171], v245 offset:17408
	ds_read_b128 v[172:175], v245 offset:18432
	ds_read_b128 v[176:179], v245 offset:19456
	ds_read_b128 v[180:183], v245 offset:20480
	ds_read_b128 v[184:187], v245 offset:21504
	ds_read_b128 v[188:191], v245 offset:22528
	ds_read_b128 v[192:195], v245 offset:23552
	global_load_lds_dwordx4 v[196:197], off
	s_add_i32 m0, s8, 0x2000
	s_add_u32 s8, s42, 0x160000
	v_lshl_add_u64 v[198:199], s[42:43], 0, v[218:219]
	s_addc_u32 s9, s43, 0
	s_add_i32 s10, s10, s82
	global_load_lds_dwordx4 v[198:199], off
	v_lshl_add_u64 v[200:201], s[8:9], 0, v[2:3]
	s_mov_b32 m0, s10
	v_lshl_add_u64 v[202:203], s[44:45], 0, v[216:217]
	global_load_lds_dwordx4 v[200:201], off
	v_lshl_add_u64 v[200:201], s[8:9], 0, v[218:219]
	s_add_i32 m0, s10, 0x2000
	s_nop 0
	global_load_lds_dwordx4 v[200:201], off
	v_lshl_add_u64 v[200:201], s[44:45], 0, v[0:1]
	s_mov_b32 m0, s83
	s_nop 0
	global_load_lds_dwordx4 v[200:201], off
	s_mov_b32 m0, s84
	s_nop 0
	global_load_lds_dwordx4 v[202:203], off
	s_waitcnt vmcnt(8) lgkmcnt(0)
	s_barrier
	s_setprio 1
	v_mfma_f32_16x16x32_bf16 v[64:67], v[92:95], v[160:163], 0
	v_mfma_f32_16x16x32_bf16 v[60:63], v[108:111], v[160:163], 0
	v_mfma_f32_16x16x32_bf16 v[48:51], v[92:95], v[172:175], 0
	v_mfma_f32_16x16x32_bf16 v[44:47], v[108:111], v[172:175], 0
	v_mfma_f32_16x16x32_bf16 v[32:35], v[92:95], v[180:183], 0
	v_mfma_f32_16x16x32_bf16 v[28:31], v[108:111], v[180:183], 0
	v_mfma_f32_16x16x32_bf16 v[16:19], v[92:95], v[188:191], 0
	v_mfma_f32_16x16x32_bf16 v[12:15], v[108:111], v[188:191], 0
	v_mfma_f32_16x16x32_bf16 v[64:67], v[100:103], v[168:171], v[64:67]
	v_mfma_f32_16x16x32_bf16 v[60:63], v[112:115], v[168:171], v[60:63]
	v_mfma_f32_16x16x32_bf16 v[48:51], v[100:103], v[176:179], v[48:51]
	v_mfma_f32_16x16x32_bf16 v[44:47], v[112:115], v[176:179], v[44:47]
	v_mfma_f32_16x16x32_bf16 v[32:35], v[100:103], v[184:187], v[32:35]
	v_mfma_f32_16x16x32_bf16 v[28:31], v[112:115], v[184:187], v[28:31]
	v_mfma_f32_16x16x32_bf16 v[16:19], v[100:103], v[192:195], v[16:19]
	v_mfma_f32_16x16x32_bf16 v[12:15], v[112:115], v[192:195], v[12:15]
	s_setprio 0
	s_setprio 1
	v_mfma_f32_16x16x32_bf16 v[56:59], v[116:119], v[160:163], 0
	v_mfma_f32_16x16x32_bf16 v[52:55], v[140:143], v[160:163], 0
	v_mfma_f32_16x16x32_bf16 v[40:43], v[116:119], v[172:175], 0
	v_mfma_f32_16x16x32_bf16 v[36:39], v[140:143], v[172:175], 0
	v_mfma_f32_16x16x32_bf16 v[24:27], v[116:119], v[180:183], 0
	v_mfma_f32_16x16x32_bf16 v[20:23], v[140:143], v[180:183], 0
	v_mfma_f32_16x16x32_bf16 v[8:11], v[116:119], v[188:191], 0
	v_mfma_f32_16x16x32_bf16 v[4:7], v[140:143], v[188:191], 0
	v_mfma_f32_16x16x32_bf16 v[56:59], v[128:131], v[168:171], v[56:59]
	v_mfma_f32_16x16x32_bf16 v[52:55], v[148:151], v[168:171], v[52:55]
	v_mfma_f32_16x16x32_bf16 v[40:43], v[128:131], v[176:179], v[40:43]
	v_mfma_f32_16x16x32_bf16 v[36:39], v[148:151], v[176:179], v[36:39]
	v_mfma_f32_16x16x32_bf16 v[24:27], v[128:131], v[184:187], v[24:27]
	v_mfma_f32_16x16x32_bf16 v[20:23], v[148:151], v[184:187], v[20:23]
	v_mfma_f32_16x16x32_bf16 v[8:11], v[128:131], v[192:195], v[8:11]
	v_mfma_f32_16x16x32_bf16 v[4:7], v[148:151], v[192:195], v[4:7]
	s_barrier
	s_setprio 0
	s_add_i32 s10, 0, 0x18000
	s_add_i32 s11, 0, 0x1c000
	v_add_u32_e32 v112, s10, v242
	v_add_u32_e32 v148, s11, v242
	ds_read_b128 v[92:95], v112
	ds_read_b128 v[100:103], v112 offset:1024
	ds_read_b128 v[108:111], v112 offset:2048
	ds_read_b128 v[112:115], v112 offset:3072
	ds_read_b128 v[116:119], v148
	ds_read_b128 v[128:131], v148 offset:1024
	ds_read_b128 v[140:143], v148 offset:2048
	ds_read_b128 v[148:151], v148 offset:3072
	s_add_u32 s8, s44, 0x160000
	s_addc_u32 s9, s45, 0
	s_mov_b32 m0, s85
	v_lshl_add_u64 v[204:205], s[8:9], 0, v[0:1]
	ds_read_b128 v[160:163], v245 offset:32768
	ds_read_b128 v[168:171], v245 offset:33792
	ds_read_b128 v[172:175], v245 offset:34816
	ds_read_b128 v[176:179], v245 offset:35840
	ds_read_b128 v[180:183], v245 offset:36864
	ds_read_b128 v[184:187], v245 offset:37888
	ds_read_b128 v[188:191], v245 offset:38912
	ds_read_b128 v[192:195], v245 offset:39936
	global_load_lds_dwordx4 v[204:205], off
	v_lshl_add_u64 v[204:205], s[8:9], 0, v[216:217]
	s_mov_b32 m0, s87
	s_nop 0
	global_load_lds_dwordx4 v[204:205], off
	s_waitcnt vmcnt(8) lgkmcnt(0)
	s_barrier
	s_setprio 1
	v_mfma_f32_16x16x32_bf16 v[164:167], v[92:95], v[160:163], v[164:167]
	v_mfma_f32_16x16x32_bf16 v[156:159], v[108:111], v[160:163], v[156:159]
	v_mfma_f32_16x16x32_bf16 v[136:139], v[92:95], v[172:175], v[136:139]
	v_mfma_f32_16x16x32_bf16 v[132:135], v[108:111], v[172:175], v[132:135]
	v_mfma_f32_16x16x32_bf16 v[104:107], v[92:95], v[180:183], v[104:107]
	v_mfma_f32_16x16x32_bf16 v[96:99], v[108:111], v[180:183], v[96:99]
	v_mfma_f32_16x16x32_bf16 v[80:83], v[92:95], v[188:191], v[80:83]
	v_mfma_f32_16x16x32_bf16 v[76:79], v[108:111], v[188:191], v[76:79]
	v_mfma_f32_16x16x32_bf16 v[164:167], v[100:103], v[168:171], v[164:167]
	v_mfma_f32_16x16x32_bf16 v[156:159], v[112:115], v[168:171], v[156:159]
	v_mfma_f32_16x16x32_bf16 v[136:139], v[100:103], v[176:179], v[136:139]
	v_mfma_f32_16x16x32_bf16 v[132:135], v[112:115], v[176:179], v[132:135]
	v_mfma_f32_16x16x32_bf16 v[104:107], v[100:103], v[184:187], v[104:107]
	v_mfma_f32_16x16x32_bf16 v[96:99], v[112:115], v[184:187], v[96:99]
	v_mfma_f32_16x16x32_bf16 v[80:83], v[100:103], v[192:195], v[80:83]
	v_mfma_f32_16x16x32_bf16 v[76:79], v[112:115], v[192:195], v[76:79]
	s_setprio 0
	s_setprio 1
	v_mfma_f32_16x16x32_bf16 v[152:155], v[116:119], v[160:163], v[152:155]
	v_mfma_f32_16x16x32_bf16 v[144:147], v[140:143], v[160:163], v[144:147]
	v_mfma_f32_16x16x32_bf16 v[124:127], v[116:119], v[172:175], v[124:127]
	v_mfma_f32_16x16x32_bf16 v[120:123], v[140:143], v[172:175], v[120:123]
	v_mfma_f32_16x16x32_bf16 v[88:91], v[116:119], v[180:183], v[88:91]
	v_mfma_f32_16x16x32_bf16 v[84:87], v[140:143], v[180:183], v[84:87]
	v_mfma_f32_16x16x32_bf16 v[72:75], v[116:119], v[188:191], v[72:75]
	v_mfma_f32_16x16x32_bf16 v[68:71], v[140:143], v[188:191], v[68:71]
	v_mfma_f32_16x16x32_bf16 v[152:155], v[128:131], v[168:171], v[152:155]
	v_mfma_f32_16x16x32_bf16 v[144:147], v[148:151], v[168:171], v[144:147]
	v_mfma_f32_16x16x32_bf16 v[124:127], v[128:131], v[176:179], v[124:127]
	v_mfma_f32_16x16x32_bf16 v[120:123], v[148:151], v[176:179], v[120:123]
	v_mfma_f32_16x16x32_bf16 v[88:91], v[128:131], v[184:187], v[88:91]
	v_mfma_f32_16x16x32_bf16 v[84:87], v[148:151], v[184:187], v[84:87]
	v_mfma_f32_16x16x32_bf16 v[72:75], v[128:131], v[192:195], v[72:75]
	v_mfma_f32_16x16x32_bf16 v[68:71], v[148:151], v[192:195], v[68:71]
	s_barrier
	s_setprio 0
	s_add_i32 s8, s10, s82
	v_lshl_add_u64 v[196:197], v[196:197], 0, s[68:69]
	s_mov_b32 m0, s8
	ds_read_b128 v[160:163], v245 offset:49152
	ds_read_b128 v[168:171], v245 offset:50176
	ds_read_b128 v[172:175], v245 offset:51200
	ds_read_b128 v[176:179], v245 offset:52224
	ds_read_b128 v[180:183], v245 offset:53248
	ds_read_b128 v[184:187], v245 offset:54272
	ds_read_b128 v[188:191], v245 offset:55296
	ds_read_b128 v[192:195], v245 offset:56320
	global_load_lds_dwordx4 v[196:197], off
	s_add_i32 m0, s8, 0x2000
	s_add_u32 s8, s42, 0x160080
	v_lshl_add_u64 v[196:197], v[198:199], 0, s[68:69]
	s_addc_u32 s9, s43, 0
	s_add_i32 s10, s11, s82
	global_load_lds_dwordx4 v[196:197], off
	v_lshl_add_u64 v[196:197], s[8:9], 0, v[2:3]
	s_mov_b32 m0, s10
	s_nop 0
	global_load_lds_dwordx4 v[196:197], off
	v_lshl_add_u64 v[196:197], s[8:9], 0, v[218:219]
	s_add_i32 m0, s10, 0x2000
	s_nop 0
	global_load_lds_dwordx4 v[196:197], off
	v_lshl_add_u64 v[196:197], v[200:201], 0, s[68:69]
	s_mov_b32 m0, s72
	s_nop 0
	global_load_lds_dwordx4 v[196:197], off
	v_lshl_add_u64 v[196:197], v[202:203], 0, s[68:69]
	s_mov_b32 m0, s88
	s_nop 0
	global_load_lds_dwordx4 v[196:197], off
	s_waitcnt vmcnt(8) lgkmcnt(0)
	s_barrier
	s_setprio 1
	v_mfma_f32_16x16x32_bf16 v[64:67], v[92:95], v[160:163], v[64:67]
	v_mfma_f32_16x16x32_bf16 v[60:63], v[108:111], v[160:163], v[60:63]
	v_mfma_f32_16x16x32_bf16 v[48:51], v[92:95], v[172:175], v[48:51]
	v_mfma_f32_16x16x32_bf16 v[44:47], v[108:111], v[172:175], v[44:47]
	v_mfma_f32_16x16x32_bf16 v[32:35], v[92:95], v[180:183], v[32:35]
	v_mfma_f32_16x16x32_bf16 v[28:31], v[108:111], v[180:183], v[28:31]
	v_mfma_f32_16x16x32_bf16 v[16:19], v[92:95], v[188:191], v[16:19]
	v_mfma_f32_16x16x32_bf16 v[12:15], v[108:111], v[188:191], v[12:15]
	v_mfma_f32_16x16x32_bf16 v[64:67], v[100:103], v[168:171], v[64:67]
	v_mfma_f32_16x16x32_bf16 v[60:63], v[112:115], v[168:171], v[60:63]
	v_mfma_f32_16x16x32_bf16 v[48:51], v[100:103], v[176:179], v[48:51]
	v_mfma_f32_16x16x32_bf16 v[44:47], v[112:115], v[176:179], v[44:47]
	v_mfma_f32_16x16x32_bf16 v[32:35], v[100:103], v[184:187], v[32:35]
	v_mfma_f32_16x16x32_bf16 v[28:31], v[112:115], v[184:187], v[28:31]
	v_mfma_f32_16x16x32_bf16 v[16:19], v[100:103], v[192:195], v[16:19]
	v_mfma_f32_16x16x32_bf16 v[12:15], v[112:115], v[192:195], v[12:15]
	s_setprio 0
	s_setprio 1
	v_mfma_f32_16x16x32_bf16 v[56:59], v[116:119], v[160:163], v[56:59]
	v_mfma_f32_16x16x32_bf16 v[52:55], v[140:143], v[160:163], v[52:55]
	v_mfma_f32_16x16x32_bf16 v[40:43], v[116:119], v[172:175], v[40:43]
	v_mfma_f32_16x16x32_bf16 v[36:39], v[140:143], v[172:175], v[36:39]
	v_mfma_f32_16x16x32_bf16 v[24:27], v[116:119], v[180:183], v[24:27]
	v_mfma_f32_16x16x32_bf16 v[20:23], v[140:143], v[180:183], v[20:23]
	v_mfma_f32_16x16x32_bf16 v[8:11], v[116:119], v[188:191], v[8:11]
	v_mfma_f32_16x16x32_bf16 v[4:7], v[140:143], v[188:191], v[4:7]
	v_mfma_f32_16x16x32_bf16 v[56:59], v[128:131], v[168:171], v[56:59]
	v_mfma_f32_16x16x32_bf16 v[52:55], v[148:151], v[168:171], v[52:55]
	v_mfma_f32_16x16x32_bf16 v[40:43], v[128:131], v[176:179], v[40:43]
	v_mfma_f32_16x16x32_bf16 v[36:39], v[148:151], v[176:179], v[36:39]
	v_mfma_f32_16x16x32_bf16 v[24:27], v[128:131], v[184:187], v[24:27]
	v_mfma_f32_16x16x32_bf16 v[20:23], v[148:151], v[184:187], v[20:23]
	v_mfma_f32_16x16x32_bf16 v[8:11], v[128:131], v[192:195], v[8:11]
	v_mfma_f32_16x16x32_bf16 v[4:7], v[148:151], v[192:195], v[4:7]
	s_barrier
	s_setprio 0
	s_add_i32 s7, s7, 2
	s_add_u32 s5, s5, 0x100
	s_addc_u32 s6, s6, 0
	s_cmpk_gt_u32 s7, 0x55
	s_mov_b64 s[38:39], s[40:41]
.LBB0_1134:
	s_add_u32 s40, s38, 0x100
	s_addc_u32 s41, s39, 0
	s_add_i32 s8, 0, 0x10000
	s_cmpk_eq_i32 s7, 0x54
	s_cselect_b32 s45, s61, s41
	s_cselect_b32 s44, s60, s40
	s_cselect_b32 s43, s63, s6
	s_cselect_b32 s42, s62, s5
	s_add_i32 s10, 0, 0x14000
	v_add_u32_e32 v112, s8, v242
	v_add_u32_e32 v148, s10, v242
	ds_read_b128 v[92:95], v112
	ds_read_b128 v[100:103], v112 offset:1024
	ds_read_b128 v[108:111], v112 offset:2048
	ds_read_b128 v[112:115], v112 offset:3072
	ds_read_b128 v[116:119], v148
	ds_read_b128 v[128:131], v148 offset:1024
	ds_read_b128 v[140:143], v148 offset:2048
	ds_read_b128 v[148:151], v148 offset:3072
	v_lshl_add_u64 v[196:197], s[38:39], 0, v[222:223]
	s_add_i32 m0, s83, 0xc000
	ds_read_b128 v[160:163], v245
	ds_read_b128 v[168:171], v245 offset:1024
	ds_read_b128 v[172:175], v245 offset:2048
	ds_read_b128 v[176:179], v245 offset:3072
	ds_read_b128 v[180:183], v245 offset:4096
	ds_read_b128 v[184:187], v245 offset:5120
	ds_read_b128 v[188:191], v245 offset:6144
	ds_read_b128 v[192:195], v245 offset:7168
	global_load_lds_dwordx4 v[196:197], off
	v_lshl_add_u64 v[196:197], s[38:39], 0, v[220:221]
	s_add_i32 m0, s83, 0xe000
	s_nop 0
	global_load_lds_dwordx4 v[196:197], off
	s_waitcnt vmcnt(8) lgkmcnt(0)
	s_barrier
	s_setprio 1
	v_mfma_f32_16x16x32_bf16 v[164:167], v[92:95], v[160:163], v[164:167]
	v_mfma_f32_16x16x32_bf16 v[156:159], v[108:111], v[160:163], v[156:159]
	v_mfma_f32_16x16x32_bf16 v[136:139], v[92:95], v[172:175], v[136:139]
	v_mfma_f32_16x16x32_bf16 v[132:135], v[108:111], v[172:175], v[132:135]
	v_mfma_f32_16x16x32_bf16 v[104:107], v[92:95], v[180:183], v[104:107]
	v_mfma_f32_16x16x32_bf16 v[96:99], v[108:111], v[180:183], v[96:99]
	v_mfma_f32_16x16x32_bf16 v[80:83], v[92:95], v[188:191], v[80:83]
	v_mfma_f32_16x16x32_bf16 v[76:79], v[108:111], v[188:191], v[76:79]
	v_mfma_f32_16x16x32_bf16 v[164:167], v[100:103], v[168:171], v[164:167]
	v_mfma_f32_16x16x32_bf16 v[156:159], v[112:115], v[168:171], v[156:159]
	v_mfma_f32_16x16x32_bf16 v[136:139], v[100:103], v[176:179], v[136:139]
	v_mfma_f32_16x16x32_bf16 v[132:135], v[112:115], v[176:179], v[132:135]
	v_mfma_f32_16x16x32_bf16 v[104:107], v[100:103], v[184:187], v[104:107]
	v_mfma_f32_16x16x32_bf16 v[96:99], v[112:115], v[184:187], v[96:99]
	v_mfma_f32_16x16x32_bf16 v[80:83], v[100:103], v[192:195], v[80:83]
	v_mfma_f32_16x16x32_bf16 v[76:79], v[112:115], v[192:195], v[76:79]
	s_setprio 0
	s_setprio 1
	v_mfma_f32_16x16x32_bf16 v[152:155], v[116:119], v[160:163], v[152:155]
	v_mfma_f32_16x16x32_bf16 v[144:147], v[140:143], v[160:163], v[144:147]
	v_mfma_f32_16x16x32_bf16 v[124:127], v[116:119], v[172:175], v[124:127]
	v_mfma_f32_16x16x32_bf16 v[120:123], v[140:143], v[172:175], v[120:123]
	v_mfma_f32_16x16x32_bf16 v[88:91], v[116:119], v[180:183], v[88:91]
	v_mfma_f32_16x16x32_bf16 v[84:87], v[140:143], v[180:183], v[84:87]
	v_mfma_f32_16x16x32_bf16 v[72:75], v[116:119], v[188:191], v[72:75]
	v_mfma_f32_16x16x32_bf16 v[68:71], v[140:143], v[188:191], v[68:71]
	v_mfma_f32_16x16x32_bf16 v[152:155], v[128:131], v[168:171], v[152:155]
	v_mfma_f32_16x16x32_bf16 v[144:147], v[148:151], v[168:171], v[144:147]
	v_mfma_f32_16x16x32_bf16 v[124:127], v[128:131], v[176:179], v[124:127]
	v_mfma_f32_16x16x32_bf16 v[120:123], v[148:151], v[176:179], v[120:123]
	v_mfma_f32_16x16x32_bf16 v[88:91], v[128:131], v[184:187], v[88:91]
	v_mfma_f32_16x16x32_bf16 v[84:87], v[148:151], v[184:187], v[84:87]
	v_mfma_f32_16x16x32_bf16 v[72:75], v[128:131], v[192:195], v[72:75]
	v_mfma_f32_16x16x32_bf16 v[68:71], v[148:151], v[192:195], v[68:71]
	s_barrier
	s_setprio 0
	s_add_i32 s8, s8, s82
	v_lshl_add_u64 v[196:197], s[42:43], 0, v[2:3]
	s_mov_b32 m0, s8
	ds_read_b128 v[160:163], v245 offset:16384
	ds_read_b128 v[168:171], v245 offset:17408
	ds_read_b128 v[172:175], v245 offset:18432
	ds_read_b128 v[176:179], v245 offset:19456
	ds_read_b128 v[180:183], v245 offset:20480
	ds_read_b128 v[184:187], v245 offset:21504
	ds_read_b128 v[188:191], v245 offset:22528
	ds_read_b128 v[192:195], v245 offset:23552
	global_load_lds_dwordx4 v[196:197], off
	s_add_i32 m0, s8, 0x2000
	s_add_u32 s8, s42, 0x160000
	v_lshl_add_u64 v[198:199], s[42:43], 0, v[218:219]
	s_addc_u32 s9, s43, 0
	s_add_i32 s10, s10, s82
	global_load_lds_dwordx4 v[198:199], off
	v_lshl_add_u64 v[200:201], s[8:9], 0, v[2:3]
	s_mov_b32 m0, s10
	v_lshl_add_u64 v[202:203], s[44:45], 0, v[216:217]
	global_load_lds_dwordx4 v[200:201], off
	v_lshl_add_u64 v[200:201], s[8:9], 0, v[218:219]
	s_add_i32 m0, s10, 0x2000
	s_nop 0
	global_load_lds_dwordx4 v[200:201], off
	v_lshl_add_u64 v[200:201], s[44:45], 0, v[0:1]
	s_mov_b32 m0, s83
	s_nop 0
	global_load_lds_dwordx4 v[200:201], off
	s_mov_b32 m0, s84
	s_nop 0
	global_load_lds_dwordx4 v[202:203], off
	s_waitcnt vmcnt(8) lgkmcnt(0)
	s_barrier
	s_setprio 1
	v_mfma_f32_16x16x32_bf16 v[64:67], v[92:95], v[160:163], v[64:67]
	v_mfma_f32_16x16x32_bf16 v[60:63], v[108:111], v[160:163], v[60:63]
	v_mfma_f32_16x16x32_bf16 v[48:51], v[92:95], v[172:175], v[48:51]
	v_mfma_f32_16x16x32_bf16 v[44:47], v[108:111], v[172:175], v[44:47]
	v_mfma_f32_16x16x32_bf16 v[32:35], v[92:95], v[180:183], v[32:35]
	v_mfma_f32_16x16x32_bf16 v[28:31], v[108:111], v[180:183], v[28:31]
	v_mfma_f32_16x16x32_bf16 v[16:19], v[92:95], v[188:191], v[16:19]
	v_mfma_f32_16x16x32_bf16 v[12:15], v[108:111], v[188:191], v[12:15]
	v_mfma_f32_16x16x32_bf16 v[64:67], v[100:103], v[168:171], v[64:67]
	v_mfma_f32_16x16x32_bf16 v[60:63], v[112:115], v[168:171], v[60:63]
	v_mfma_f32_16x16x32_bf16 v[48:51], v[100:103], v[176:179], v[48:51]
	v_mfma_f32_16x16x32_bf16 v[44:47], v[112:115], v[176:179], v[44:47]
	v_mfma_f32_16x16x32_bf16 v[32:35], v[100:103], v[184:187], v[32:35]
	v_mfma_f32_16x16x32_bf16 v[28:31], v[112:115], v[184:187], v[28:31]
	v_mfma_f32_16x16x32_bf16 v[16:19], v[100:103], v[192:195], v[16:19]
	v_mfma_f32_16x16x32_bf16 v[12:15], v[112:115], v[192:195], v[12:15]
	s_setprio 0
	s_setprio 1
	v_mfma_f32_16x16x32_bf16 v[56:59], v[116:119], v[160:163], v[56:59]
	v_mfma_f32_16x16x32_bf16 v[52:55], v[140:143], v[160:163], v[52:55]
	v_mfma_f32_16x16x32_bf16 v[40:43], v[116:119], v[172:175], v[40:43]
	v_mfma_f32_16x16x32_bf16 v[36:39], v[140:143], v[172:175], v[36:39]
	v_mfma_f32_16x16x32_bf16 v[24:27], v[116:119], v[180:183], v[24:27]
	v_mfma_f32_16x16x32_bf16 v[20:23], v[140:143], v[180:183], v[20:23]
	v_mfma_f32_16x16x32_bf16 v[8:11], v[116:119], v[188:191], v[8:11]
	v_mfma_f32_16x16x32_bf16 v[4:7], v[140:143], v[188:191], v[4:7]
	v_mfma_f32_16x16x32_bf16 v[56:59], v[128:131], v[168:171], v[56:59]
	v_mfma_f32_16x16x32_bf16 v[52:55], v[148:151], v[168:171], v[52:55]
	v_mfma_f32_16x16x32_bf16 v[40:43], v[128:131], v[176:179], v[40:43]
	v_mfma_f32_16x16x32_bf16 v[36:39], v[148:151], v[176:179], v[36:39]
	v_mfma_f32_16x16x32_bf16 v[24:27], v[128:131], v[184:187], v[24:27]
	v_mfma_f32_16x16x32_bf16 v[20:23], v[148:151], v[184:187], v[20:23]
	v_mfma_f32_16x16x32_bf16 v[8:11], v[128:131], v[192:195], v[8:11]
	v_mfma_f32_16x16x32_bf16 v[4:7], v[148:151], v[192:195], v[4:7]
	s_barrier
	s_setprio 0
	s_add_i32 s10, 0, 0x18000
	s_add_i32 s11, 0, 0x1c000
	v_add_u32_e32 v112, s10, v242
	v_add_u32_e32 v148, s11, v242
	ds_read_b128 v[92:95], v112
	ds_read_b128 v[100:103], v112 offset:1024
	ds_read_b128 v[108:111], v112 offset:2048
	ds_read_b128 v[112:115], v112 offset:3072
	ds_read_b128 v[116:119], v148
	ds_read_b128 v[128:131], v148 offset:1024
	ds_read_b128 v[140:143], v148 offset:2048
	ds_read_b128 v[148:151], v148 offset:3072
	s_add_u32 s8, s44, 0x160000
	s_addc_u32 s9, s45, 0
	s_mov_b32 m0, s85
	v_lshl_add_u64 v[204:205], s[8:9], 0, v[0:1]
	ds_read_b128 v[160:163], v245 offset:32768
	ds_read_b128 v[168:171], v245 offset:33792
	ds_read_b128 v[172:175], v245 offset:34816
	ds_read_b128 v[176:179], v245 offset:35840
	ds_read_b128 v[180:183], v245 offset:36864
	ds_read_b128 v[184:187], v245 offset:37888
	ds_read_b128 v[188:191], v245 offset:38912
	ds_read_b128 v[192:195], v245 offset:39936
	global_load_lds_dwordx4 v[204:205], off
	v_lshl_add_u64 v[204:205], s[8:9], 0, v[216:217]
	s_mov_b32 m0, s87
	s_nop 0
	global_load_lds_dwordx4 v[204:205], off
	s_waitcnt vmcnt(8) lgkmcnt(0)
	s_barrier
	s_setprio 1
	v_mfma_f32_16x16x32_bf16 v[164:167], v[92:95], v[160:163], v[164:167]
	v_mfma_f32_16x16x32_bf16 v[156:159], v[108:111], v[160:163], v[156:159]
	v_mfma_f32_16x16x32_bf16 v[136:139], v[92:95], v[172:175], v[136:139]
	v_mfma_f32_16x16x32_bf16 v[132:135], v[108:111], v[172:175], v[132:135]
	v_mfma_f32_16x16x32_bf16 v[104:107], v[92:95], v[180:183], v[104:107]
	v_mfma_f32_16x16x32_bf16 v[96:99], v[108:111], v[180:183], v[96:99]
	v_mfma_f32_16x16x32_bf16 v[80:83], v[92:95], v[188:191], v[80:83]
	v_mfma_f32_16x16x32_bf16 v[76:79], v[108:111], v[188:191], v[76:79]
	v_mfma_f32_16x16x32_bf16 v[164:167], v[100:103], v[168:171], v[164:167]
	v_mfma_f32_16x16x32_bf16 v[156:159], v[112:115], v[168:171], v[156:159]
	v_mfma_f32_16x16x32_bf16 v[136:139], v[100:103], v[176:179], v[136:139]
	v_mfma_f32_16x16x32_bf16 v[132:135], v[112:115], v[176:179], v[132:135]
	v_mfma_f32_16x16x32_bf16 v[104:107], v[100:103], v[184:187], v[104:107]
	v_mfma_f32_16x16x32_bf16 v[96:99], v[112:115], v[184:187], v[96:99]
	v_mfma_f32_16x16x32_bf16 v[80:83], v[100:103], v[192:195], v[80:83]
	v_mfma_f32_16x16x32_bf16 v[76:79], v[112:115], v[192:195], v[76:79]
	s_setprio 0
	s_setprio 1
	v_mfma_f32_16x16x32_bf16 v[152:155], v[116:119], v[160:163], v[152:155]
	v_mfma_f32_16x16x32_bf16 v[144:147], v[140:143], v[160:163], v[144:147]
	v_mfma_f32_16x16x32_bf16 v[124:127], v[116:119], v[172:175], v[124:127]
	v_mfma_f32_16x16x32_bf16 v[120:123], v[140:143], v[172:175], v[120:123]
	v_mfma_f32_16x16x32_bf16 v[88:91], v[116:119], v[180:183], v[88:91]
	v_mfma_f32_16x16x32_bf16 v[84:87], v[140:143], v[180:183], v[84:87]
	v_mfma_f32_16x16x32_bf16 v[72:75], v[116:119], v[188:191], v[72:75]
	v_mfma_f32_16x16x32_bf16 v[68:71], v[140:143], v[188:191], v[68:71]
	v_mfma_f32_16x16x32_bf16 v[152:155], v[128:131], v[168:171], v[152:155]
	v_mfma_f32_16x16x32_bf16 v[144:147], v[148:151], v[168:171], v[144:147]
	v_mfma_f32_16x16x32_bf16 v[124:127], v[128:131], v[176:179], v[124:127]
	v_mfma_f32_16x16x32_bf16 v[120:123], v[148:151], v[176:179], v[120:123]
	v_mfma_f32_16x16x32_bf16 v[88:91], v[128:131], v[184:187], v[88:91]
	v_mfma_f32_16x16x32_bf16 v[84:87], v[148:151], v[184:187], v[84:87]
	v_mfma_f32_16x16x32_bf16 v[72:75], v[128:131], v[192:195], v[72:75]
	v_mfma_f32_16x16x32_bf16 v[68:71], v[148:151], v[192:195], v[68:71]
	s_barrier
	s_setprio 0
	s_add_i32 s8, s10, s82
	v_lshl_add_u64 v[196:197], v[196:197], 0, s[68:69]
	s_mov_b32 m0, s8
	ds_read_b128 v[160:163], v245 offset:49152
	ds_read_b128 v[168:171], v245 offset:50176
	ds_read_b128 v[172:175], v245 offset:51200
	ds_read_b128 v[176:179], v245 offset:52224
	ds_read_b128 v[180:183], v245 offset:53248
	ds_read_b128 v[184:187], v245 offset:54272
	ds_read_b128 v[188:191], v245 offset:55296
	ds_read_b128 v[192:195], v245 offset:56320
	global_load_lds_dwordx4 v[196:197], off
	s_add_i32 m0, s8, 0x2000
	s_add_u32 s8, s42, 0x160080
	v_lshl_add_u64 v[196:197], v[198:199], 0, s[68:69]
	s_addc_u32 s9, s43, 0
	s_add_i32 s10, s11, s82
	global_load_lds_dwordx4 v[196:197], off
	v_lshl_add_u64 v[196:197], s[8:9], 0, v[2:3]
	s_mov_b32 m0, s10
	s_nop 0
	global_load_lds_dwordx4 v[196:197], off
	v_lshl_add_u64 v[196:197], s[8:9], 0, v[218:219]
	s_add_i32 m0, s10, 0x2000
	s_nop 0
	global_load_lds_dwordx4 v[196:197], off
	v_lshl_add_u64 v[196:197], v[200:201], 0, s[68:69]
	s_mov_b32 m0, s72
	s_nop 0
	global_load_lds_dwordx4 v[196:197], off
	v_lshl_add_u64 v[196:197], v[202:203], 0, s[68:69]
	s_mov_b32 m0, s88
	s_nop 0
	global_load_lds_dwordx4 v[196:197], off
	s_waitcnt vmcnt(8) lgkmcnt(0)
	s_barrier
	s_setprio 1
	v_mfma_f32_16x16x32_bf16 v[64:67], v[92:95], v[160:163], v[64:67]
	v_mfma_f32_16x16x32_bf16 v[60:63], v[108:111], v[160:163], v[60:63]
	v_mfma_f32_16x16x32_bf16 v[48:51], v[92:95], v[172:175], v[48:51]
	v_mfma_f32_16x16x32_bf16 v[44:47], v[108:111], v[172:175], v[44:47]
	v_mfma_f32_16x16x32_bf16 v[32:35], v[92:95], v[180:183], v[32:35]
	v_mfma_f32_16x16x32_bf16 v[28:31], v[108:111], v[180:183], v[28:31]
	v_mfma_f32_16x16x32_bf16 v[16:19], v[92:95], v[188:191], v[16:19]
	v_mfma_f32_16x16x32_bf16 v[12:15], v[108:111], v[188:191], v[12:15]
	v_mfma_f32_16x16x32_bf16 v[64:67], v[100:103], v[168:171], v[64:67]
	v_mfma_f32_16x16x32_bf16 v[60:63], v[112:115], v[168:171], v[60:63]
	v_mfma_f32_16x16x32_bf16 v[48:51], v[100:103], v[176:179], v[48:51]
	v_mfma_f32_16x16x32_bf16 v[44:47], v[112:115], v[176:179], v[44:47]
	v_mfma_f32_16x16x32_bf16 v[32:35], v[100:103], v[184:187], v[32:35]
	v_mfma_f32_16x16x32_bf16 v[28:31], v[112:115], v[184:187], v[28:31]
	v_mfma_f32_16x16x32_bf16 v[16:19], v[100:103], v[192:195], v[16:19]
	v_mfma_f32_16x16x32_bf16 v[12:15], v[112:115], v[192:195], v[12:15]
	s_setprio 0
	s_setprio 1
	v_mfma_f32_16x16x32_bf16 v[56:59], v[116:119], v[160:163], v[56:59]
	v_mfma_f32_16x16x32_bf16 v[52:55], v[140:143], v[160:163], v[52:55]
	v_mfma_f32_16x16x32_bf16 v[40:43], v[116:119], v[172:175], v[40:43]
	v_mfma_f32_16x16x32_bf16 v[36:39], v[140:143], v[172:175], v[36:39]
	v_mfma_f32_16x16x32_bf16 v[24:27], v[116:119], v[180:183], v[24:27]
	v_mfma_f32_16x16x32_bf16 v[20:23], v[140:143], v[180:183], v[20:23]
	v_mfma_f32_16x16x32_bf16 v[8:11], v[116:119], v[188:191], v[8:11]
	v_mfma_f32_16x16x32_bf16 v[4:7], v[140:143], v[188:191], v[4:7]
	v_mfma_f32_16x16x32_bf16 v[56:59], v[128:131], v[168:171], v[56:59]
	v_mfma_f32_16x16x32_bf16 v[52:55], v[148:151], v[168:171], v[52:55]
	v_mfma_f32_16x16x32_bf16 v[40:43], v[128:131], v[176:179], v[40:43]
	v_mfma_f32_16x16x32_bf16 v[36:39], v[148:151], v[176:179], v[36:39]
	v_mfma_f32_16x16x32_bf16 v[24:27], v[128:131], v[184:187], v[24:27]
	v_mfma_f32_16x16x32_bf16 v[20:23], v[148:151], v[184:187], v[20:23]
	v_mfma_f32_16x16x32_bf16 v[8:11], v[128:131], v[192:195], v[8:11]
	v_mfma_f32_16x16x32_bf16 v[4:7], v[148:151], v[192:195], v[4:7]
	s_barrier
	s_setprio 0
	s_add_i32 s7, s7, 2
	s_add_u32 s5, s5, 0x100
	s_addc_u32 s6, s6, 0
	s_cmpk_gt_u32 s7, 0x55
	s_mov_b64 s[38:39], s[40:41]
	s_cbranch_scc0 .LBB0_1134
	s_and_b64 vcc, exec, s[52:53]
	s_cbranch_vccz .LBB0_1137
	s_barrier
